# v24 + EpiGate g-row loads fetched one step ahead (own address arithmetic, counted waits) + EpiNorm row statistics: cross-lane hops of the 8 rows batched (2 LDS round trips instead of 16), same summati
# speedup vs baseline: 1.0055x; 1.0055x over previous
;     __device__ __forceinline__ void rowstat(const f32x4 (&v)[2][2][4][2], const Unit& u, int wr, int wc, int fr, int fq, float* slot, unsigned* cnt) const {
;     ...
; #pragma unroll
;         for (int ai = 0; ai < 2; ++ai)
; #pragma unroll
;             for (int m = 0; m < 4; ++m) {
;                 float ss = 0.f;
; #pragma unroll
;                 for (int bj = 0; bj < 2; ++bj)
; #pragma unroll
;                     for (int n = 0; n < 2; ++n) { const f32x4 x = v[ai][bj][m][n]; ss += (x[0] * x[0] + x[1] * x[1]) + (x[2] * x[2] + x[3] * x[3]); }
;                 ss += __shfl_xor(ss, 16); ss += __shfl_xor(ss, 32);
;                 if (fq == 0) Pp[(ai * HALF + wr * 64 + m * 16 + fr) * 4 + wc] = ss;
.LBB0_919:
	v_and_b32_e32 v131, 64, v238
	v_xor_b32_e32 v130, 16, v238
	v_add_u32_e32 v131, 64, v131
	v_cmp_lt_i32_e32 vcc, v130, v131
	s_nop 1
	v_mul_f32_e32 v132, v109, v109
	v_fmac_f32_e32 v132, v108, v108
	v_cndmask_b32_e32 v130, v238, v130, vcc
	v_lshlrev_b32_e32 v170, 2, v130
	v_mul_f32_e32 v130, v107, v107
	v_fmac_f32_e32 v130, v106, v106
	v_add_f32_e32 v130, v130, v132
	v_mul_f32_e32 v132, v115, v115
	v_mul_f32_e32 v133, v117, v117
	v_fmac_f32_e32 v132, v114, v114
	v_fmac_f32_e32 v133, v116, v116
	v_add_f32_e32 v132, v132, v133
	v_add_f32_e32 v130, v130, v132
	v_mul_f32_e32 v132, v63, v63
	v_mul_f32_e32 v133, v65, v65
	v_fmac_f32_e32 v132, v62, v62
	v_fmac_f32_e32 v133, v64, v64
	v_add_f32_e32 v132, v132, v133
	v_add_f32_e32 v130, v130, v132
	v_mul_f32_e32 v132, v35, v35
	v_mul_f32_e32 v133, v37, v37
	v_fmac_f32_e32 v132, v34, v34
	v_fmac_f32_e32 v133, v36, v36
	v_add_f32_e32 v132, v132, v133
	v_add_f32_e32 v130, v130, v132
	v_xor_b32_e32 v133, 32, v238
	v_cmp_lt_i32_e32 vcc, v133, v131
	s_nop 1
	v_cndmask_b32_e32 v131, v238, v133, vcc
	v_lshlrev_b32_e32 v171, 2, v131
	v_mov_b32_e32 v134, v130
	v_mul_f32_e32 v130, v99, v99
	v_mul_f32_e32 v131, v101, v101
	v_fmac_f32_e32 v130, v98, v98
	v_fmac_f32_e32 v131, v100, v100
	v_add_f32_e32 v130, v130, v131
	v_mul_f32_e32 v131, v111, v111
	v_mul_f32_e32 v132, v113, v113
	v_fmac_f32_e32 v131, v110, v110
	v_fmac_f32_e32 v132, v112, v112
	v_add_f32_e32 v131, v131, v132
	v_add_f32_e32 v130, v130, v131
	v_mul_f32_e32 v131, v59, v59
	v_mul_f32_e32 v132, v61, v61
	v_fmac_f32_e32 v131, v58, v58
	v_fmac_f32_e32 v132, v60, v60
	v_add_f32_e32 v131, v131, v132
	v_add_f32_e32 v130, v130, v131
	v_mul_f32_e32 v131, v31, v31
	v_mul_f32_e32 v132, v33, v33
	v_fmac_f32_e32 v131, v30, v30
	v_fmac_f32_e32 v132, v32, v32
	v_add_f32_e32 v131, v131, v132
	v_add_f32_e32 v130, v130, v131
	v_mov_b32_e32 v135, v130
	v_mul_f32_e32 v130, v95, v95
	v_mul_f32_e32 v131, v97, v97
	v_fmac_f32_e32 v130, v94, v94
	v_fmac_f32_e32 v131, v96, v96
	v_add_f32_e32 v130, v130, v131
	v_mul_f32_e32 v131, v103, v103
	v_mul_f32_e32 v132, v105, v105
	v_fmac_f32_e32 v131, v102, v102
	v_fmac_f32_e32 v132, v104, v104
	v_add_f32_e32 v131, v131, v132
	v_add_f32_e32 v130, v130, v131
	v_mul_f32_e32 v131, v55, v55
	v_mul_f32_e32 v132, v57, v57
	v_fmac_f32_e32 v131, v54, v54
	v_fmac_f32_e32 v132, v56, v56
	v_add_f32_e32 v131, v131, v132
	v_add_f32_e32 v130, v130, v131
	v_mul_f32_e32 v131, v27, v27
	v_mul_f32_e32 v132, v29, v29
	v_fmac_f32_e32 v131, v26, v26
	v_fmac_f32_e32 v132, v28, v28
	v_add_f32_e32 v131, v131, v132
	v_add_f32_e32 v130, v130, v131
	v_mov_b32_e32 v136, v130
	v_mul_f32_e32 v130, v91, v91
	v_mul_f32_e32 v131, v93, v93
	v_fmac_f32_e32 v130, v90, v90
	v_fmac_f32_e32 v131, v92, v92
	v_add_f32_e32 v130, v130, v131
	v_mul_f32_e32 v131, v127, v127
	v_mul_f32_e32 v132, v129, v129
	v_fmac_f32_e32 v131, v126, v126
	v_fmac_f32_e32 v132, v128, v128
	v_add_f32_e32 v131, v131, v132
	v_add_f32_e32 v130, v130, v131
	v_mul_f32_e32 v131, v51, v51
	v_mul_f32_e32 v132, v53, v53
	v_fmac_f32_e32 v131, v50, v50
	v_fmac_f32_e32 v132, v52, v52
	v_add_f32_e32 v131, v131, v132
	v_add_f32_e32 v130, v130, v131
	v_mul_f32_e32 v131, v23, v23
	v_mul_f32_e32 v132, v25, v25
	v_fmac_f32_e32 v131, v22, v22
	v_fmac_f32_e32 v132, v24, v24
	v_add_f32_e32 v131, v131, v132
	v_add_f32_e32 v130, v130, v131
	v_mov_b32_e32 v137, v130
	v_mul_f32_e32 v130, v87, v87
	v_mul_f32_e32 v131, v89, v89
	v_fmac_f32_e32 v130, v86, v86
	v_fmac_f32_e32 v131, v88, v88
	v_add_f32_e32 v130, v130, v131
	v_mul_f32_e32 v131, v123, v123
	v_mul_f32_e32 v132, v125, v125
	v_fmac_f32_e32 v131, v122, v122
	v_fmac_f32_e32 v132, v124, v124
	v_add_f32_e32 v131, v131, v132
	v_add_f32_e32 v130, v130, v131
	v_mul_f32_e32 v131, v47, v47
	v_mul_f32_e32 v132, v49, v49
	v_fmac_f32_e32 v131, v46, v46
	v_fmac_f32_e32 v132, v48, v48
	v_add_f32_e32 v131, v131, v132
	v_add_f32_e32 v130, v130, v131
	v_mul_f32_e32 v131, v15, v15
	v_mul_f32_e32 v132, v17, v17
	v_fmac_f32_e32 v131, v14, v14
	v_fmac_f32_e32 v132, v16, v16
	v_add_f32_e32 v131, v131, v132
	v_add_f32_e32 v130, v130, v131
	v_mov_b32_e32 v152, v130
	v_mul_f32_e32 v130, v83, v83
	v_mul_f32_e32 v131, v85, v85
	v_fmac_f32_e32 v130, v82, v82
	v_fmac_f32_e32 v131, v84, v84
	v_add_f32_e32 v130, v130, v131
	v_mul_f32_e32 v131, v119, v119
	v_mul_f32_e32 v132, v121, v121
	v_fmac_f32_e32 v131, v118, v118
	v_fmac_f32_e32 v132, v120, v120
	v_add_f32_e32 v131, v131, v132
	v_add_f32_e32 v130, v130, v131
	v_mul_f32_e32 v131, v43, v43
	v_mul_f32_e32 v132, v45, v45
	v_fmac_f32_e32 v131, v42, v42
	v_fmac_f32_e32 v132, v44, v44
	v_add_f32_e32 v131, v131, v132
	v_add_f32_e32 v130, v130, v131
	v_mul_f32_e32 v131, v9, v9
	v_mul_f32_e32 v132, v11, v11
	v_fmac_f32_e32 v131, v8, v8
	v_fmac_f32_e32 v132, v10, v10
	v_add_f32_e32 v131, v131, v132
	v_add_f32_e32 v130, v130, v131
	v_mov_b32_e32 v153, v130
	v_mul_f32_e32 v130, v79, v79
	v_mul_f32_e32 v131, v81, v81
	v_fmac_f32_e32 v130, v78, v78
	v_fmac_f32_e32 v131, v80, v80
	v_add_f32_e32 v130, v130, v131
	v_mul_f32_e32 v131, v71, v71
	v_mul_f32_e32 v132, v73, v73
	v_fmac_f32_e32 v131, v70, v70
	v_fmac_f32_e32 v132, v72, v72
	v_add_f32_e32 v131, v131, v132
	v_add_f32_e32 v130, v130, v131
	v_mul_f32_e32 v131, v39, v39
	v_mul_f32_e32 v132, v41, v41
	v_fmac_f32_e32 v131, v38, v38
	v_fmac_f32_e32 v132, v40, v40
	v_add_f32_e32 v131, v131, v132
	v_add_f32_e32 v130, v130, v131
	v_mul_f32_e32 v131, v5, v5
	v_mul_f32_e32 v132, v7, v7
	v_fmac_f32_e32 v131, v4, v4
	v_fmac_f32_e32 v132, v6, v6
	v_add_f32_e32 v131, v131, v132
	v_add_f32_e32 v130, v130, v131
	v_mov_b32_e32 v154, v130
	v_mul_f32_e32 v130, v75, v75
	v_mul_f32_e32 v131, v77, v77
	v_fmac_f32_e32 v130, v74, v74
	v_fmac_f32_e32 v131, v76, v76
	v_add_f32_e32 v130, v130, v131
	v_mul_f32_e32 v131, v67, v67
	v_mul_f32_e32 v132, v69, v69
	v_fmac_f32_e32 v131, v66, v66
	v_fmac_f32_e32 v132, v68, v68
	v_add_f32_e32 v131, v131, v132
	v_add_f32_e32 v130, v130, v131
	v_mul_f32_e32 v131, v19, v19
	v_mul_f32_e32 v132, v21, v21
	v_fmac_f32_e32 v131, v18, v18
	v_fmac_f32_e32 v132, v20, v20
	v_add_f32_e32 v131, v131, v132
	v_add_f32_e32 v130, v130, v131
	v_mul_f32_e32 v131, v1, v1
	v_mul_f32_e32 v132, v3, v3
	v_fmac_f32_e32 v131, v0, v0
	v_fmac_f32_e32 v132, v2, v2
	v_add_f32_e32 v131, v131, v132
	v_add_f32_e32 v130, v130, v131
	v_mov_b32_e32 v155, v130
	ds_bpermute_b32 v156, v170, v134
	ds_bpermute_b32 v157, v170, v135
	ds_bpermute_b32 v158, v170, v136
	ds_bpermute_b32 v159, v170, v137
	ds_bpermute_b32 v160, v170, v152
	ds_bpermute_b32 v161, v170, v153
	ds_bpermute_b32 v162, v170, v154
	ds_bpermute_b32 v163, v170, v155
	s_waitcnt lgkmcnt(0)
;     __device__ __forceinline__ void rowstat(const f32x4 (&v)[2][2][4][2], const Unit& u, int wr, int wc, int fr, int fq, float* slot, unsigned* cnt) const {
;     ...
;                 ss += __shfl_xor(ss, 16); ss += __shfl_xor(ss, 32);
;                 if (fq == 0) Pp[(ai * HALF + wr * 64 + m * 16 + fr) * 4 + wc] = ss;
	v_add_f32_e32 v134, v134, v156
	v_add_f32_e32 v135, v135, v157
	v_add_f32_e32 v136, v136, v158
	v_add_f32_e32 v137, v137, v159
	v_add_f32_e32 v152, v152, v160
	v_add_f32_e32 v153, v153, v161
	v_add_f32_e32 v154, v154, v162
	v_add_f32_e32 v155, v155, v163
	ds_bpermute_b32 v156, v171, v134
	ds_bpermute_b32 v157, v171, v135
	ds_bpermute_b32 v158, v171, v136
	ds_bpermute_b32 v159, v171, v137
	ds_bpermute_b32 v160, v171, v152
	ds_bpermute_b32 v161, v171, v153
	ds_bpermute_b32 v162, v171, v154
	ds_bpermute_b32 v163, v171, v155
	s_and_saveexec_b64 s[8:9], s[2:3]
	s_movk_i32 s65, 0x300
	s_cbranch_execz .Lrs_skip_0
	s_waitcnt lgkmcnt(0)
	v_add_f32_e32 v134, v134, v156
	v_add_f32_e32 v135, v135, v157
	v_add_f32_e32 v136, v136, v158
	v_add_f32_e32 v137, v137, v159
	v_add_f32_e32 v152, v152, v160
	v_add_f32_e32 v153, v153, v161
	v_add_f32_e32 v154, v154, v162
	v_add_f32_e32 v155, v155, v163
	ds_write_b32 v248, v134
	ds_write_b32 v248, v135 offset:256
	ds_write_b32 v248, v136 offset:512
	ds_write_b32 v248, v137 offset:768
	ds_write_b32 v248, v152 offset:2048
	ds_write_b32 v248, v153 offset:2304
	ds_write_b32 v248, v154 offset:2560
	ds_write_b32 v248, v155 offset:2816

; #define LAS __attribute__((address_space(3)))
;     __device__ __forceinline__ void operator()(f32x4 (&acc)[2][2][4][2], const Unit& u, int wr, int wc, int fr, int fq) const {
;         const LAS float* S = (const LAS float*)(xl + 4096);
;         const float* md = modb + (size_t)(u.pm >> 4) * 6144;
;         rowstat(acc, u, wr, wc, fr, fq, slot1, cnt1);
; #pragma unroll
;         for (int bj = 0; bj < 2; ++bj)
; #pragma unroll
;             for (int n = 0; n < 2; ++n) {
;                 const int col = u.pn * BM + bj * HALF + wc * 32 + 8 * fq + 4 * n;
;                 const f32x4 gg = *(const f32x4*)(md + gate_off + col) * *(const f32x4*)(gpost + col);
; #pragma unroll
;                 for (int ai = 0; ai < 2; ++ai)
; #pragma unroll
;                     for (int m = 0; m < 4; ++m) {
;                         const int rl = ai * HALF + wr * 64 + m * 16 + fr; const size_t off = (size_t)(u.pm * BM + rl) * DM + col;
;                         const f32x4 xv = *(const f32x4*)(xin + off);
;                         const f32x4 xn = xv + gg * (acc[ai][bj][m][n] * S[rl]);
.LBB0_948:
	s_or_b64 exec, exec, s[40:41]
	s_ashr_i32 s40, s82, 4
	s_mul_hi_i32 s41, s40, 0x6000
	s_mulk_i32 s40, 0x6000
	s_add_u32 s53, s25, s40
	s_addc_u32 s64, s29, s41
	v_lshl_or_b32 v178, s96, 8, v168
	s_lshl_b32 s40, s82, 8
	s_add_u32 vcc_lo, s53, 0x2000
	v_ashrrev_i32_e32 v179, 31, v178
	s_addc_u32 vcc_hi, s64, 0
	v_lshlrev_b64 v[182:183], 2, v[178:179]
	s_waitcnt vmcnt(0) lgkmcnt(0)
	s_barrier
	s_waitcnt lgkmcnt(0)
	v_lshl_add_u64 v[212:213], vcc, 0, v[182:183]
	v_lshl_add_u64 v[214:215], s[12:13], 0, v[182:183]
	global_load_dwordx4 v[130:133], v[212:213], off
	global_load_dwordx4 v[134:137], v[214:215], off
	v_add_u32_e32 v204, s40, v166
	v_add_u32_e32 v205, s40, v217
	v_add_u32_e32 v224, s40, v219
	v_add_u32_e32 v225, s40, v221
	v_add_u32_e32 v232, s40, v207
	v_add_u32_e32 v164, s40, v227
	v_add_u32_e32 v165, s40, v229
	v_add_u32_e32 v181, s40, v231
	v_lshl_add_u32 v204, v204, 10, v178
	v_lshl_add_u32 v205, v205, 10, v178
	v_lshl_add_u32 v224, v224, 10, v178
	v_lshl_add_u32 v225, v225, 10, v178
	v_lshl_add_u32 v232, v232, 10, v178
	v_lshl_add_u32 v164, v164, 10, v178
	v_lshl_add_u32 v165, v165, 10, v178
	v_lshl_add_u32 v181, v181, 10, v178
	v_lshlrev_b32_e32 v204, 2, v204
	v_lshlrev_b32_e32 v205, 2, v205
	v_lshlrev_b32_e32 v224, 2, v224
	v_lshlrev_b32_e32 v225, 2, v225
	v_lshlrev_b32_e32 v232, 2, v232
	v_lshlrev_b32_e32 v164, 2, v164
	v_lshlrev_b32_e32 v165, 2, v165
	v_lshlrev_b32_e32 v181, 2, v181
	global_load_dwordx4 v[184:187], v204, s[10:11]
	global_load_dwordx4 v[188:191], v205, s[10:11]
	global_load_dwordx4 v[192:195], v224, s[10:11]
	global_load_dwordx4 v[196:199], v225, s[10:11]
	global_load_dwordx4 v[200:203], v232, s[10:11]
	global_load_dwordx4 v[208:211], v164, s[10:11]
	global_load_dwordx4 v[152:155], v165, s[10:11]
	global_load_dwordx4 v[156:159], v181, s[10:11]
	ds_read_b32 v176, v234
	ds_read_b32 v206, v235
	ds_read_b32 v216, v236
	ds_read_b32 v218, v242
	ds_read_b32 v220, v243
	ds_read_b32 v226, v244
	ds_read_b32 v228, v245
	ds_read_b32 v230, v246
	s_waitcnt lgkmcnt(7)
	v_pk_mul_f32 v[106:107], v[106:107], v[176:177] op_sel_hi:[1,0]
	v_pk_mul_f32 v[108:109], v[108:109], v[176:177] op_sel_hi:[1,0]
	v_pk_mul_f32 v[114:115], v[114:115], v[176:177] op_sel_hi:[1,0]
	v_pk_mul_f32 v[116:117], v[116:117], v[176:177] op_sel_hi:[1,0]
	v_pk_mul_f32 v[62:63], v[62:63], v[176:177] op_sel_hi:[1,0]
	v_pk_mul_f32 v[64:65], v[64:65], v[176:177] op_sel_hi:[1,0]
	v_pk_mul_f32 v[34:35], v[34:35], v[176:177] op_sel_hi:[1,0]
	v_pk_mul_f32 v[36:37], v[36:37], v[176:177] op_sel_hi:[1,0]
	s_waitcnt lgkmcnt(6)
	v_pk_mul_f32 v[98:99], v[98:99], v[206:207] op_sel_hi:[1,0]
	v_pk_mul_f32 v[100:101], v[100:101], v[206:207] op_sel_hi:[1,0]
	v_pk_mul_f32 v[110:111], v[110:111], v[206:207] op_sel_hi:[1,0]
	v_pk_mul_f32 v[112:113], v[112:113], v[206:207] op_sel_hi:[1,0]
	v_pk_mul_f32 v[58:59], v[58:59], v[206:207] op_sel_hi:[1,0]
	v_pk_mul_f32 v[60:61], v[60:61], v[206:207] op_sel_hi:[1,0]
	v_pk_mul_f32 v[30:31], v[30:31], v[206:207] op_sel_hi:[1,0]
	v_pk_mul_f32 v[32:33], v[32:33], v[206:207] op_sel_hi:[1,0]
	s_waitcnt lgkmcnt(5)
	v_pk_mul_f32 v[94:95], v[94:95], v[216:217] op_sel_hi:[1,0]
	v_pk_mul_f32 v[96:97], v[96:97], v[216:217] op_sel_hi:[1,0]
	v_pk_mul_f32 v[102:103], v[102:103], v[216:217] op_sel_hi:[1,0]
	v_pk_mul_f32 v[104:105], v[104:105], v[216:217] op_sel_hi:[1,0]
	v_pk_mul_f32 v[54:55], v[54:55], v[216:217] op_sel_hi:[1,0]
	v_pk_mul_f32 v[56:57], v[56:57], v[216:217] op_sel_hi:[1,0]
	v_pk_mul_f32 v[26:27], v[26:27], v[216:217] op_sel_hi:[1,0]
	v_pk_mul_f32 v[28:29], v[28:29], v[216:217] op_sel_hi:[1,0]
	s_waitcnt lgkmcnt(4)
	v_pk_mul_f32 v[90:91], v[90:91], v[218:219] op_sel_hi:[1,0]
	v_pk_mul_f32 v[92:93], v[92:93], v[218:219] op_sel_hi:[1,0]
	v_pk_mul_f32 v[126:127], v[126:127], v[218:219] op_sel_hi:[1,0]
	v_pk_mul_f32 v[128:129], v[128:129], v[218:219] op_sel_hi:[1,0]
	v_pk_mul_f32 v[50:51], v[50:51], v[218:219] op_sel_hi:[1,0]
	v_pk_mul_f32 v[52:53], v[52:53], v[218:219] op_sel_hi:[1,0]
	v_pk_mul_f32 v[22:23], v[22:23], v[218:219] op_sel_hi:[1,0]
	v_pk_mul_f32 v[24:25], v[24:25], v[218:219] op_sel_hi:[1,0]
	s_waitcnt lgkmcnt(3)
	v_pk_mul_f32 v[86:87], v[86:87], v[220:221] op_sel_hi:[1,0]
	v_pk_mul_f32 v[88:89], v[88:89], v[220:221] op_sel_hi:[1,0]
	v_pk_mul_f32 v[122:123], v[122:123], v[220:221] op_sel_hi:[1,0]
	v_pk_mul_f32 v[124:125], v[124:125], v[220:221] op_sel_hi:[1,0]
	v_pk_mul_f32 v[46:47], v[46:47], v[220:221] op_sel_hi:[1,0]
	v_pk_mul_f32 v[48:49], v[48:49], v[220:221] op_sel_hi:[1,0]
	v_pk_mul_f32 v[14:15], v[14:15], v[220:221] op_sel_hi:[1,0]
	v_pk_mul_f32 v[16:17], v[16:17], v[220:221] op_sel_hi:[1,0]
	s_waitcnt lgkmcnt(2)
	v_pk_mul_f32 v[82:83], v[82:83], v[226:227] op_sel_hi:[1,0]
	v_pk_mul_f32 v[84:85], v[84:85], v[226:227] op_sel_hi:[1,0]
	v_pk_mul_f32 v[118:119], v[118:119], v[226:227] op_sel_hi:[1,0]
	v_pk_mul_f32 v[120:121], v[120:121], v[226:227] op_sel_hi:[1,0]
	v_pk_mul_f32 v[42:43], v[42:43], v[226:227] op_sel_hi:[1,0]
	v_pk_mul_f32 v[44:45], v[44:45], v[226:227] op_sel_hi:[1,0]
	v_pk_mul_f32 v[8:9], v[8:9], v[226:227] op_sel_hi:[1,0]
	v_pk_mul_f32 v[10:11], v[10:11], v[226:227] op_sel_hi:[1,0]
	s_waitcnt lgkmcnt(1)
	v_pk_mul_f32 v[78:79], v[78:79], v[228:229] op_sel_hi:[1,0]
	v_pk_mul_f32 v[80:81], v[80:81], v[228:229] op_sel_hi:[1,0]
	v_pk_mul_f32 v[70:71], v[70:71], v[228:229] op_sel_hi:[1,0]
	v_pk_mul_f32 v[72:73], v[72:73], v[228:229] op_sel_hi:[1,0]
	v_pk_mul_f32 v[38:39], v[38:39], v[228:229] op_sel_hi:[1,0]
	v_pk_mul_f32 v[40:41], v[40:41], v[228:229] op_sel_hi:[1,0]
	v_pk_mul_f32 v[4:5], v[4:5], v[228:229] op_sel_hi:[1,0]
	v_pk_mul_f32 v[6:7], v[6:7], v[228:229] op_sel_hi:[1,0]
	s_waitcnt lgkmcnt(0)
;     __device__ __forceinline__ void operator()(f32x4 (&acc)[2][2][4][2], const Unit& u, int wr, int wc, int fr, int fq) const {
;     ...
;             for (int n = 0; n < 2; ++n) {
;                 const int col = u.pn * BM + bj * HALF + wc * 32 + 8 * fq + 4 * n;
;                 const f32x4 gg = *(const f32x4*)(md + gate_off + col) * *(const f32x4*)(gpost + col);
; #pragma unroll
;                 for (int ai = 0; ai < 2; ++ai)
; #pragma unroll
;                     for (int m = 0; m < 4; ++m) {
;                         const int rl = ai * HALF + wr * 64 + m * 16 + fr; const size_t off = (size_t)(u.pm * BM + rl) * DM + col;
;                         const f32x4 xv = *(const f32x4*)(xin + off);
;                         const f32x4 xn = xv + gg * (acc[ai][bj][m][n] * S[rl]);
;                         acc[ai][bj][m][n] = xn; *(f32x4*)(xout + off) = xn;
;                     }
	v_pk_mul_f32 v[74:75], v[74:75], v[230:231] op_sel_hi:[1,0]
	v_pk_mul_f32 v[76:77], v[76:77], v[230:231] op_sel_hi:[1,0]
	v_pk_mul_f32 v[66:67], v[66:67], v[230:231] op_sel_hi:[1,0]
	v_pk_mul_f32 v[68:69], v[68:69], v[230:231] op_sel_hi:[1,0]
	v_pk_mul_f32 v[18:19], v[18:19], v[230:231] op_sel_hi:[1,0]
	v_pk_mul_f32 v[20:21], v[20:21], v[230:231] op_sel_hi:[1,0]
	v_pk_mul_f32 v[0:1], v[0:1], v[230:231] op_sel_hi:[1,0]
	v_pk_mul_f32 v[2:3], v[2:3], v[230:231] op_sel_hi:[1,0]
	s_waitcnt vmcnt(8)
	v_pk_mul_f32 v[172:173], v[130:131], v[134:135]
	v_pk_mul_f32 v[174:175], v[132:133], v[136:137]
	global_load_dwordx4 v[130:133], v[212:213], off offset:16
	global_load_dwordx4 v[134:137], v[214:215], off offset:16
	s_waitcnt vmcnt(9)
	v_pk_fma_f32 v[108:109], v[174:175], v[108:109], v[186:187]
	v_pk_fma_f32 v[106:107], v[172:173], v[106:107], v[184:185]
	global_store_dwordx4 v204, v[106:109], s[60:61]
	global_load_dwordx4 v[184:187], v204, s[10:11] offset:16
	s_waitcnt vmcnt(10)
	v_pk_fma_f32 v[100:101], v[174:175], v[100:101], v[190:191]
	v_pk_fma_f32 v[98:99], v[172:173], v[98:99], v[188:189]
	global_store_dwordx4 v205, v[98:101], s[60:61]
	global_load_dwordx4 v[188:191], v205, s[10:11] offset:16
	s_waitcnt vmcnt(11)
	v_pk_fma_f32 v[96:97], v[174:175], v[96:97], v[194:195]
	v_pk_fma_f32 v[94:95], v[172:173], v[94:95], v[192:193]
	global_store_dwordx4 v224, v[94:97], s[60:61]
	global_load_dwordx4 v[192:195], v224, s[10:11] offset:16
	s_waitcnt vmcnt(12)
	v_pk_fma_f32 v[92:93], v[174:175], v[92:93], v[198:199]
	v_pk_fma_f32 v[90:91], v[172:173], v[90:91], v[196:197]
	global_store_dwordx4 v225, v[90:93], s[60:61]
	global_load_dwordx4 v[196:199], v225, s[10:11] offset:16
	s_waitcnt vmcnt(13)
	v_pk_fma_f32 v[88:89], v[174:175], v[88:89], v[202:203]
	v_pk_fma_f32 v[86:87], v[172:173], v[86:87], v[200:201]
	global_store_dwordx4 v232, v[86:89], s[60:61]
	global_load_dwordx4 v[200:203], v232, s[10:11] offset:16
	s_waitcnt vmcnt(14)
	v_pk_fma_f32 v[84:85], v[174:175], v[84:85], v[210:211]
	v_pk_fma_f32 v[82:83], v[172:173], v[82:83], v[208:209]
	global_store_dwordx4 v164, v[82:85], s[60:61]
	global_load_dwordx4 v[208:211], v164, s[10:11] offset:16
	s_waitcnt vmcnt(15)
	v_pk_fma_f32 v[80:81], v[174:175], v[80:81], v[154:155]
	v_pk_fma_f32 v[78:79], v[172:173], v[78:79], v[152:153]
	global_store_dwordx4 v165, v[78:81], s[60:61]
	global_load_dwordx4 v[152:155], v165, s[10:11] offset:16
	s_waitcnt vmcnt(16)
	v_pk_fma_f32 v[76:77], v[174:175], v[76:77], v[158:159]
	v_pk_fma_f32 v[74:75], v[172:173], v[74:75], v[156:157]
	global_store_dwordx4 v181, v[74:77], s[60:61]
	global_load_dwordx4 v[156:159], v181, s[10:11] offset:16
	s_waitcnt vmcnt(16)
	v_pk_mul_f32 v[160:161], v[130:131], v[134:135]
	v_pk_mul_f32 v[162:163], v[132:133], v[136:137]
	global_load_dwordx4 v[130:133], v[212:213], off offset:512
	global_load_dwordx4 v[134:137], v[214:215], off offset:512
	s_waitcnt vmcnt(16)
	v_pk_fma_f32 v[116:117], v[162:163], v[116:117], v[186:187]
	v_pk_fma_f32 v[114:115], v[160:161], v[114:115], v[184:185]
	global_store_dwordx4 v204, v[114:117], s[60:61] offset:16
	global_load_dwordx4 v[184:187], v204, s[10:11] offset:512
	s_waitcnt vmcnt(16)
	v_pk_fma_f32 v[112:113], v[162:163], v[112:113], v[190:191]
	v_pk_fma_f32 v[110:111], v[160:161], v[110:111], v[188:189]
	global_store_dwordx4 v205, v[110:113], s[60:61] offset:16
	global_load_dwordx4 v[188:191], v205, s[10:11] offset:512
	s_waitcnt vmcnt(16)
	v_pk_fma_f32 v[104:105], v[162:163], v[104:105], v[194:195]
	v_pk_fma_f32 v[102:103], v[160:161], v[102:103], v[192:193]
	global_store_dwordx4 v224, v[102:105], s[60:61] offset:16
	global_load_dwordx4 v[192:195], v224, s[10:11] offset:512
	s_waitcnt vmcnt(16)
	v_pk_fma_f32 v[128:129], v[162:163], v[128:129], v[198:199]
	v_pk_fma_f32 v[126:127], v[160:161], v[126:127], v[196:197]
	global_store_dwordx4 v225, v[126:129], s[60:61] offset:16
	global_load_dwordx4 v[196:199], v225, s[10:11] offset:512
	s_waitcnt vmcnt(16)
	v_pk_fma_f32 v[124:125], v[162:163], v[124:125], v[202:203]
	v_pk_fma_f32 v[122:123], v[160:161], v[122:123], v[200:201]
	global_store_dwordx4 v232, v[122:125], s[60:61] offset:16
	global_load_dwordx4 v[200:203], v232, s[10:11] offset:512
	s_waitcnt vmcnt(16)
	v_pk_fma_f32 v[120:121], v[162:163], v[120:121], v[210:211]
	v_pk_fma_f32 v[118:119], v[160:161], v[118:119], v[208:209]
	global_store_dwordx4 v164, v[118:121], s[60:61] offset:16
	global_load_dwordx4 v[208:211], v164, s[10:11] offset:512
	s_waitcnt vmcnt(16)
	v_pk_fma_f32 v[72:73], v[162:163], v[72:73], v[154:155]
	v_pk_fma_f32 v[70:71], v[160:161], v[70:71], v[152:153]
	global_store_dwordx4 v165, v[70:73], s[60:61] offset:16
	global_load_dwordx4 v[152:155], v165, s[10:11] offset:512
	s_waitcnt vmcnt(16)
	v_pk_fma_f32 v[68:69], v[162:163], v[68:69], v[158:159]
	v_pk_fma_f32 v[66:67], v[160:161], v[66:67], v[156:157]
	global_store_dwordx4 v181, v[66:69], s[60:61] offset:16
	global_load_dwordx4 v[156:159], v181, s[10:11] offset:512
	s_waitcnt vmcnt(16)
	v_pk_mul_f32 v[172:173], v[130:131], v[134:135]
	v_pk_mul_f32 v[174:175], v[132:133], v[136:137]
	global_load_dwordx4 v[130:133], v[212:213], off offset:528
	global_load_dwordx4 v[134:137], v[214:215], off offset:528
	s_waitcnt vmcnt(16)
	v_pk_fma_f32 v[64:65], v[174:175], v[64:65], v[186:187]
	v_pk_fma_f32 v[62:63], v[172:173], v[62:63], v[184:185]
	global_store_dwordx4 v204, v[62:65], s[60:61] offset:512
	global_load_dwordx4 v[184:187], v204, s[10:11] offset:528
	s_waitcnt vmcnt(16)
	v_pk_fma_f32 v[60:61], v[174:175], v[60:61], v[190:191]
	v_pk_fma_f32 v[58:59], v[172:173], v[58:59], v[188:189]
	global_store_dwordx4 v205, v[58:61], s[60:61] offset:512
	global_load_dwordx4 v[188:191], v205, s[10:11] offset:528
	s_waitcnt vmcnt(16)
;     __device__ __forceinline__ void rowstat(const f32x4 (&v)[2][2][4][2], const Unit& u, int wr, int wc, int fr, int fq, float* slot, unsigned* cnt) const {
;     ...
;                 float ss = 0.f;
; #pragma unroll
;                 for (int bj = 0; bj < 2; ++bj)
; #pragma unroll
;                     for (int n = 0; n < 2; ++n) { const f32x4 x = v[ai][bj][m][n]; ss += (x[0] * x[0] + x[1] * x[1]) + (x[2] * x[2] + x[3] * x[3]); }
;                 ss += __shfl_xor(ss, 16); ss += __shfl_xor(ss, 32);
;     __device__ __forceinline__ void operator()(f32x4 (&acc)[2][2][4][2], const Unit& u, int wr, int wc, int fr, int fq) const {
;     ...
;             for (int n = 0; n < 2; ++n) {
;                 const int col = u.pn * BM + bj * HALF + wc * 32 + 8 * fq + 4 * n;
;                 const f32x4 gg = *(const f32x4*)(md + gate_off + col) * *(const f32x4*)(gpost + col);
; #pragma unroll
;                 for (int ai = 0; ai < 2; ++ai)
; #pragma unroll
;                     for (int m = 0; m < 4; ++m) {
;                         const int rl = ai * HALF + wr * 64 + m * 16 + fr; const size_t off = (size_t)(u.pm * BM + rl) * DM + col;
;                         const f32x4 xv = *(const f32x4*)(xin + off);
;                         const f32x4 xn = xv + gg * (acc[ai][bj][m][n] * S[rl]);
;                         acc[ai][bj][m][n] = xn; *(f32x4*)(xout + off) = xn;
;                     }
;             }
;         if (XN == nullptr) return;
;         asm volatile("s_waitcnt lgkmcnt(0)" ::: "memory"); __builtin_amdgcn_s_barrier(); asm volatile("" ::: "memory");
;         rowstat(acc, u, wr, wc, fr, fq, slot2, cnt2);
	v_pk_fma_f32 v[56:57], v[174:175], v[56:57], v[194:195]
	v_pk_fma_f32 v[54:55], v[172:173], v[54:55], v[192:193]
	global_store_dwordx4 v224, v[54:57], s[60:61] offset:512
	global_load_dwordx4 v[192:195], v224, s[10:11] offset:528
	s_waitcnt vmcnt(16)
	v_pk_fma_f32 v[52:53], v[174:175], v[52:53], v[198:199]
	v_pk_fma_f32 v[50:51], v[172:173], v[50:51], v[196:197]
	global_store_dwordx4 v225, v[50:53], s[60:61] offset:512
	global_load_dwordx4 v[196:199], v225, s[10:11] offset:528
	s_waitcnt vmcnt(16)
	v_pk_fma_f32 v[48:49], v[174:175], v[48:49], v[202:203]
	v_pk_fma_f32 v[46:47], v[172:173], v[46:47], v[200:201]
	global_store_dwordx4 v232, v[46:49], s[60:61] offset:512
	global_load_dwordx4 v[200:203], v232, s[10:11] offset:528
	s_waitcnt vmcnt(16)
	v_pk_fma_f32 v[44:45], v[174:175], v[44:45], v[210:211]
	v_pk_fma_f32 v[42:43], v[172:173], v[42:43], v[208:209]
	global_store_dwordx4 v164, v[42:45], s[60:61] offset:512
	global_load_dwordx4 v[208:211], v164, s[10:11] offset:528
	s_waitcnt vmcnt(16)
	v_pk_fma_f32 v[40:41], v[174:175], v[40:41], v[154:155]
	v_pk_fma_f32 v[38:39], v[172:173], v[38:39], v[152:153]
	global_store_dwordx4 v165, v[38:41], s[60:61] offset:512
	global_load_dwordx4 v[152:155], v165, s[10:11] offset:528
	s_waitcnt vmcnt(16)
	v_pk_fma_f32 v[20:21], v[174:175], v[20:21], v[158:159]
	v_pk_fma_f32 v[18:19], v[172:173], v[18:19], v[156:157]
	global_store_dwordx4 v181, v[18:21], s[60:61] offset:512
	global_load_dwordx4 v[156:159], v181, s[10:11] offset:528
	s_waitcnt vmcnt(16)
	v_pk_mul_f32 v[160:161], v[130:131], v[134:135]
	v_pk_mul_f32 v[162:163], v[132:133], v[136:137]
	s_waitcnt vmcnt(14)
	v_pk_fma_f32 v[136:137], v[162:163], v[36:37], v[186:187]
	v_pk_fma_f32 v[134:135], v[160:161], v[34:35], v[184:185]
	global_store_dwordx4 v204, v[134:137], s[60:61] offset:528
	s_waitcnt vmcnt(13)
	v_pk_fma_f32 v[132:133], v[162:163], v[32:33], v[190:191]
	v_pk_fma_f32 v[130:131], v[160:161], v[30:31], v[188:189]
	global_store_dwordx4 v205, v[130:133], s[60:61] offset:528
	s_waitcnt vmcnt(12)
	v_pk_fma_f32 v[36:37], v[162:163], v[28:29], v[194:195]
	v_pk_fma_f32 v[34:35], v[160:161], v[26:27], v[192:193]
	global_store_dwordx4 v224, v[34:37], s[60:61] offset:528
	s_waitcnt vmcnt(11)
	v_pk_fma_f32 v[24:25], v[162:163], v[24:25], v[198:199]
	v_pk_fma_f32 v[22:23], v[160:161], v[22:23], v[196:197]
	global_store_dwordx4 v225, v[22:25], s[60:61] offset:528
	s_waitcnt vmcnt(10)
	v_pk_fma_f32 v[16:17], v[162:163], v[16:17], v[202:203]
	v_pk_fma_f32 v[14:15], v[160:161], v[14:15], v[200:201]
	global_store_dwordx4 v232, v[14:17], s[60:61] offset:528
	s_waitcnt vmcnt(9)
	v_pk_fma_f32 v[10:11], v[162:163], v[10:11], v[210:211]
	v_pk_fma_f32 v[8:9], v[160:161], v[8:9], v[208:209]
	global_store_dwordx4 v164, v[8:11], s[60:61] offset:528
	s_waitcnt vmcnt(8)
	v_pk_fma_f32 v[6:7], v[162:163], v[6:7], v[154:155]
	v_pk_fma_f32 v[4:5], v[160:161], v[4:5], v[152:153]
	global_store_dwordx4 v165, v[4:7], s[60:61] offset:528
	s_waitcnt vmcnt(7)
	v_pk_fma_f32 v[2:3], v[162:163], v[2:3], v[158:159]
	v_pk_fma_f32 v[0:1], v[160:161], v[0:1], v[156:157]
	global_store_dwordx4 v181, v[0:3], s[60:61] offset:528
	v_add_u32_e32 v180, s40, v166
	v_ashrrev_i32_e32 v181, 31, v180
	v_add_u32_e32 v164, s40, v217
	v_ashrrev_i32_e32 v165, 31, v164
	v_add_u32_e32 v162, s40, v219
	v_ashrrev_i32_e32 v163, 31, v162
	v_add_u32_e32 v160, s40, v221
	v_ashrrev_i32_e32 v161, 31, v160
	v_add_u32_e32 v152, s40, v207
	v_ashrrev_i32_e32 v153, 31, v152
	v_add_u32_e32 v158, s40, v227
	v_ashrrev_i32_e32 v159, 31, v158
	v_add_u32_e32 v156, s40, v229
	v_ashrrev_i32_e32 v157, 31, v156
	v_add_u32_e32 v154, s40, v231
	v_ashrrev_i32_e32 v155, 31, v154
	v_or_b32_e32 v222, 0x80, v178
	v_ashrrev_i32_e32 v223, 31, v222
	v_readlane_b32 s40, v253, 34
	v_readlane_b32 s41, v253, 35
	s_nop 3
	s_andn2_b64 vcc, exec, s[40:41]
	s_nop 1
	s_cbranch_vccnz .LBB0_979
	v_mul_f32_e32 v26, v107, v107
	v_mul_f32_e32 v27, v109, v109
	v_fmac_f32_e32 v26, v106, v106
	v_fmac_f32_e32 v27, v108, v108
	v_add_f32_e32 v26, v26, v27
	v_mul_f32_e32 v27, v115, v115
	v_mul_f32_e32 v28, v117, v117
	v_fmac_f32_e32 v27, v114, v114
	v_fmac_f32_e32 v28, v116, v116
	v_add_f32_e32 v27, v27, v28
	v_add_f32_e32 v26, v26, v27
	v_mul_f32_e32 v27, v63, v63
	v_mul_f32_e32 v28, v65, v65
	v_fmac_f32_e32 v27, v62, v62
	v_fmac_f32_e32 v28, v64, v64
	v_add_f32_e32 v27, v27, v28
	v_add_f32_e32 v26, v26, v27
	v_mul_f32_e32 v27, v135, v135
	v_mul_f32_e32 v28, v137, v137
	v_fmac_f32_e32 v27, v134, v134
	v_fmac_f32_e32 v28, v136, v136
	v_add_f32_e32 v27, v27, v28
	v_add_f32_e32 v26, v26, v27
	s_waitcnt lgkmcnt(0)
	s_barrier
;     __device__ __forceinline__ void rowstat(const f32x4 (&v)[2][2][4][2], const Unit& u, int wr, int wc, int fr, int fq, float* slot, unsigned* cnt) const {
;     ...
;         for (int ai = 0; ai < 2; ++ai)
; #pragma unroll
;             for (int m = 0; m < 4; ++m) {
;                 float ss = 0.f;
; #pragma unroll
;                 for (int bj = 0; bj < 2; ++bj)
; #pragma unroll
;                     for (int n = 0; n < 2; ++n) { const f32x4 x = v[ai][bj][m][n]; ss += (x[0] * x[0] + x[1] * x[1]) + (x[2] * x[2] + x[3] * x[3]); }
;                 ss += __shfl_xor(ss, 16); ss += __shfl_xor(ss, 32);
;                 if (fq == 0) Pp[(ai * HALF + wr * 64 + m * 16 + fr) * 4 + wc] = ss;
	v_mov_b32_e32 v29, v26
	v_mul_f32_e32 v26, v99, v99
	v_mul_f32_e32 v27, v101, v101
	v_fmac_f32_e32 v26, v98, v98
	v_fmac_f32_e32 v27, v100, v100
	v_add_f32_e32 v26, v26, v27
	v_mul_f32_e32 v27, v111, v111
	v_mul_f32_e32 v28, v113, v113
	v_fmac_f32_e32 v27, v110, v110
	v_fmac_f32_e32 v28, v112, v112
	v_add_f32_e32 v27, v27, v28
	v_add_f32_e32 v26, v26, v27
	v_mul_f32_e32 v27, v59, v59
	v_mul_f32_e32 v28, v61, v61
	v_fmac_f32_e32 v27, v58, v58
	v_fmac_f32_e32 v28, v60, v60
	v_add_f32_e32 v27, v27, v28
	v_add_f32_e32 v26, v26, v27
	v_mul_f32_e32 v27, v131, v131
	v_mul_f32_e32 v28, v133, v133
	v_fmac_f32_e32 v27, v130, v130
	v_fmac_f32_e32 v28, v132, v132
	v_add_f32_e32 v27, v27, v28
	v_add_f32_e32 v26, v26, v27
	v_mov_b32_e32 v30, v26
	v_mul_f32_e32 v26, v95, v95
	v_mul_f32_e32 v27, v97, v97
	v_fmac_f32_e32 v26, v94, v94
	v_fmac_f32_e32 v27, v96, v96
	v_add_f32_e32 v26, v26, v27
	v_mul_f32_e32 v27, v103, v103
	v_mul_f32_e32 v28, v105, v105
	v_fmac_f32_e32 v27, v102, v102
	v_fmac_f32_e32 v28, v104, v104
	v_add_f32_e32 v27, v27, v28
	v_add_f32_e32 v26, v26, v27
	v_mul_f32_e32 v27, v55, v55
	v_mul_f32_e32 v28, v57, v57
	v_fmac_f32_e32 v27, v54, v54
	v_fmac_f32_e32 v28, v56, v56
	v_add_f32_e32 v27, v27, v28
	v_add_f32_e32 v26, v26, v27
	v_mul_f32_e32 v27, v35, v35
	v_mul_f32_e32 v28, v37, v37
	v_fmac_f32_e32 v27, v34, v34
	v_fmac_f32_e32 v28, v36, v36
	v_add_f32_e32 v27, v27, v28
	v_add_f32_e32 v26, v26, v27
	v_mov_b32_e32 v31, v26
	v_mul_f32_e32 v26, v91, v91
	v_mul_f32_e32 v27, v93, v93
	v_fmac_f32_e32 v26, v90, v90
	v_fmac_f32_e32 v27, v92, v92
	v_add_f32_e32 v26, v26, v27
	v_mul_f32_e32 v27, v127, v127
	v_mul_f32_e32 v28, v129, v129
	v_fmac_f32_e32 v27, v126, v126
	v_fmac_f32_e32 v28, v128, v128
	v_add_f32_e32 v27, v27, v28
	v_add_f32_e32 v26, v26, v27
	v_mul_f32_e32 v27, v51, v51
	v_mul_f32_e32 v28, v53, v53
	v_fmac_f32_e32 v27, v50, v50
	v_fmac_f32_e32 v28, v52, v52
	v_add_f32_e32 v27, v27, v28
	v_add_f32_e32 v26, v26, v27
	v_mul_f32_e32 v27, v23, v23
	v_mul_f32_e32 v28, v25, v25
	v_fmac_f32_e32 v27, v22, v22
	v_fmac_f32_e32 v28, v24, v24
	v_add_f32_e32 v27, v27, v28
	v_add_f32_e32 v26, v26, v27
	v_mov_b32_e32 v32, v26
	v_mul_f32_e32 v26, v87, v87
	v_mul_f32_e32 v27, v89, v89
	v_fmac_f32_e32 v26, v86, v86
	v_fmac_f32_e32 v27, v88, v88
	v_add_f32_e32 v26, v26, v27
	v_mul_f32_e32 v27, v123, v123
	v_mul_f32_e32 v28, v125, v125
	v_fmac_f32_e32 v27, v122, v122
	v_fmac_f32_e32 v28, v124, v124
	v_add_f32_e32 v27, v27, v28
	v_add_f32_e32 v26, v26, v27
	v_mul_f32_e32 v27, v47, v47
	v_mul_f32_e32 v28, v49, v49
	v_fmac_f32_e32 v27, v46, v46
	v_fmac_f32_e32 v28, v48, v48
	v_add_f32_e32 v27, v27, v28
	v_add_f32_e32 v26, v26, v27
	v_mul_f32_e32 v27, v15, v15
	v_mul_f32_e32 v28, v17, v17
	v_fmac_f32_e32 v27, v14, v14
	v_fmac_f32_e32 v28, v16, v16
	v_add_f32_e32 v27, v27, v28
	v_add_f32_e32 v26, v26, v27
	v_mov_b32_e32 v33, v26
	v_mul_f32_e32 v26, v83, v83
	v_mul_f32_e32 v27, v85, v85
	v_fmac_f32_e32 v26, v82, v82
	v_fmac_f32_e32 v27, v84, v84
	v_add_f32_e32 v26, v26, v27
	v_mul_f32_e32 v27, v119, v119
	v_mul_f32_e32 v28, v121, v121
	v_fmac_f32_e32 v27, v118, v118
	v_fmac_f32_e32 v28, v120, v120
	v_add_f32_e32 v27, v27, v28
	v_add_f32_e32 v26, v26, v27
	v_mul_f32_e32 v27, v43, v43
	v_mul_f32_e32 v28, v45, v45
	v_fmac_f32_e32 v27, v42, v42
	v_fmac_f32_e32 v28, v44, v44
	v_add_f32_e32 v27, v27, v28
	v_add_f32_e32 v26, v26, v27
	v_mul_f32_e32 v27, v9, v9
	v_mul_f32_e32 v28, v11, v11
	v_fmac_f32_e32 v27, v8, v8
	v_fmac_f32_e32 v28, v10, v10
	v_add_f32_e32 v27, v27, v28
	v_add_f32_e32 v26, v26, v27
	v_mov_b32_e32 v172, v26
	v_mul_f32_e32 v26, v79, v79
	v_mul_f32_e32 v27, v81, v81
	v_fmac_f32_e32 v26, v78, v78
	v_fmac_f32_e32 v27, v80, v80
	v_add_f32_e32 v26, v26, v27
	v_mul_f32_e32 v27, v71, v71
	v_mul_f32_e32 v28, v73, v73
	v_fmac_f32_e32 v27, v70, v70
	v_fmac_f32_e32 v28, v72, v72
	v_add_f32_e32 v27, v27, v28
	v_add_f32_e32 v26, v26, v27
	v_mul_f32_e32 v27, v39, v39
	v_mul_f32_e32 v28, v41, v41
	v_fmac_f32_e32 v27, v38, v38
	v_fmac_f32_e32 v28, v40, v40
	v_add_f32_e32 v27, v27, v28
	v_add_f32_e32 v26, v26, v27
	v_mul_f32_e32 v27, v5, v5
	v_mul_f32_e32 v28, v7, v7
	v_fmac_f32_e32 v27, v4, v4
	v_fmac_f32_e32 v28, v6, v6
	v_add_f32_e32 v27, v27, v28
	v_add_f32_e32 v26, v26, v27
	v_mov_b32_e32 v173, v26
	v_mul_f32_e32 v26, v75, v75
	v_mul_f32_e32 v27, v77, v77
	v_fmac_f32_e32 v26, v74, v74
	v_fmac_f32_e32 v27, v76, v76
	v_add_f32_e32 v26, v26, v27
	v_mul_f32_e32 v27, v67, v67
	v_mul_f32_e32 v28, v69, v69
	v_fmac_f32_e32 v27, v66, v66
	v_fmac_f32_e32 v28, v68, v68
	v_add_f32_e32 v27, v27, v28
	v_add_f32_e32 v26, v26, v27
	v_mul_f32_e32 v27, v19, v19
	v_mul_f32_e32 v28, v21, v21
	v_fmac_f32_e32 v27, v18, v18
	v_fmac_f32_e32 v28, v20, v20
	v_add_f32_e32 v27, v27, v28
	v_add_f32_e32 v26, v26, v27
	v_mul_f32_e32 v27, v1, v1
	v_mul_f32_e32 v28, v3, v3
	v_fmac_f32_e32 v27, v0, v0
	v_fmac_f32_e32 v28, v2, v2
	v_add_f32_e32 v27, v27, v28
	v_add_f32_e32 v26, v26, v27
	v_mov_b32_e32 v174, v26
	ds_bpermute_b32 v175, v170, v29
	ds_bpermute_b32 v176, v170, v30
	ds_bpermute_b32 v177, v170, v31
	ds_bpermute_b32 v184, v170, v32
	ds_bpermute_b32 v185, v170, v33
	ds_bpermute_b32 v186, v170, v172
	ds_bpermute_b32 v187, v170, v173
	ds_bpermute_b32 v188, v170, v174
	s_waitcnt lgkmcnt(0)
	v_add_f32_e32 v29, v29, v175
	v_add_f32_e32 v30, v30, v176
	v_add_f32_e32 v31, v31, v177
	v_add_f32_e32 v32, v32, v184
	v_add_f32_e32 v33, v33, v185
	v_add_f32_e32 v172, v172, v186
	v_add_f32_e32 v173, v173, v187
	v_add_f32_e32 v174, v174, v188
	ds_bpermute_b32 v175, v171, v29
	ds_bpermute_b32 v176, v171, v30
	ds_bpermute_b32 v177, v171, v31
	ds_bpermute_b32 v184, v171, v32
	ds_bpermute_b32 v185, v171, v33
	ds_bpermute_b32 v186, v171, v172
	ds_bpermute_b32 v187, v171, v173
	ds_bpermute_b32 v188, v171, v174
	s_and_saveexec_b64 s[40:41], s[2:3]
	s_cbranch_execz .Lrs_skip_1
	s_waitcnt lgkmcnt(0)
	v_add_f32_e32 v29, v29, v175
	v_add_f32_e32 v30, v30, v176
	v_add_f32_e32 v31, v31, v177
	v_add_f32_e32 v32, v32, v184
	v_add_f32_e32 v33, v33, v185
	v_add_f32_e32 v172, v172, v186
	v_add_f32_e32 v173, v173, v187
	v_add_f32_e32 v174, v174, v188
	ds_write_b32 v248, v29
	ds_write_b32 v248, v30 offset:256
	ds_write_b32 v248, v31 offset:512
	ds_write_b32 v248, v32 offset:768
	ds_write_b32 v248, v33 offset:2048
	ds_write_b32 v248, v172 offset:2304
	ds_write_b32 v248, v173 offset:2560
	ds_write_b32 v248, v174 offset:2816

;     __device__ __forceinline__ void operator()(const f32x4 (&acc)[2][2][4][2], const Unit& u, int wr, int wc, int fr, int fq) const {
;     ...
;         for (int bj = 0; bj < 2; ++bj) {
;             const int col = u.pn * BM + bj * HALF + wc * 32 + 8 * fq;
;             f32x4 w0[2], w1[2], w2[2], bb[2];
; #pragma unroll
;             for (int n = 0; n < 2; ++n) { w0[n] = *(const f32x4*)(cw + col + 4 * n); w1[n] = *(const f32x4*)(cw + DFF + col + 4 * n); w2[n] = *(const f32x4*)(cw + 2 * DFF + col + 4 * n); bb[n] = *(const f32x4*)(cb + col + 4 * n); }
; #pragma unroll
;             for (int ai = 0; ai < 2; ++ai)
; #pragma unroll
;                 for (int m = 0; m < 4; ++m) {
;                     const int row = u.pm * BM + ai * HALF + wr * 64 + m * 16 + fr;
;                     const int t = row & (SEQ - 1);
;                     const bf16_t* gp = G + (size_t)row * DFF + col;
;                     const bool hasm = t > 0, hasn = t < SEQ - 1;
;                     u32x4 gm = *(const u32x4*)(gp - (hasm ? DFF : 0));
;                     const u32x4 g0 = *(const u32x4*)gp;
;                     u32x4 gn = *(const u32x4*)(gp + (hasn ? DFF : 0));
;                     const unsigned mm = hasm ? 0xffffffffu : 0u, mn = hasn ? 0xffffffffu : 0u;
;                     gm.x &= mm; gm.y &= mm; gm.z &= mm; gm.w &= mm; gn.x &= mn; gn.y &= mn; gn.z &= mn; gn.w &= mn;
;                     unsigned ow[4];
; #pragma unroll
;                     for (int n = 0; n < 2; ++n) {
;                         const unsigned m0 = n ? gm.z : gm.x, m1 = n ? gm.w : gm.y, c0 = n ? g0.z : g0.x, c1 = n ? g0.w : g0.y, n0 = n ? gn.z : gn.x, n1 = n ? gn.w : gn.y;
;                         const f32x4 fm = {bflo(m0), bfhi(m0), bflo(m1), bfhi(m1)}, f0 = {bflo(c0), bfhi(c0), bflo(c1), bfhi(c1)}, fn = {bflo(n0), bfhi(n0), bflo(n1), bfhi(n1)};
;                         const f32x4 gc = bb[n] + fm * w0[n] + f0 * w1[n] + fn * w2[n];
;                         const f32x4 a = acc[ai][bj][m][n];
;                         constexpr float C1 = -2.0f * LOG2E * 0.7978845608028654f, C2 = C1 * 0.044715f;
;                         const f32x4 arg = gc * ((gc * gc) * C2 + C1);
;                         const f32x4 den = (f32x4){__builtin_amdgcn_exp2f(arg[0]), __builtin_amdgcn_exp2f(arg[1]), __builtin_amdgcn_exp2f(arg[2]), __builtin_amdgcn_exp2f(arg[3])} + 1.0f;
.LBB0_1115:
	v_lshl_or_b32 v226, s10, 8, v244
	v_lshl_add_u32 v166, s11, 8, v242
	v_ashrrev_i32_e32 v227, 31, v226
	v_and_b32_e32 v12, 0xfcf, v166
	v_mov_b64_e32 v[232:233], s[72:73]
	v_lshlrev_b64 v[122:123], 2, v[226:227]
	v_mad_i64_i32 v[162:163], s[4:5], v166, s67, v[232:233]
	v_lshlrev_b64 v[230:231], 1, v[226:227]
	v_cmp_eq_u32_e64 s[8:9], 0, v12
	v_mov_b32_e32 v227, 0xffffea00
	v_lshl_add_u64 v[216:217], v[162:163], 0, v[230:231]
	v_mov_b64_e32 v[246:247], v[216:217]
	v_cndmask_b32_e64 v163, -1, 0, s[8:9]
	v_cndmask_b32_e64 v162, v227, 0, s[8:9]
	v_lshl_add_u64 v[224:225], s[26:27], 0, v[122:123]
	v_lshl_add_u64 v[130:131], s[16:17], 0, v[122:123]
	v_lshl_add_u64 v[134:135], s[12:13], 0, v[122:123]
	v_lshl_add_u64 v[228:229], v[216:217], 0, v[162:163]
	v_lshl_add_u64 v[222:223], s[30:31], 0, v[122:123]
	global_load_dwordx4 v[122:125], v[224:225], off offset:16
	global_load_dwordx4 v[138:141], v[224:225], off
	global_load_dwordx4 v[126:129], v[130:131], off offset:16
	global_load_dwordx4 v[142:145], v[130:131], off
	s_nop 0
	global_load_dwordx4 v[130:133], v[134:135], off offset:16
	global_load_dwordx4 v[146:149], v[134:135], off
	s_nop 0
	global_load_dwordx4 v[134:137], v[222:223], off offset:16
	global_load_dwordx4 v[150:153], v[222:223], off
	global_load_dwordx4 v[168:171], v[228:229], off
	global_load_dwordx4 v[162:165], v[216:217], off
	v_add_co_u32_e32 v218, vcc, s52, v216
	s_mov_b32 s4, 0xc0135761
	s_nop 0
	v_addc_co_u32_e32 v219, vcc, 0, v217, vcc
	global_load_dwordx4 v[172:175], v[218:219], off offset:1536
	v_mov_b64_e32 v[234:235], s[14:15]
	s_waitcnt vmcnt(0)
	s_mov_b32 s100, 88064
	s_mov_b32 s101, 0
	v_lshl_add_u64 v[204:205], v[246:247], 0, s[100:101]
	s_mov_b32 s100, 94208
	v_lshl_add_u64 v[202:203], v[246:247], 0, s[100:101]
	global_load_dwordx4 v[194:197], v[204:205], off offset:-3584
	global_load_dwordx4 v[198:201], v[204:205], off offset:2048
	global_load_dwordx4 v[202:205], v[202:203], off offset:1536
	v_cndmask_b32_e64 v12, v168, 0, s[8:9]
	v_cndmask_b32_e64 v167, v169, 0, s[8:9]
	v_cndmask_b32_e64 v192, v170, 0, s[8:9]
	v_cndmask_b32_e64 v193, v171, 0, s[8:9]
	v_lshlrev_b32_e32 v168, 16, v12
	v_and_b32_e32 v169, 0xffff0000, v12
	v_lshlrev_b32_e32 v170, 16, v167
	v_and_b32_e32 v171, 0xffff0000, v167
	v_lshlrev_b32_e32 v176, 16, v162
	v_and_b32_e32 v177, 0xffff0000, v162
	v_lshlrev_b32_e32 v162, 16, v163
	v_and_b32_e32 v163, 0xffff0000, v163
	v_pk_fma_f32 v[168:169], v[138:139], v[168:169], v[150:151]
	v_pk_fma_f32 v[170:171], v[140:141], v[170:171], v[152:153]
	v_lshlrev_b32_e32 v190, 16, v172
	v_and_b32_e32 v191, 0xffff0000, v172
	v_lshlrev_b32_e32 v172, 16, v173
	v_and_b32_e32 v173, 0xffff0000, v173
	v_pk_fma_f32 v[162:163], v[144:145], v[162:163], v[170:171]
	v_pk_fma_f32 v[168:169], v[142:143], v[176:177], v[168:169]
	v_pk_fma_f32 v[170:171], v[148:149], v[172:173], v[162:163]
	v_pk_fma_f32 v[168:169], v[146:147], v[190:191], v[168:169]
	v_pk_mul_f32 v[172:173], v[170:171], v[170:171]
	v_pk_mul_f32 v[176:177], v[168:169], v[168:169]
	v_mov_b64_e32 v[162:163], s[4:5]
	v_pk_fma_f32 v[176:177], v[176:177], s[86:87], v[162:163] op_sel_hi:[1,0,0] neg_lo:[1,0,0] neg_hi:[1,0,0]
	v_pk_fma_f32 v[172:173], v[172:173], s[86:87], v[162:163] op_sel_hi:[1,0,0] neg_lo:[1,0,0] neg_hi:[1,0,0]
	v_pk_mul_f32 v[176:177], v[168:169], v[176:177]
	v_pk_mul_f32 v[172:173], v[170:171], v[172:173]
	v_exp_f32_e32 v176, v176
	v_exp_f32_e32 v177, v177
	v_exp_f32_e32 v172, v172
	v_exp_f32_e32 v173, v173
	v_pk_mul_f32 v[158:159], v[158:159], v[168:169]
	v_pk_add_f32 v[176:177], v[176:177], 1.0 op_sel_hi:[1,0]
	v_pk_mul_f32 v[160:161], v[160:161], v[170:171]
	v_pk_add_f32 v[172:173], v[172:173], 1.0 op_sel_hi:[1,0]
	v_rcp_f32_e32 v176, v176
	v_rcp_f32_e32 v177, v177
	v_rcp_f32_e32 v172, v172
	v_rcp_f32_e32 v173, v173
	v_lshlrev_b32_e32 v170, 16, v164
	v_pk_mul_f32 v[158:159], v[158:159], v[176:177]
	v_and_b32_e32 v171, 0xffff0000, v164
	v_pk_mul_f32 v[160:161], v[160:161], v[172:173]
	v_cvt_pk_bf16_f32 v158, v158, v159
	v_cvt_pk_bf16_f32 v159, v160, v161
	v_lshlrev_b32_e32 v160, 16, v192
	v_and_b32_e32 v161, 0xffff0000, v192
	v_pk_fma_f32 v[160:161], v[122:123], v[160:161], v[134:135]
	v_lshlrev_b32_e32 v172, 16, v174
	v_and_b32_e32 v173, 0xffff0000, v174
	v_pk_fma_f32 v[160:161], v[126:127], v[170:171], v[160:161]
	v_lshlrev_b32_e32 v168, 16, v193
	v_pk_fma_f32 v[160:161], v[130:131], v[172:173], v[160:161]
	v_and_b32_e32 v169, 0xffff0000, v193
	v_pk_mul_f32 v[170:171], v[160:161], v[160:161]
	v_lshlrev_b32_e32 v164, 16, v165
	v_and_b32_e32 v165, 0xffff0000, v165
	v_pk_fma_f32 v[168:169], v[124:125], v[168:169], v[136:137]
	v_pk_fma_f32 v[170:171], v[170:171], s[86:87], v[162:163] op_sel_hi:[1,0,0] neg_lo:[1,0,0] neg_hi:[1,0,0]
	v_lshlrev_b32_e32 v174, 16, v175
	v_and_b32_e32 v175, 0xffff0000, v175
	v_pk_fma_f32 v[164:165], v[128:129], v[164:165], v[168:169]
	v_pk_mul_f32 v[170:171], v[160:161], v[170:171]
	v_pk_fma_f32 v[164:165], v[132:133], v[174:175], v[164:165]
	v_exp_f32_e32 v170, v170
	v_exp_f32_e32 v171, v171
	v_pk_mul_f32 v[168:169], v[164:165], v[164:165]
	v_pk_mul_f32 v[154:155], v[154:155], v[160:161]
	v_pk_fma_f32 v[168:169], v[168:169], s[86:87], v[162:163] op_sel_hi:[1,0,0] neg_lo:[1,0,0] neg_hi:[1,0,0]
	v_pk_add_f32 v[170:171], v[170:171], 1.0 op_sel_hi:[1,0]
	v_pk_mul_f32 v[168:169], v[164:165], v[168:169]
	v_rcp_f32_e32 v170, v170
	v_exp_f32_e32 v168, v168
	v_exp_f32_e32 v169, v169
	v_rcp_f32_e32 v171, v171
	v_or_b32_e32 v12, 16, v166
	v_pk_mul_f32 v[156:157], v[156:157], v[164:165]
	v_pk_add_f32 v[168:169], v[168:169], 1.0 op_sel_hi:[1,0]
	v_pk_mul_f32 v[154:155], v[154:155], v[170:171]
	v_rcp_f32_e32 v168, v168
	v_rcp_f32_e32 v169, v169
	v_cvt_pk_bf16_f32 v160, v154, v155
	v_mad_i64_i32 v[154:155], s[4:5], v166, s67, v[234:235]
	v_lshl_add_u64 v[220:221], v[154:155], 0, v[230:231]
	v_mad_i64_i32 v[154:155], s[4:5], v12, s67, v[232:233]
	v_lshl_add_u64 v[212:213], v[154:155], 0, v[230:231]
	v_pk_mul_f32 v[156:157], v[156:157], v[168:169]
	v_add_co_u32_e32 v214, vcc, s53, v212
	v_cvt_pk_bf16_f32 v161, v156, v157
	s_nop 0
	v_addc_co_u32_e32 v215, vcc, -1, v213, vcc
	global_store_dwordx4 v[220:221], v[158:161], off
	v_add_co_u32_e32 v208, vcc, s52, v212
	v_addc_co_u32_e32 v209, vcc, 0, v213, vcc
	v_mov_b32_e32 v167, 0x1600
	s_waitcnt vmcnt(3)
; __device__ __forceinline__ float bflo(unsigned u) { return __uint_as_float(u << 16); }
;     __device__ __forceinline__ void operator()(const f32x4 (&acc)[2][2][4][2], const Unit& u, int wr, int wc, int fr, int fq) const {
;     ...
;                     const int row = u.pm * BM + ai * HALF + wr * 64 + m * 16 + fr;
;                     const int t = row & (SEQ - 1);
;                     const bf16_t* gp = G + (size_t)row * DFF + col;
;                     const bool hasm = t > 0, hasn = t < SEQ - 1;
;                     u32x4 gm = *(const u32x4*)(gp - (hasm ? DFF : 0));
;                     const u32x4 g0 = *(const u32x4*)gp;
;                     u32x4 gn = *(const u32x4*)(gp + (hasn ? DFF : 0));
;                     const unsigned mm = hasm ? 0xffffffffu : 0u, mn = hasn ? 0xffffffffu : 0u;
;                     gm.x &= mm; gm.y &= mm; gm.z &= mm; gm.w &= mm; gn.x &= mn; gn.y &= mn; gn.z &= mn; gn.w &= mn;
;                     unsigned ow[4];
; #pragma unroll
;                     for (int n = 0; n < 2; ++n) {
;                         const unsigned m0 = n ? gm.z : gm.x, m1 = n ? gm.w : gm.y, c0 = n ? g0.z : g0.x, c1 = n ? g0.w : g0.y, n0 = n ? gn.z : gn.x, n1 = n ? gn.w : gn.y;
;                         const f32x4 fm = {bflo(m0), bfhi(m0), bflo(m1), bfhi(m1)}, f0 = {bflo(c0), bfhi(c0), bflo(c1), bfhi(c1)}, fn = {bflo(n0), bfhi(n0), bflo(n1), bfhi(n1)};
;                         const f32x4 gc = bb[n] + fm * w0[n] + f0 * w1[n] + fn * w2[n];
;                         const f32x4 a = acc[ai][bj][m][n];
;                         constexpr float C1 = -2.0f * LOG2E * 0.7978845608028654f, C2 = C1 * 0.044715f;
;                         const f32x4 arg = gc * ((gc * gc) * C2 + C1);
;                         const f32x4 den = (f32x4){__builtin_amdgcn_exp2f(arg[0]), __builtin_amdgcn_exp2f(arg[1]), __builtin_amdgcn_exp2f(arg[2]), __builtin_amdgcn_exp2f(arg[3])} + 1.0f;
;                         const f32x4 rc = {__builtin_amdgcn_rcpf(den[0]), __builtin_amdgcn_rcpf(den[1]), __builtin_amdgcn_rcpf(den[2]), __builtin_amdgcn_rcpf(den[3])};
;                         const f32x4 o = (gc * a) * rc;
;                         ow[2 * n] = pk2(o[0], o[1]); ow[2 * n + 1] = pk2(o[2], o[3]);
;                     }
;                     *(u32x4*)(H + (size_t)row * DFF + col) = (u32x4){ow[0], ow[1], ow[2], ow[3]};
	v_lshlrev_b32_e32 v164, 16, v194
	v_and_b32_e32 v165, 0xffff0000, v194
	v_lshlrev_b32_e32 v154, 16, v195
	v_and_b32_e32 v155, 0xffff0000, v195
	s_waitcnt vmcnt(2)
	v_lshlrev_b32_e32 v172, 16, v198
	v_and_b32_e32 v173, 0xffff0000, v198
	v_lshlrev_b32_e32 v158, 16, v199
	v_and_b32_e32 v159, 0xffff0000, v199
	v_pk_fma_f32 v[164:165], v[138:139], v[164:165], v[150:151]
	v_pk_fma_f32 v[154:155], v[140:141], v[154:155], v[152:153]
	s_waitcnt vmcnt(1)
	v_lshlrev_b32_e32 v174, 16, v202
	v_and_b32_e32 v175, 0xffff0000, v202
	v_lshlrev_b32_e32 v168, 16, v203
	v_and_b32_e32 v169, 0xffff0000, v203
	v_pk_fma_f32 v[154:155], v[144:145], v[158:159], v[154:155]
	v_pk_fma_f32 v[158:159], v[142:143], v[172:173], v[164:165]
	v_pk_fma_f32 v[154:155], v[148:149], v[168:169], v[154:155]
	v_pk_fma_f32 v[158:159], v[146:147], v[174:175], v[158:159]
	v_pk_mul_f32 v[164:165], v[154:155], v[154:155]
	s_mov_b32 s100, 178176
	s_mov_b32 s101, 0
	v_lshl_add_u64 v[250:251], v[246:247], 0, s[100:101]
	s_mov_b32 s100, 184320
	v_lshl_add_u64 v[248:249], v[246:247], 0, s[100:101]
	global_load_dwordx4 v[172:175], v[250:251], off offset:-3584
	global_load_dwordx4 v[190:193], v[250:251], off offset:2048
	global_load_dwordx4 v[248:251], v[248:249], off offset:1536
	v_pk_mul_f32 v[168:169], v[158:159], v[158:159]
	v_pk_fma_f32 v[164:165], v[164:165], s[86:87], v[162:163] op_sel_hi:[1,0,0] neg_lo:[1,0,0] neg_hi:[1,0,0]
	v_pk_fma_f32 v[168:169], v[168:169], s[86:87], v[162:163] op_sel_hi:[1,0,0] neg_lo:[1,0,0] neg_hi:[1,0,0]
	v_pk_mul_f32 v[164:165], v[154:155], v[164:165]
	v_pk_mul_f32 v[168:169], v[158:159], v[168:169]
	v_exp_f32_e32 v164, v164
	v_exp_f32_e32 v168, v168
	v_exp_f32_e32 v169, v169
	v_exp_f32_e32 v165, v165
	v_pk_mul_f32 v[118:119], v[118:119], v[158:159]
	v_pk_mul_f32 v[120:121], v[120:121], v[154:155]
	v_pk_add_f32 v[168:169], v[168:169], 1.0 op_sel_hi:[1,0]
	v_pk_add_f32 v[164:165], v[164:165], 1.0 op_sel_hi:[1,0]
	v_rcp_f32_e32 v168, v168
	v_rcp_f32_e32 v169, v169
	v_rcp_f32_e32 v164, v164
	v_rcp_f32_e32 v165, v165
	v_lshlrev_b32_e32 v154, 16, v197
	v_pk_mul_f32 v[118:119], v[118:119], v[168:169]
	v_and_b32_e32 v155, 0xffff0000, v197
	v_pk_mul_f32 v[120:121], v[120:121], v[164:165]
	v_cvt_pk_bf16_f32 v118, v118, v119
	v_cvt_pk_bf16_f32 v119, v120, v121
	v_lshlrev_b32_e32 v120, 16, v196
	v_and_b32_e32 v121, 0xffff0000, v196
	v_lshlrev_b32_e32 v156, 16, v200
	v_and_b32_e32 v157, 0xffff0000, v200
	v_pk_fma_f32 v[120:121], v[122:123], v[120:121], v[134:135]
	v_lshlrev_b32_e32 v158, 16, v201
	v_and_b32_e32 v159, 0xffff0000, v201
	v_lshlrev_b32_e32 v160, 16, v204
	v_and_b32_e32 v161, 0xffff0000, v204
	v_pk_fma_f32 v[120:121], v[126:127], v[156:157], v[120:121]
	v_pk_fma_f32 v[154:155], v[124:125], v[154:155], v[136:137]
	v_pk_fma_f32 v[120:121], v[130:131], v[160:161], v[120:121]
	v_pk_fma_f32 v[154:155], v[128:129], v[158:159], v[154:155]
	v_pk_mul_f32 v[158:159], v[120:121], v[120:121]
	v_lshlrev_b32_e32 v164, 16, v205
	v_pk_fma_f32 v[158:159], v[158:159], s[86:87], v[162:163] op_sel_hi:[1,0,0] neg_lo:[1,0,0] neg_hi:[1,0,0]
	v_and_b32_e32 v165, 0xffff0000, v205
	v_pk_mul_f32 v[158:159], v[120:121], v[158:159]
	v_pk_fma_f32 v[154:155], v[132:133], v[164:165], v[154:155]
	v_exp_f32_e32 v158, v158
	v_exp_f32_e32 v159, v159
	v_pk_mul_f32 v[156:157], v[154:155], v[154:155]
	v_pk_mul_f32 v[114:115], v[114:115], v[120:121]
	v_pk_fma_f32 v[156:157], v[156:157], s[86:87], v[162:163] op_sel_hi:[1,0,0] neg_lo:[1,0,0] neg_hi:[1,0,0]
	v_pk_add_f32 v[158:159], v[158:159], 1.0 op_sel_hi:[1,0]
	v_pk_mul_f32 v[156:157], v[154:155], v[156:157]
	v_rcp_f32_e32 v158, v158
	v_exp_f32_e32 v156, v156
	v_exp_f32_e32 v157, v157
	v_rcp_f32_e32 v159, v159
	v_pk_mul_f32 v[116:117], v[116:117], v[154:155]
	v_pk_add_f32 v[156:157], v[156:157], 1.0 op_sel_hi:[1,0]
	s_nop 0
	v_rcp_f32_e32 v156, v156
	v_rcp_f32_e32 v157, v157
	v_pk_mul_f32 v[114:115], v[114:115], v[158:159]
	v_pk_mul_f32 v[116:117], v[116:117], v[156:157]
	v_cvt_pk_bf16_f32 v120, v114, v115
	v_mad_i64_i32 v[114:115], s[4:5], v12, s67, v[234:235]
	v_or_b32_e32 v12, 32, v166
	v_lshl_add_u64 v[210:211], v[114:115], 0, v[230:231]
	v_mad_i64_i32 v[114:115], s[4:5], v12, s67, v[232:233]
	v_lshl_add_u64 v[204:205], v[114:115], 0, v[230:231]
	v_add_co_u32_e32 v206, vcc, s53, v204
	v_cvt_pk_bf16_f32 v121, v116, v117
	s_nop 0
	v_addc_co_u32_e32 v207, vcc, -1, v205, vcc
	global_store_dwordx4 v[210:211], v[118:121], off
	v_add_co_u32_e32 v200, vcc, s52, v204
	v_addc_co_u32_e32 v201, vcc, 0, v205, vcc
	s_waitcnt vmcnt(3)
	v_lshlrev_b32_e32 v158, 16, v172
	v_and_b32_e32 v159, 0xffff0000, v172
	v_lshlrev_b32_e32 v114, 16, v173
	v_and_b32_e32 v115, 0xffff0000, v173
	s_waitcnt vmcnt(2)
	v_lshlrev_b32_e32 v160, 16, v190
	v_and_b32_e32 v161, 0xffff0000, v190
	v_lshlrev_b32_e32 v118, 16, v191
	v_and_b32_e32 v119, 0xffff0000, v191
	v_pk_fma_f32 v[158:159], v[138:139], v[158:159], v[150:151]
	v_pk_fma_f32 v[114:115], v[140:141], v[114:115], v[152:153]
	s_waitcnt vmcnt(1)
; __device__ __forceinline__ float bflo(unsigned u) { return __uint_as_float(u << 16); }
;     __device__ __forceinline__ void operator()(const f32x4 (&acc)[2][2][4][2], const Unit& u, int wr, int wc, int fr, int fq) const {
;     ...
;                     const int row = u.pm * BM + ai * HALF + wr * 64 + m * 16 + fr;
;                     const int t = row & (SEQ - 1);
;                     const bf16_t* gp = G + (size_t)row * DFF + col;
;                     const bool hasm = t > 0, hasn = t < SEQ - 1;
;                     u32x4 gm = *(const u32x4*)(gp - (hasm ? DFF : 0));
;                     const u32x4 g0 = *(const u32x4*)gp;
;                     u32x4 gn = *(const u32x4*)(gp + (hasn ? DFF : 0));
;                     const unsigned mm = hasm ? 0xffffffffu : 0u, mn = hasn ? 0xffffffffu : 0u;
;                     gm.x &= mm; gm.y &= mm; gm.z &= mm; gm.w &= mm; gn.x &= mn; gn.y &= mn; gn.z &= mn; gn.w &= mn;
;                     unsigned ow[4];
; #pragma unroll
;                     for (int n = 0; n < 2; ++n) {
;                         const unsigned m0 = n ? gm.z : gm.x, m1 = n ? gm.w : gm.y, c0 = n ? g0.z : g0.x, c1 = n ? g0.w : g0.y, n0 = n ? gn.z : gn.x, n1 = n ? gn.w : gn.y;
;                         const f32x4 fm = {bflo(m0), bfhi(m0), bflo(m1), bfhi(m1)}, f0 = {bflo(c0), bfhi(c0), bflo(c1), bfhi(c1)}, fn = {bflo(n0), bfhi(n0), bflo(n1), bfhi(n1)};
;                         const f32x4 gc = bb[n] + fm * w0[n] + f0 * w1[n] + fn * w2[n];
;                         const f32x4 a = acc[ai][bj][m][n];
;                         constexpr float C1 = -2.0f * LOG2E * 0.7978845608028654f, C2 = C1 * 0.044715f;
;                         const f32x4 arg = gc * ((gc * gc) * C2 + C1);
;                         const f32x4 den = (f32x4){__builtin_amdgcn_exp2f(arg[0]), __builtin_amdgcn_exp2f(arg[1]), __builtin_amdgcn_exp2f(arg[2]), __builtin_amdgcn_exp2f(arg[3])} + 1.0f;
;                         const f32x4 rc = {__builtin_amdgcn_rcpf(den[0]), __builtin_amdgcn_rcpf(den[1]), __builtin_amdgcn_rcpf(den[2]), __builtin_amdgcn_rcpf(den[3])};
;                         const f32x4 o = (gc * a) * rc;
;                         ow[2 * n] = pk2(o[0], o[1]); ow[2 * n + 1] = pk2(o[2], o[3]);
;                     }
;                     *(u32x4*)(H + (size_t)row * DFF + col) = (u32x4){ow[0], ow[1], ow[2], ow[3]};
	v_lshlrev_b32_e32 v164, 16, v248
	v_and_b32_e32 v165, 0xffff0000, v248
	v_lshlrev_b32_e32 v154, 16, v249
	v_and_b32_e32 v155, 0xffff0000, v249
	v_pk_fma_f32 v[114:115], v[144:145], v[118:119], v[114:115]
	v_pk_fma_f32 v[118:119], v[142:143], v[160:161], v[158:159]
	v_pk_fma_f32 v[114:115], v[148:149], v[154:155], v[114:115]
	v_pk_fma_f32 v[118:119], v[146:147], v[164:165], v[118:119]
	v_pk_mul_f32 v[154:155], v[114:115], v[114:115]
	v_pk_mul_f32 v[158:159], v[118:119], v[118:119]
	v_pk_fma_f32 v[154:155], v[154:155], s[86:87], v[162:163] op_sel_hi:[1,0,0] neg_lo:[1,0,0] neg_hi:[1,0,0]
	v_pk_fma_f32 v[158:159], v[158:159], s[86:87], v[162:163] op_sel_hi:[1,0,0] neg_lo:[1,0,0] neg_hi:[1,0,0]
	v_pk_mul_f32 v[154:155], v[114:115], v[154:155]
	v_pk_mul_f32 v[158:159], v[118:119], v[158:159]
	v_exp_f32_e32 v154, v154
	v_exp_f32_e32 v158, v158
	v_exp_f32_e32 v159, v159
	v_exp_f32_e32 v155, v155
	v_pk_mul_f32 v[110:111], v[110:111], v[118:119]
	v_pk_mul_f32 v[112:113], v[112:113], v[114:115]
	v_pk_add_f32 v[158:159], v[158:159], 1.0 op_sel_hi:[1,0]
	v_pk_add_f32 v[154:155], v[154:155], 1.0 op_sel_hi:[1,0]
	v_rcp_f32_e32 v158, v158
	v_rcp_f32_e32 v159, v159
	v_rcp_f32_e32 v154, v154
	v_rcp_f32_e32 v155, v155
	v_lshlrev_b32_e32 v114, 16, v175
	v_pk_mul_f32 v[110:111], v[110:111], v[158:159]
	v_and_b32_e32 v115, 0xffff0000, v175
	v_pk_mul_f32 v[112:113], v[112:113], v[154:155]
	v_cvt_pk_bf16_f32 v110, v110, v111
	v_cvt_pk_bf16_f32 v111, v112, v113
	v_lshlrev_b32_e32 v112, 16, v174
	v_and_b32_e32 v113, 0xffff0000, v174
	v_lshlrev_b32_e32 v116, 16, v192
	v_and_b32_e32 v117, 0xffff0000, v192
	v_pk_fma_f32 v[112:113], v[122:123], v[112:113], v[134:135]
	v_lshlrev_b32_e32 v118, 16, v193
	v_and_b32_e32 v119, 0xffff0000, v193
	v_lshlrev_b32_e32 v120, 16, v250
	v_and_b32_e32 v121, 0xffff0000, v250
	v_pk_fma_f32 v[112:113], v[126:127], v[116:117], v[112:113]
	v_pk_fma_f32 v[114:115], v[124:125], v[114:115], v[136:137]
	v_pk_fma_f32 v[112:113], v[130:131], v[120:121], v[112:113]
	v_pk_fma_f32 v[114:115], v[128:129], v[118:119], v[114:115]
	v_pk_mul_f32 v[118:119], v[112:113], v[112:113]
	v_lshlrev_b32_e32 v154, 16, v251
	v_and_b32_e32 v155, 0xffff0000, v251
	s_mov_b32 s100, 268288
	s_mov_b32 s101, 0
	v_lshl_add_u64 v[174:175], v[246:247], 0, s[100:101]
	s_mov_b32 s100, 274432
	v_lshl_add_u64 v[172:173], v[246:247], 0, s[100:101]
	global_load_dwordx4 v[158:161], v[174:175], off offset:-3584
	global_load_dwordx4 v[168:171], v[174:175], off offset:2048
	global_load_dwordx4 v[172:175], v[172:173], off offset:1536
	v_pk_fma_f32 v[118:119], v[118:119], s[86:87], v[162:163] op_sel_hi:[1,0,0] neg_lo:[1,0,0] neg_hi:[1,0,0]
	v_pk_fma_f32 v[114:115], v[132:133], v[154:155], v[114:115]
	v_pk_mul_f32 v[118:119], v[112:113], v[118:119]
	v_pk_mul_f32 v[116:117], v[114:115], v[114:115]
	v_exp_f32_e32 v118, v118
	v_exp_f32_e32 v119, v119
	v_pk_fma_f32 v[116:117], v[116:117], s[86:87], v[162:163] op_sel_hi:[1,0,0] neg_lo:[1,0,0] neg_hi:[1,0,0]
	v_pk_mul_f32 v[106:107], v[106:107], v[112:113]
	v_pk_mul_f32 v[116:117], v[114:115], v[116:117]
	v_pk_add_f32 v[118:119], v[118:119], 1.0 op_sel_hi:[1,0]
	v_exp_f32_e32 v116, v116
	v_exp_f32_e32 v117, v117
	v_rcp_f32_e32 v118, v118
	v_rcp_f32_e32 v119, v119
	v_or_b32_e32 v154, 48, v166
	v_pk_add_f32 v[116:117], v[116:117], 1.0 op_sel_hi:[1,0]
	v_pk_mul_f32 v[108:109], v[108:109], v[114:115]
	v_rcp_f32_e32 v116, v116
	v_rcp_f32_e32 v117, v117
	v_pk_mul_f32 v[106:107], v[106:107], v[118:119]
	v_pk_mul_f32 v[108:109], v[108:109], v[116:117]
	v_cvt_pk_bf16_f32 v112, v106, v107
	v_mad_i64_i32 v[106:107], s[4:5], v12, s67, v[234:235]
	v_lshl_add_u64 v[202:203], v[106:107], 0, v[230:231]
	v_bitop3_b32 v12, v166, s51, 48 bitop3:0xc8
	v_mad_i64_i32 v[106:107], s[4:5], v154, s67, v[232:233]
	v_lshl_add_u64 v[196:197], v[106:107], 0, v[230:231]
	v_cmp_eq_u32_e64 s[6:7], s51, v12
	v_cvt_pk_bf16_f32 v113, v108, v109
	v_add_co_u32_e32 v198, vcc, s53, v196
	v_cndmask_b32_e64 v12, v167, 0, s[6:7]
	global_store_dwordx4 v[202:203], v[110:113], off
	v_addc_co_u32_e32 v199, vcc, -1, v197, vcc
	v_lshl_add_u64 v[194:195], v[196:197], 0, v[12:13]
	s_waitcnt vmcnt(1)
	v_cndmask_b32_e64 v12, v172, 0, s[6:7]
	v_cndmask_b32_e64 v121, v173, 0, s[6:7]
	v_lshlrev_b32_e32 v114, 16, v158
	v_and_b32_e32 v115, 0xffff0000, v158
	v_lshlrev_b32_e32 v106, 16, v159
	v_and_b32_e32 v107, 0xffff0000, v159
	v_cndmask_b32_e64 v155, v174, 0, s[6:7]
	v_cndmask_b32_e64 v156, v175, 0, s[6:7]
	v_lshlrev_b32_e32 v116, 16, v168
	v_and_b32_e32 v117, 0xffff0000, v168
	v_lshlrev_b32_e32 v110, 16, v169
	v_and_b32_e32 v111, 0xffff0000, v169
	v_pk_fma_f32 v[114:115], v[138:139], v[114:115], v[150:151]
	v_pk_fma_f32 v[106:107], v[140:141], v[106:107], v[152:153]
	v_lshlrev_b32_e32 v118, 16, v12
	v_and_b32_e32 v119, 0xffff0000, v12
	v_lshlrev_b32_e32 v120, 16, v121
	v_and_b32_e32 v121, 0xffff0000, v121
	v_pk_fma_f32 v[106:107], v[144:145], v[110:111], v[106:107]
	v_pk_fma_f32 v[110:111], v[142:143], v[116:117], v[114:115]
	v_pk_fma_f32 v[106:107], v[148:149], v[120:121], v[106:107]
	v_pk_fma_f32 v[110:111], v[146:147], v[118:119], v[110:111]
	v_pk_mul_f32 v[114:115], v[106:107], v[106:107]
	v_pk_mul_f32 v[116:117], v[110:111], v[110:111]
	v_pk_fma_f32 v[114:115], v[114:115], s[86:87], v[162:163] op_sel_hi:[1,0,0] neg_lo:[1,0,0] neg_hi:[1,0,0]
	v_pk_fma_f32 v[116:117], v[116:117], s[86:87], v[162:163] op_sel_hi:[1,0,0] neg_lo:[1,0,0] neg_hi:[1,0,0]
	v_pk_mul_f32 v[114:115], v[106:107], v[114:115]
	v_pk_mul_f32 v[116:117], v[110:111], v[116:117]
	v_exp_f32_e32 v114, v114
	v_exp_f32_e32 v116, v116
	v_exp_f32_e32 v117, v117
	v_exp_f32_e32 v115, v115
	v_pk_mul_f32 v[102:103], v[102:103], v[110:111]
; __device__ __forceinline__ float bflo(unsigned u) { return __uint_as_float(u << 16); }
;     __device__ __forceinline__ void operator()(const f32x4 (&acc)[2][2][4][2], const Unit& u, int wr, int wc, int fr, int fq) const {
;     ...
;                     const int row = u.pm * BM + ai * HALF + wr * 64 + m * 16 + fr;
;                     const int t = row & (SEQ - 1);
;                     const bf16_t* gp = G + (size_t)row * DFF + col;
;                     const bool hasm = t > 0, hasn = t < SEQ - 1;
;                     u32x4 gm = *(const u32x4*)(gp - (hasm ? DFF : 0));
;                     const u32x4 g0 = *(const u32x4*)gp;
;                     u32x4 gn = *(const u32x4*)(gp + (hasn ? DFF : 0));
;                     const unsigned mm = hasm ? 0xffffffffu : 0u, mn = hasn ? 0xffffffffu : 0u;
;                     gm.x &= mm; gm.y &= mm; gm.z &= mm; gm.w &= mm; gn.x &= mn; gn.y &= mn; gn.z &= mn; gn.w &= mn;
;                     unsigned ow[4];
; #pragma unroll
;                     for (int n = 0; n < 2; ++n) {
;                         const unsigned m0 = n ? gm.z : gm.x, m1 = n ? gm.w : gm.y, c0 = n ? g0.z : g0.x, c1 = n ? g0.w : g0.y, n0 = n ? gn.z : gn.x, n1 = n ? gn.w : gn.y;
;                         const f32x4 fm = {bflo(m0), bfhi(m0), bflo(m1), bfhi(m1)}, f0 = {bflo(c0), bfhi(c0), bflo(c1), bfhi(c1)}, fn = {bflo(n0), bfhi(n0), bflo(n1), bfhi(n1)};
;                         const f32x4 gc = bb[n] + fm * w0[n] + f0 * w1[n] + fn * w2[n];
;                         const f32x4 a = acc[ai][bj][m][n];
;                         constexpr float C1 = -2.0f * LOG2E * 0.7978845608028654f, C2 = C1 * 0.044715f;
;                         const f32x4 arg = gc * ((gc * gc) * C2 + C1);
;                         const f32x4 den = (f32x4){__builtin_amdgcn_exp2f(arg[0]), __builtin_amdgcn_exp2f(arg[1]), __builtin_amdgcn_exp2f(arg[2]), __builtin_amdgcn_exp2f(arg[3])} + 1.0f;
;                         const f32x4 rc = {__builtin_amdgcn_rcpf(den[0]), __builtin_amdgcn_rcpf(den[1]), __builtin_amdgcn_rcpf(den[2]), __builtin_amdgcn_rcpf(den[3])};
;                         const f32x4 o = (gc * a) * rc;
;                         ow[2 * n] = pk2(o[0], o[1]); ow[2 * n + 1] = pk2(o[2], o[3]);
;                     }
;                     *(u32x4*)(H + (size_t)row * DFF + col) = (u32x4){ow[0], ow[1], ow[2], ow[3]};
	v_pk_mul_f32 v[104:105], v[104:105], v[106:107]
	v_pk_add_f32 v[116:117], v[116:117], 1.0 op_sel_hi:[1,0]
	v_pk_add_f32 v[114:115], v[114:115], 1.0 op_sel_hi:[1,0]
	v_rcp_f32_e32 v116, v116
	v_rcp_f32_e32 v117, v117
	v_rcp_f32_e32 v114, v114
	v_rcp_f32_e32 v115, v115
	v_lshlrev_b32_e32 v106, 16, v161
	v_pk_mul_f32 v[102:103], v[102:103], v[116:117]
	v_and_b32_e32 v107, 0xffff0000, v161
	v_pk_mul_f32 v[104:105], v[104:105], v[114:115]
	v_cvt_pk_bf16_f32 v102, v102, v103
	v_cvt_pk_bf16_f32 v103, v104, v105
	v_lshlrev_b32_e32 v104, 16, v160
	v_and_b32_e32 v105, 0xffff0000, v160
	v_lshlrev_b32_e32 v108, 16, v170
	v_and_b32_e32 v109, 0xffff0000, v170
	v_pk_fma_f32 v[104:105], v[122:123], v[104:105], v[134:135]
	v_lshlrev_b32_e32 v110, 16, v171
	v_and_b32_e32 v111, 0xffff0000, v171
	s_mov_b32 s100, 718848
	s_mov_b32 s101, 0
	v_lshl_add_u64 v[174:175], v[246:247], 0, s[100:101]
	s_mov_b32 s100, 724992
	v_lshl_add_u64 v[172:173], v[246:247], 0, s[100:101]
	global_load_dwordx4 v[116:119], v[174:175], off offset:-3584
	global_load_dwordx4 v[168:171], v[174:175], off offset:2048
	global_load_dwordx4 v[172:175], v[172:173], off offset:1536
	v_lshlrev_b32_e32 v112, 16, v155
	v_and_b32_e32 v113, 0xffff0000, v155
	v_pk_fma_f32 v[106:107], v[124:125], v[106:107], v[136:137]
	v_pk_fma_f32 v[104:105], v[126:127], v[108:109], v[104:105]
	v_lshlrev_b32_e32 v114, 16, v156
	v_and_b32_e32 v115, 0xffff0000, v156
	v_pk_fma_f32 v[106:107], v[128:129], v[110:111], v[106:107]
	v_pk_fma_f32 v[104:105], v[130:131], v[112:113], v[104:105]
	v_pk_fma_f32 v[106:107], v[132:133], v[114:115], v[106:107]
	v_pk_mul_f32 v[110:111], v[104:105], v[104:105]
	v_pk_mul_f32 v[108:109], v[106:107], v[106:107]
	v_pk_fma_f32 v[110:111], v[110:111], s[86:87], v[162:163] op_sel_hi:[1,0,0] neg_lo:[1,0,0] neg_hi:[1,0,0]
	v_pk_fma_f32 v[108:109], v[108:109], s[86:87], v[162:163] op_sel_hi:[1,0,0] neg_lo:[1,0,0] neg_hi:[1,0,0]
	v_pk_mul_f32 v[110:111], v[104:105], v[110:111]
	v_pk_mul_f32 v[108:109], v[106:107], v[108:109]
	v_exp_f32_e32 v110, v110
	v_exp_f32_e32 v111, v111
	v_exp_f32_e32 v108, v108
	v_exp_f32_e32 v109, v109
	v_pk_mul_f32 v[98:99], v[98:99], v[104:105]
	v_pk_add_f32 v[110:111], v[110:111], 1.0 op_sel_hi:[1,0]
	v_pk_mul_f32 v[100:101], v[100:101], v[106:107]
	v_pk_add_f32 v[108:109], v[108:109], 1.0 op_sel_hi:[1,0]
	v_rcp_f32_e32 v110, v110
	v_rcp_f32_e32 v111, v111
	v_rcp_f32_e32 v108, v108
	v_rcp_f32_e32 v109, v109
	v_add_u32_e32 v12, 0x80, v166
	v_pk_mul_f32 v[98:99], v[98:99], v[110:111]
	v_pk_mul_f32 v[100:101], v[100:101], v[108:109]
	v_cvt_pk_bf16_f32 v104, v98, v99
	v_mad_i64_i32 v[98:99], s[4:5], v154, s67, v[234:235]
	v_cvt_pk_bf16_f32 v105, v100, v101
	v_lshl_add_u64 v[160:161], v[98:99], 0, v[230:231]
	v_and_b32_e32 v100, 0xfcf, v12
	v_mad_i64_i32 v[98:99], s[4:5], v12, s67, v[232:233]
	v_cmp_eq_u32_e64 s[4:5], 0, v100
	v_lshl_add_u64 v[164:165], v[98:99], 0, v[230:231]
	global_store_dwordx4 v[160:161], v[102:105], off
	v_cndmask_b32_e64 v99, -1, 0, s[4:5]
	v_cndmask_b32_e64 v98, v227, 0, s[4:5]
	v_lshl_add_u64 v[190:191], v[164:165], 0, v[98:99]
	v_add_co_u32_e32 v192, vcc, s52, v164
	s_waitcnt vmcnt(3)
	v_cndmask_b32_e64 v110, v116, 0, s[4:5]
	v_addc_co_u32_e32 v193, vcc, 0, v165, vcc
	v_cndmask_b32_e64 v111, v117, 0, s[4:5]
	v_cndmask_b32_e64 v114, v118, 0, s[4:5]
	v_cndmask_b32_e64 v115, v119, 0, s[4:5]
	v_lshlrev_b32_e32 v98, 16, v110
	v_and_b32_e32 v99, 0xffff0000, v110
	v_lshlrev_b32_e32 v100, 16, v111
	v_and_b32_e32 v101, 0xffff0000, v111
	s_waitcnt vmcnt(2)
	v_lshlrev_b32_e32 v110, 16, v168
	v_and_b32_e32 v111, 0xffff0000, v168
	v_lshlrev_b32_e32 v102, 16, v169
	v_and_b32_e32 v103, 0xffff0000, v169
	v_pk_fma_f32 v[98:99], v[138:139], v[98:99], v[150:151]
	v_pk_fma_f32 v[100:101], v[140:141], v[100:101], v[152:153]
	v_pk_fma_f32 v[98:99], v[142:143], v[110:111], v[98:99]
	v_pk_fma_f32 v[100:101], v[144:145], v[102:103], v[100:101]
	s_waitcnt vmcnt(1)
	v_lshlrev_b32_e32 v112, 16, v172
	v_and_b32_e32 v113, 0xffff0000, v172
	v_lshlrev_b32_e32 v106, 16, v173
	v_and_b32_e32 v107, 0xffff0000, v173
	v_pk_fma_f32 v[98:99], v[146:147], v[112:113], v[98:99]
	v_pk_fma_f32 v[100:101], v[148:149], v[106:107], v[100:101]
	v_pk_mul_f32 v[106:107], v[98:99], v[98:99]
	v_pk_mul_f32 v[102:103], v[100:101], v[100:101]
	v_pk_fma_f32 v[106:107], v[106:107], s[86:87], v[162:163] op_sel_hi:[1,0,0] neg_lo:[1,0,0] neg_hi:[1,0,0]
	v_pk_fma_f32 v[102:103], v[102:103], s[86:87], v[162:163] op_sel_hi:[1,0,0] neg_lo:[1,0,0] neg_hi:[1,0,0]
	v_pk_mul_f32 v[106:107], v[98:99], v[106:107]
	v_pk_mul_f32 v[102:103], v[100:101], v[102:103]
	v_exp_f32_e32 v106, v106
	v_exp_f32_e32 v107, v107
	v_exp_f32_e32 v102, v102
	v_exp_f32_e32 v103, v103
	v_pk_mul_f32 v[70:71], v[70:71], v[98:99]
	v_pk_add_f32 v[106:107], v[106:107], 1.0 op_sel_hi:[1,0]
	v_pk_mul_f32 v[72:73], v[72:73], v[100:101]
	v_pk_add_f32 v[102:103], v[102:103], 1.0 op_sel_hi:[1,0]
	v_rcp_f32_e32 v106, v106
	v_rcp_f32_e32 v107, v107
	v_rcp_f32_e32 v102, v102
	v_rcp_f32_e32 v103, v103
	v_lshlrev_b32_e32 v100, 16, v170
	v_pk_mul_f32 v[70:71], v[70:71], v[106:107]
	v_and_b32_e32 v101, 0xffff0000, v170
	v_pk_mul_f32 v[72:73], v[72:73], v[102:103]
	v_cvt_pk_bf16_f32 v70, v70, v71
	v_cvt_pk_bf16_f32 v71, v72, v73
	v_lshlrev_b32_e32 v72, 16, v114
	v_and_b32_e32 v73, 0xffff0000, v114
	v_pk_fma_f32 v[72:73], v[122:123], v[72:73], v[134:135]
	v_lshlrev_b32_e32 v98, 16, v115
	v_and_b32_e32 v99, 0xffff0000, v115
	v_lshlrev_b32_e32 v102, 16, v171
	v_and_b32_e32 v103, 0xffff0000, v171
	v_lshlrev_b32_e32 v104, 16, v174
	v_and_b32_e32 v105, 0xffff0000, v174
	v_pk_fma_f32 v[72:73], v[126:127], v[100:101], v[72:73]
	v_pk_fma_f32 v[98:99], v[124:125], v[98:99], v[136:137]
; __device__ __forceinline__ float bflo(unsigned u) { return __uint_as_float(u << 16); }
;     __device__ __forceinline__ void operator()(const f32x4 (&acc)[2][2][4][2], const Unit& u, int wr, int wc, int fr, int fq) const {
;     ...
;                     const int row = u.pm * BM + ai * HALF + wr * 64 + m * 16 + fr;
;                     const int t = row & (SEQ - 1);
;                     const bf16_t* gp = G + (size_t)row * DFF + col;
;                     const bool hasm = t > 0, hasn = t < SEQ - 1;
;                     u32x4 gm = *(const u32x4*)(gp - (hasm ? DFF : 0));
;                     const u32x4 g0 = *(const u32x4*)gp;
;                     u32x4 gn = *(const u32x4*)(gp + (hasn ? DFF : 0));
;                     const unsigned mm = hasm ? 0xffffffffu : 0u, mn = hasn ? 0xffffffffu : 0u;
;                     gm.x &= mm; gm.y &= mm; gm.z &= mm; gm.w &= mm; gn.x &= mn; gn.y &= mn; gn.z &= mn; gn.w &= mn;
;                     unsigned ow[4];
; #pragma unroll
;                     for (int n = 0; n < 2; ++n) {
;                         const unsigned m0 = n ? gm.z : gm.x, m1 = n ? gm.w : gm.y, c0 = n ? g0.z : g0.x, c1 = n ? g0.w : g0.y, n0 = n ? gn.z : gn.x, n1 = n ? gn.w : gn.y;
;                         const f32x4 fm = {bflo(m0), bfhi(m0), bflo(m1), bfhi(m1)}, f0 = {bflo(c0), bfhi(c0), bflo(c1), bfhi(c1)}, fn = {bflo(n0), bfhi(n0), bflo(n1), bfhi(n1)};
;                         const f32x4 gc = bb[n] + fm * w0[n] + f0 * w1[n] + fn * w2[n];
;                         const f32x4 a = acc[ai][bj][m][n];
;                         constexpr float C1 = -2.0f * LOG2E * 0.7978845608028654f, C2 = C1 * 0.044715f;
;                         const f32x4 arg = gc * ((gc * gc) * C2 + C1);
;                         const f32x4 den = (f32x4){__builtin_amdgcn_exp2f(arg[0]), __builtin_amdgcn_exp2f(arg[1]), __builtin_amdgcn_exp2f(arg[2]), __builtin_amdgcn_exp2f(arg[3])} + 1.0f;
;                         const f32x4 rc = {__builtin_amdgcn_rcpf(den[0]), __builtin_amdgcn_rcpf(den[1]), __builtin_amdgcn_rcpf(den[2]), __builtin_amdgcn_rcpf(den[3])};
;                         const f32x4 o = (gc * a) * rc;
;                         ow[2 * n] = pk2(o[0], o[1]); ow[2 * n + 1] = pk2(o[2], o[3]);
;                     }
;                     *(u32x4*)(H + (size_t)row * DFF + col) = (u32x4){ow[0], ow[1], ow[2], ow[3]};
	v_pk_fma_f32 v[72:73], v[130:131], v[104:105], v[72:73]
	v_pk_fma_f32 v[98:99], v[128:129], v[102:103], v[98:99]
	v_pk_mul_f32 v[102:103], v[72:73], v[72:73]
	v_lshlrev_b32_e32 v106, 16, v175
	v_pk_fma_f32 v[102:103], v[102:103], s[86:87], v[162:163] op_sel_hi:[1,0,0] neg_lo:[1,0,0] neg_hi:[1,0,0]
	v_and_b32_e32 v107, 0xffff0000, v175
	s_mov_b32 s100, 808960
	s_mov_b32 s101, 0
	v_lshl_add_u64 v[170:171], v[246:247], 0, s[100:101]
	s_mov_b32 s100, 815104
	v_lshl_add_u64 v[168:169], v[246:247], 0, s[100:101]
	global_load_dwordx4 v[110:113], v[170:171], off offset:-3584
	global_load_dwordx4 v[114:117], v[170:171], off offset:2048
	global_load_dwordx4 v[168:171], v[168:169], off offset:1536
	v_pk_mul_f32 v[102:103], v[72:73], v[102:103]
	v_pk_fma_f32 v[98:99], v[132:133], v[106:107], v[98:99]
	v_exp_f32_e32 v102, v102
	v_exp_f32_e32 v103, v103
	v_pk_mul_f32 v[100:101], v[98:99], v[98:99]
	v_pk_mul_f32 v[66:67], v[66:67], v[72:73]
	v_pk_fma_f32 v[100:101], v[100:101], s[86:87], v[162:163] op_sel_hi:[1,0,0] neg_lo:[1,0,0] neg_hi:[1,0,0]
	v_pk_add_f32 v[102:103], v[102:103], 1.0 op_sel_hi:[1,0]
	v_pk_mul_f32 v[100:101], v[98:99], v[100:101]
	v_rcp_f32_e32 v102, v102
	v_exp_f32_e32 v100, v100
	v_exp_f32_e32 v101, v101
	v_rcp_f32_e32 v103, v103
	v_pk_mul_f32 v[68:69], v[68:69], v[98:99]
	v_pk_add_f32 v[100:101], v[100:101], 1.0 op_sel_hi:[1,0]
	s_nop 0
	v_rcp_f32_e32 v100, v100
	v_rcp_f32_e32 v101, v101
	v_pk_mul_f32 v[66:67], v[66:67], v[102:103]
	v_pk_mul_f32 v[68:69], v[68:69], v[100:101]
	v_cvt_pk_bf16_f32 v72, v66, v67
	v_mad_i64_i32 v[66:67], s[10:11], v12, s67, v[234:235]
	v_add_u32_e32 v12, 0x90, v166
	v_lshl_add_u64 v[120:121], v[66:67], 0, v[230:231]
	v_mad_i64_i32 v[66:67], s[10:11], v12, s67, v[232:233]
	v_lshl_add_u64 v[154:155], v[66:67], 0, v[230:231]
	v_add_co_u32_e32 v156, vcc, s53, v154
	v_cvt_pk_bf16_f32 v73, v68, v69
	s_nop 0
	v_addc_co_u32_e32 v157, vcc, -1, v155, vcc
	global_store_dwordx4 v[120:121], v[70:73], off
	v_add_co_u32_e32 v158, vcc, s52, v154
	v_addc_co_u32_e32 v159, vcc, 0, v155, vcc
	s_waitcnt vmcnt(3)
	v_lshlrev_b32_e32 v102, 16, v110
	v_and_b32_e32 v103, 0xffff0000, v110
	v_lshlrev_b32_e32 v66, 16, v111
	v_and_b32_e32 v67, 0xffff0000, v111
	s_waitcnt vmcnt(2)
	v_lshlrev_b32_e32 v104, 16, v114
	v_and_b32_e32 v105, 0xffff0000, v114
	v_lshlrev_b32_e32 v70, 16, v115
	v_and_b32_e32 v71, 0xffff0000, v115
	v_pk_fma_f32 v[102:103], v[138:139], v[102:103], v[150:151]
	v_pk_fma_f32 v[66:67], v[140:141], v[66:67], v[152:153]
	s_waitcnt vmcnt(1)
	v_lshlrev_b32_e32 v106, 16, v168
	v_and_b32_e32 v107, 0xffff0000, v168
	v_lshlrev_b32_e32 v98, 16, v169
	v_and_b32_e32 v99, 0xffff0000, v169
	v_pk_fma_f32 v[66:67], v[144:145], v[70:71], v[66:67]
	v_pk_fma_f32 v[70:71], v[142:143], v[104:105], v[102:103]
	v_pk_fma_f32 v[66:67], v[148:149], v[98:99], v[66:67]
	v_pk_fma_f32 v[70:71], v[146:147], v[106:107], v[70:71]
	v_pk_mul_f32 v[98:99], v[66:67], v[66:67]
	s_mov_b32 s100, 899072
	s_mov_b32 s101, 0
	v_lshl_add_u64 v[250:251], v[246:247], 0, s[100:101]
	s_mov_b32 s100, 905216
	v_lshl_add_u64 v[248:249], v[246:247], 0, s[100:101]
	global_load_dwordx4 v[104:107], v[250:251], off offset:-3584
	global_load_dwordx4 v[172:175], v[250:251], off offset:2048
	global_load_dwordx4 v[248:251], v[248:249], off offset:1536
	v_pk_mul_f32 v[102:103], v[70:71], v[70:71]
	v_pk_fma_f32 v[98:99], v[98:99], s[86:87], v[162:163] op_sel_hi:[1,0,0] neg_lo:[1,0,0] neg_hi:[1,0,0]
	v_pk_fma_f32 v[102:103], v[102:103], s[86:87], v[162:163] op_sel_hi:[1,0,0] neg_lo:[1,0,0] neg_hi:[1,0,0]
	v_pk_mul_f32 v[98:99], v[66:67], v[98:99]
	v_pk_mul_f32 v[102:103], v[70:71], v[102:103]
	v_exp_f32_e32 v98, v98
	v_exp_f32_e32 v102, v102
	v_exp_f32_e32 v103, v103
	v_exp_f32_e32 v99, v99
	v_pk_mul_f32 v[62:63], v[62:63], v[70:71]
	v_pk_mul_f32 v[64:65], v[64:65], v[66:67]
	v_pk_add_f32 v[102:103], v[102:103], 1.0 op_sel_hi:[1,0]
	v_pk_add_f32 v[98:99], v[98:99], 1.0 op_sel_hi:[1,0]
	v_rcp_f32_e32 v102, v102
	v_rcp_f32_e32 v103, v103
	v_rcp_f32_e32 v98, v98
	v_rcp_f32_e32 v99, v99
	v_lshlrev_b32_e32 v66, 16, v113
	v_pk_mul_f32 v[62:63], v[62:63], v[102:103]
	v_and_b32_e32 v67, 0xffff0000, v113
	v_pk_mul_f32 v[64:65], v[64:65], v[98:99]
	v_cvt_pk_bf16_f32 v62, v62, v63
	v_cvt_pk_bf16_f32 v63, v64, v65
	v_lshlrev_b32_e32 v64, 16, v112
	v_and_b32_e32 v65, 0xffff0000, v112
	v_lshlrev_b32_e32 v68, 16, v116
	v_and_b32_e32 v69, 0xffff0000, v116
	v_pk_fma_f32 v[64:65], v[122:123], v[64:65], v[134:135]
	v_lshlrev_b32_e32 v70, 16, v117
	v_and_b32_e32 v71, 0xffff0000, v117
	v_lshlrev_b32_e32 v72, 16, v170
	v_and_b32_e32 v73, 0xffff0000, v170
	v_pk_fma_f32 v[64:65], v[126:127], v[68:69], v[64:65]
	v_pk_fma_f32 v[66:67], v[124:125], v[66:67], v[136:137]
	v_pk_fma_f32 v[64:65], v[130:131], v[72:73], v[64:65]
	v_pk_fma_f32 v[66:67], v[128:129], v[70:71], v[66:67]
	v_pk_mul_f32 v[70:71], v[64:65], v[64:65]
	v_lshlrev_b32_e32 v98, 16, v171
	v_pk_fma_f32 v[70:71], v[70:71], s[86:87], v[162:163] op_sel_hi:[1,0,0] neg_lo:[1,0,0] neg_hi:[1,0,0]
	v_and_b32_e32 v99, 0xffff0000, v171
	v_pk_mul_f32 v[70:71], v[64:65], v[70:71]
	v_pk_fma_f32 v[66:67], v[132:133], v[98:99], v[66:67]
	v_exp_f32_e32 v70, v70
	v_exp_f32_e32 v71, v71
	v_pk_mul_f32 v[68:69], v[66:67], v[66:67]
	v_pk_mul_f32 v[58:59], v[58:59], v[64:65]
	v_pk_fma_f32 v[68:69], v[68:69], s[86:87], v[162:163] op_sel_hi:[1,0,0] neg_lo:[1,0,0] neg_hi:[1,0,0]
	v_pk_add_f32 v[70:71], v[70:71], 1.0 op_sel_hi:[1,0]
	v_pk_mul_f32 v[68:69], v[66:67], v[68:69]
	v_rcp_f32_e32 v70, v70
	v_exp_f32_e32 v68, v68
	v_exp_f32_e32 v69, v69
	v_rcp_f32_e32 v71, v71
	v_pk_mul_f32 v[60:61], v[60:61], v[66:67]
	v_pk_add_f32 v[68:69], v[68:69], 1.0 op_sel_hi:[1,0]
	s_nop 0
	v_rcp_f32_e32 v68, v68
	v_rcp_f32_e32 v69, v69
	v_pk_mul_f32 v[58:59], v[58:59], v[70:71]
	v_pk_mul_f32 v[60:61], v[60:61], v[68:69]
	v_cvt_pk_bf16_f32 v64, v58, v59
	v_mad_i64_i32 v[58:59], s[10:11], v12, s67, v[234:235]
	v_add_u32_e32 v12, 0xa0, v166
	v_lshl_add_u64 v[112:113], v[58:59], 0, v[230:231]
	v_mad_i64_i32 v[58:59], s[10:11], v12, s67, v[232:233]
	v_lshl_add_u64 v[114:115], v[58:59], 0, v[230:231]
	v_add_co_u32_e32 v116, vcc, s53, v114
	v_cvt_pk_bf16_f32 v65, v60, v61
	s_nop 0
	v_addc_co_u32_e32 v117, vcc, -1, v115, vcc
	global_store_dwordx4 v[112:113], v[62:65], off
	v_add_co_u32_e32 v118, vcc, s52, v114
	v_addc_co_u32_e32 v119, vcc, 0, v115, vcc
	s_waitcnt vmcnt(3)
; __device__ __forceinline__ float bflo(unsigned u) { return __uint_as_float(u << 16); }
;     __device__ __forceinline__ void operator()(const f32x4 (&acc)[2][2][4][2], const Unit& u, int wr, int wc, int fr, int fq) const {
;     ...
;                     const int row = u.pm * BM + ai * HALF + wr * 64 + m * 16 + fr;
;                     const int t = row & (SEQ - 1);
;                     const bf16_t* gp = G + (size_t)row * DFF + col;
;                     const bool hasm = t > 0, hasn = t < SEQ - 1;
;                     u32x4 gm = *(const u32x4*)(gp - (hasm ? DFF : 0));
;                     const u32x4 g0 = *(const u32x4*)gp;
;                     u32x4 gn = *(const u32x4*)(gp + (hasn ? DFF : 0));
;                     const unsigned mm = hasm ? 0xffffffffu : 0u, mn = hasn ? 0xffffffffu : 0u;
;                     gm.x &= mm; gm.y &= mm; gm.z &= mm; gm.w &= mm; gn.x &= mn; gn.y &= mn; gn.z &= mn; gn.w &= mn;
;                     unsigned ow[4];
; #pragma unroll
;                     for (int n = 0; n < 2; ++n) {
;                         const unsigned m0 = n ? gm.z : gm.x, m1 = n ? gm.w : gm.y, c0 = n ? g0.z : g0.x, c1 = n ? g0.w : g0.y, n0 = n ? gn.z : gn.x, n1 = n ? gn.w : gn.y;
;                         const f32x4 fm = {bflo(m0), bfhi(m0), bflo(m1), bfhi(m1)}, f0 = {bflo(c0), bfhi(c0), bflo(c1), bfhi(c1)}, fn = {bflo(n0), bfhi(n0), bflo(n1), bfhi(n1)};
;                         const f32x4 gc = bb[n] + fm * w0[n] + f0 * w1[n] + fn * w2[n];
;                         const f32x4 a = acc[ai][bj][m][n];
;                         constexpr float C1 = -2.0f * LOG2E * 0.7978845608028654f, C2 = C1 * 0.044715f;
;                         const f32x4 arg = gc * ((gc * gc) * C2 + C1);
;                         const f32x4 den = (f32x4){__builtin_amdgcn_exp2f(arg[0]), __builtin_amdgcn_exp2f(arg[1]), __builtin_amdgcn_exp2f(arg[2]), __builtin_amdgcn_exp2f(arg[3])} + 1.0f;
;                         const f32x4 rc = {__builtin_amdgcn_rcpf(den[0]), __builtin_amdgcn_rcpf(den[1]), __builtin_amdgcn_rcpf(den[2]), __builtin_amdgcn_rcpf(den[3])};
;                         const f32x4 o = (gc * a) * rc;
;                         ow[2 * n] = pk2(o[0], o[1]); ow[2 * n + 1] = pk2(o[2], o[3]);
;                     }
;                     *(u32x4*)(H + (size_t)row * DFF + col) = (u32x4){ow[0], ow[1], ow[2], ow[3]};
	v_lshlrev_b32_e32 v70, 16, v104
	v_and_b32_e32 v71, 0xffff0000, v104
	v_lshlrev_b32_e32 v58, 16, v105
	v_and_b32_e32 v59, 0xffff0000, v105
	s_waitcnt vmcnt(2)
	v_lshlrev_b32_e32 v72, 16, v172
	v_and_b32_e32 v73, 0xffff0000, v172
	v_lshlrev_b32_e32 v62, 16, v173
	v_and_b32_e32 v63, 0xffff0000, v173
	v_pk_fma_f32 v[70:71], v[138:139], v[70:71], v[150:151]
	v_pk_fma_f32 v[58:59], v[140:141], v[58:59], v[152:153]
	s_waitcnt vmcnt(1)
	v_lshlrev_b32_e32 v98, 16, v248
	v_and_b32_e32 v99, 0xffff0000, v248
	v_lshlrev_b32_e32 v66, 16, v249
	v_and_b32_e32 v67, 0xffff0000, v249
	v_pk_fma_f32 v[58:59], v[144:145], v[62:63], v[58:59]
	v_pk_fma_f32 v[62:63], v[142:143], v[72:73], v[70:71]
	v_pk_fma_f32 v[58:59], v[148:149], v[66:67], v[58:59]
	v_pk_fma_f32 v[62:63], v[146:147], v[98:99], v[62:63]
	v_pk_mul_f32 v[66:67], v[58:59], v[58:59]
	v_pk_mul_f32 v[70:71], v[62:63], v[62:63]
	v_pk_fma_f32 v[66:67], v[66:67], s[86:87], v[162:163] op_sel_hi:[1,0,0] neg_lo:[1,0,0] neg_hi:[1,0,0]
	v_pk_fma_f32 v[70:71], v[70:71], s[86:87], v[162:163] op_sel_hi:[1,0,0] neg_lo:[1,0,0] neg_hi:[1,0,0]
	v_pk_mul_f32 v[66:67], v[58:59], v[66:67]
	v_pk_mul_f32 v[70:71], v[62:63], v[70:71]
	v_exp_f32_e32 v66, v66
	v_exp_f32_e32 v70, v70
	v_exp_f32_e32 v71, v71
	v_exp_f32_e32 v67, v67
	v_pk_mul_f32 v[54:55], v[54:55], v[62:63]
	v_pk_mul_f32 v[56:57], v[56:57], v[58:59]
	v_pk_add_f32 v[70:71], v[70:71], 1.0 op_sel_hi:[1,0]
	v_pk_add_f32 v[66:67], v[66:67], 1.0 op_sel_hi:[1,0]
	v_rcp_f32_e32 v70, v70
	v_rcp_f32_e32 v71, v71
	v_rcp_f32_e32 v66, v66
	v_rcp_f32_e32 v67, v67
	v_lshlrev_b32_e32 v58, 16, v107
	v_pk_mul_f32 v[54:55], v[54:55], v[70:71]
	v_and_b32_e32 v59, 0xffff0000, v107
	s_mov_b32 s100, 989184
	s_mov_b32 s101, 0
	v_lshl_add_u64 v[170:171], v[246:247], 0, s[100:101]
	s_mov_b32 s100, 995328
	v_lshl_add_u64 v[168:169], v[246:247], 0, s[100:101]
	global_load_dwordx4 v[70:73], v[170:171], off offset:-3584
	global_load_dwordx4 v[98:101], v[170:171], off offset:2048
	global_load_dwordx4 v[168:171], v[168:169], off offset:1536
	v_pk_mul_f32 v[56:57], v[56:57], v[66:67]
	v_cvt_pk_bf16_f32 v54, v54, v55
	v_cvt_pk_bf16_f32 v55, v56, v57
	v_lshlrev_b32_e32 v56, 16, v106
	v_and_b32_e32 v57, 0xffff0000, v106
	v_lshlrev_b32_e32 v60, 16, v174
	v_and_b32_e32 v61, 0xffff0000, v174
	v_pk_fma_f32 v[56:57], v[122:123], v[56:57], v[134:135]
	v_lshlrev_b32_e32 v62, 16, v175
	v_and_b32_e32 v63, 0xffff0000, v175
	v_lshlrev_b32_e32 v64, 16, v250
	v_and_b32_e32 v65, 0xffff0000, v250
	v_pk_fma_f32 v[56:57], v[126:127], v[60:61], v[56:57]
	v_pk_fma_f32 v[58:59], v[124:125], v[58:59], v[136:137]
	v_pk_fma_f32 v[56:57], v[130:131], v[64:65], v[56:57]
	v_pk_fma_f32 v[58:59], v[128:129], v[62:63], v[58:59]
	v_pk_mul_f32 v[62:63], v[56:57], v[56:57]
	v_lshlrev_b32_e32 v66, 16, v251
	v_and_b32_e32 v67, 0xffff0000, v251
	v_pk_fma_f32 v[62:63], v[62:63], s[86:87], v[162:163] op_sel_hi:[1,0,0] neg_lo:[1,0,0] neg_hi:[1,0,0]
	v_pk_fma_f32 v[58:59], v[132:133], v[66:67], v[58:59]
	v_pk_mul_f32 v[62:63], v[56:57], v[62:63]
	v_pk_mul_f32 v[60:61], v[58:59], v[58:59]
	v_exp_f32_e32 v62, v62
	v_exp_f32_e32 v63, v63
	v_pk_fma_f32 v[60:61], v[60:61], s[86:87], v[162:163] op_sel_hi:[1,0,0] neg_lo:[1,0,0] neg_hi:[1,0,0]
	v_pk_mul_f32 v[50:51], v[50:51], v[56:57]
	v_pk_mul_f32 v[60:61], v[58:59], v[60:61]
	v_pk_add_f32 v[62:63], v[62:63], 1.0 op_sel_hi:[1,0]
	v_exp_f32_e32 v60, v60
	v_exp_f32_e32 v61, v61
	v_rcp_f32_e32 v62, v62
	v_rcp_f32_e32 v63, v63
	v_add_u32_e32 v66, 0xb0, v166
	v_pk_add_f32 v[60:61], v[60:61], 1.0 op_sel_hi:[1,0]
	v_pk_mul_f32 v[52:53], v[52:53], v[58:59]
	v_rcp_f32_e32 v60, v60
	v_rcp_f32_e32 v61, v61
	v_pk_mul_f32 v[50:51], v[50:51], v[62:63]
	v_pk_mul_f32 v[52:53], v[52:53], v[60:61]
	v_cvt_pk_bf16_f32 v56, v50, v51
	v_mad_i64_i32 v[50:51], s[10:11], v12, s67, v[234:235]
	v_lshl_add_u64 v[104:105], v[50:51], 0, v[230:231]
	v_and_b32_e32 v12, 0xfff, v66
	v_mad_i64_i32 v[50:51], s[10:11], v66, s67, v[232:233]
	v_lshl_add_u64 v[108:109], v[50:51], 0, v[230:231]
	v_cmp_eq_u32_e32 vcc, s51, v12
	v_cvt_pk_bf16_f32 v57, v52, v53
	v_add_co_u32_e64 v110, s[10:11], s53, v108
	v_cndmask_b32_e64 v12, v167, 0, vcc
	global_store_dwordx4 v[104:105], v[54:57], off
	v_addc_co_u32_e64 v111, s[10:11], -1, v109, s[10:11]
	v_lshl_add_u64 v[106:107], v[108:109], 0, v[12:13]
	s_waitcnt vmcnt(1)
;     __device__ __forceinline__ void operator()(const f32x4 (&acc)[2][2][4][2], const Unit& u, int wr, int wc, int fr, int fq) const {
;     ...
;             const int col = u.pn * BM + bj * HALF + wc * 32 + 8 * fq;
;             f32x4 w0[2], w1[2], w2[2], bb[2];
; #pragma unroll
;     ...
;                     const int row = u.pm * BM + ai * HALF + wr * 64 + m * 16 + fr;
;                     const int t = row & (SEQ - 1);
;                     const bf16_t* gp = G + (size_t)row * DFF + col;
;                     const bool hasm = t > 0, hasn = t < SEQ - 1;
;                     u32x4 gm = *(const u32x4*)(gp - (hasm ? DFF : 0));
;                     const u32x4 g0 = *(const u32x4*)gp;
;                     u32x4 gn = *(const u32x4*)(gp + (hasn ? DFF : 0));
;                     const unsigned mm = hasm ? 0xffffffffu : 0u, mn = hasn ? 0xffffffffu : 0u;
;                     gm.x &= mm; gm.y &= mm; gm.z &= mm; gm.w &= mm; gn.x &= mn; gn.y &= mn; gn.z &= mn; gn.w &= mn;
;                     unsigned ow[4];
; #pragma unroll
;                     for (int n = 0; n < 2; ++n) {
;                         const unsigned m0 = n ? gm.z : gm.x, m1 = n ? gm.w : gm.y, c0 = n ? g0.z : g0.x, c1 = n ? g0.w : g0.y, n0 = n ? gn.z : gn.x, n1 = n ? gn.w : gn.y;
;                         const f32x4 fm = {bflo(m0), bfhi(m0), bflo(m1), bfhi(m1)}, f0 = {bflo(c0), bfhi(c0), bflo(c1), bfhi(c1)}, fn = {bflo(n0), bfhi(n0), bflo(n1), bfhi(n1)};
;                         const f32x4 gc = bb[n] + fm * w0[n] + f0 * w1[n] + fn * w2[n];
;                         const f32x4 a = acc[ai][bj][m][n];
;                         constexpr float C1 = -2.0f * LOG2E * 0.7978845608028654f, C2 = C1 * 0.044715f;
;                         const f32x4 arg = gc * ((gc * gc) * C2 + C1);
;                         const f32x4 den = (f32x4){__builtin_amdgcn_exp2f(arg[0]), __builtin_amdgcn_exp2f(arg[1]), __builtin_amdgcn_exp2f(arg[2]), __builtin_amdgcn_exp2f(arg[3])} + 1.0f;
;                         const f32x4 rc = {__builtin_amdgcn_rcpf(den[0]), __builtin_amdgcn_rcpf(den[1]), __builtin_amdgcn_rcpf(den[2]), __builtin_amdgcn_rcpf(den[3])};
;                         const f32x4 o = (gc * a) * rc;
;                         ow[2 * n] = pk2(o[0], o[1]); ow[2 * n + 1] = pk2(o[2], o[3]);
;                     }
;                     *(u32x4*)(H + (size_t)row * DFF + col) = (u32x4){ow[0], ow[1], ow[2], ow[3]};
	v_cndmask_b32_e64 v12, v168, 0, vcc
	v_cndmask_b32_e64 v65, v169, 0, vcc
	v_lshlrev_b32_e32 v58, 16, v70
	v_and_b32_e32 v59, 0xffff0000, v70
	v_lshlrev_b32_e32 v50, 16, v71
	v_and_b32_e32 v51, 0xffff0000, v71
	v_cndmask_b32_e64 v67, v170, 0, vcc
	v_cndmask_b32_e64 v68, v171, 0, vcc
	v_lshlrev_b32_e32 v60, 16, v98
	v_and_b32_e32 v61, 0xffff0000, v98
	v_lshlrev_b32_e32 v54, 16, v99
	v_and_b32_e32 v55, 0xffff0000, v99
	v_pk_fma_f32 v[58:59], v[138:139], v[58:59], v[150:151]
	v_pk_fma_f32 v[50:51], v[140:141], v[50:51], v[152:153]
	v_lshlrev_b32_e32 v62, 16, v12
	v_and_b32_e32 v63, 0xffff0000, v12
	v_lshlrev_b32_e32 v64, 16, v65
	v_and_b32_e32 v65, 0xffff0000, v65
	v_pk_fma_f32 v[50:51], v[144:145], v[54:55], v[50:51]
	v_pk_fma_f32 v[54:55], v[142:143], v[60:61], v[58:59]
	v_pk_fma_f32 v[50:51], v[148:149], v[64:65], v[50:51]
	v_pk_fma_f32 v[54:55], v[146:147], v[62:63], v[54:55]
	v_pk_mul_f32 v[58:59], v[50:51], v[50:51]
	v_pk_mul_f32 v[60:61], v[54:55], v[54:55]
	v_pk_fma_f32 v[58:59], v[58:59], s[86:87], v[162:163] op_sel_hi:[1,0,0] neg_lo:[1,0,0] neg_hi:[1,0,0]
	v_pk_fma_f32 v[60:61], v[60:61], s[86:87], v[162:163] op_sel_hi:[1,0,0] neg_lo:[1,0,0] neg_hi:[1,0,0]
	v_pk_mul_f32 v[58:59], v[50:51], v[58:59]
	v_pk_mul_f32 v[60:61], v[54:55], v[60:61]
	v_exp_f32_e32 v58, v58
	v_exp_f32_e32 v60, v60
	v_exp_f32_e32 v61, v61
	v_exp_f32_e32 v59, v59
	v_pk_mul_f32 v[46:47], v[46:47], v[54:55]
	v_pk_mul_f32 v[48:49], v[48:49], v[50:51]
	v_pk_add_f32 v[60:61], v[60:61], 1.0 op_sel_hi:[1,0]
	v_pk_add_f32 v[58:59], v[58:59], 1.0 op_sel_hi:[1,0]
	v_rcp_f32_e32 v60, v60
	v_rcp_f32_e32 v61, v61
	v_rcp_f32_e32 v58, v58
	v_rcp_f32_e32 v59, v59
	v_lshlrev_b32_e32 v50, 16, v73
	v_pk_mul_f32 v[46:47], v[46:47], v[60:61]
	v_and_b32_e32 v51, 0xffff0000, v73
	v_pk_mul_f32 v[48:49], v[48:49], v[58:59]
	v_cvt_pk_bf16_f32 v46, v46, v47
	v_cvt_pk_bf16_f32 v47, v48, v49
	v_lshlrev_b32_e32 v48, 16, v72
	v_and_b32_e32 v49, 0xffff0000, v72
	v_lshlrev_b32_e32 v52, 16, v100
	v_and_b32_e32 v53, 0xffff0000, v100
	v_pk_fma_f32 v[48:49], v[122:123], v[48:49], v[134:135]
	v_lshlrev_b32_e32 v54, 16, v101
	v_and_b32_e32 v55, 0xffff0000, v101
	v_lshlrev_b32_e32 v56, 16, v67
	v_and_b32_e32 v57, 0xffff0000, v67
	v_pk_fma_f32 v[48:49], v[126:127], v[52:53], v[48:49]
	v_pk_fma_f32 v[50:51], v[124:125], v[50:51], v[136:137]
	v_pk_fma_f32 v[48:49], v[130:131], v[56:57], v[48:49]
	v_pk_fma_f32 v[50:51], v[128:129], v[54:55], v[50:51]
	v_pk_mul_f32 v[54:55], v[48:49], v[48:49]
	v_lshlrev_b32_e32 v58, 16, v68
	v_and_b32_e32 v59, 0xffff0000, v68
	v_pk_fma_f32 v[54:55], v[54:55], s[86:87], v[162:163] op_sel_hi:[1,0,0] neg_lo:[1,0,0] neg_hi:[1,0,0]
	v_pk_fma_f32 v[50:51], v[132:133], v[58:59], v[50:51]
	v_pk_mul_f32 v[54:55], v[48:49], v[54:55]
	v_pk_mul_f32 v[52:53], v[50:51], v[50:51]
	v_exp_f32_e32 v54, v54
	v_exp_f32_e32 v55, v55
	v_pk_fma_f32 v[52:53], v[52:53], s[86:87], v[162:163] op_sel_hi:[1,0,0] neg_lo:[1,0,0] neg_hi:[1,0,0]
	v_pk_mul_f32 v[42:43], v[42:43], v[48:49]
	v_pk_mul_f32 v[52:53], v[50:51], v[52:53]
	v_pk_add_f32 v[54:55], v[54:55], 1.0 op_sel_hi:[1,0]
	v_exp_f32_e32 v52, v52
	v_exp_f32_e32 v53, v53
	v_rcp_f32_e32 v54, v54
	v_rcp_f32_e32 v55, v55
	v_pk_mul_f32 v[44:45], v[44:45], v[50:51]
	v_pk_add_f32 v[52:53], v[52:53], 1.0 op_sel_hi:[1,0]
	v_pk_mul_f32 v[42:43], v[42:43], v[54:55]
	v_rcp_f32_e32 v52, v52
	v_rcp_f32_e32 v53, v53
	v_cvt_pk_bf16_f32 v48, v42, v43
	v_mad_i64_i32 v[42:43], s[10:11], v66, s67, v[234:235]
	v_lshl_add_u64 v[102:103], v[42:43], 0, v[230:231]
	v_or_b32_e32 v42, 0x80, v226
	v_pk_mul_f32 v[44:45], v[44:45], v[52:53]
	v_ashrrev_i32_e32 v43, 31, v42
	v_cvt_pk_bf16_f32 v49, v44, v45
	v_lshlrev_b64 v[42:43], 2, v[42:43]
	global_store_dwordx4 v[102:103], v[46:49], off
	v_lshl_add_u64 v[44:45], s[16:17], 0, v[42:43]
	v_lshl_add_u64 v[54:55], s[12:13], 0, v[42:43]
	global_load_dwordx4 v[50:53], v[224:225], off offset:528
	global_load_dwordx4 v[66:69], v[224:225], off offset:512
	global_load_dwordx4 v[46:49], v[44:45], off offset:16
	global_load_dwordx4 v[62:65], v[44:45], off
	s_nop 0
	global_load_dwordx4 v[42:45], v[54:55], off offset:16
	global_load_dwordx4 v[58:61], v[54:55], off
	s_nop 0
	global_load_dwordx4 v[54:57], v[222:223], off offset:528
	global_load_dwordx4 v[70:73], v[222:223], off offset:512
	global_load_dwordx4 v[98:101], v[228:229], off offset:256
	global_load_dwordx4 v[122:125], v[216:217], off offset:256
	global_load_dwordx4 v[126:129], v[218:219], off offset:1792
	s_waitcnt vmcnt(2)
	v_cndmask_b32_e64 v12, v98, 0, s[8:9]
	v_cndmask_b32_e64 v130, v99, 0, s[8:9]
	v_cndmask_b32_e64 v134, v100, 0, s[8:9]
	v_cndmask_b32_e64 v135, v101, 0, s[8:9]
	v_lshlrev_b32_e32 v98, 16, v12
	v_and_b32_e32 v99, 0xffff0000, v12
	v_lshlrev_b32_e32 v100, 16, v130
	v_and_b32_e32 v101, 0xffff0000, v130
	s_waitcnt vmcnt(1)
	v_lshlrev_b32_e32 v130, 16, v122
	v_and_b32_e32 v131, 0xffff0000, v122
	v_lshlrev_b32_e32 v122, 16, v123
	v_and_b32_e32 v123, 0xffff0000, v123
	v_pk_fma_f32 v[98:99], v[66:67], v[98:99], v[70:71]
	v_pk_fma_f32 v[100:101], v[68:69], v[100:101], v[72:73]
	s_waitcnt vmcnt(0)
; __device__ __forceinline__ float bflo(unsigned u) { return __uint_as_float(u << 16); }
;     __device__ __forceinline__ void operator()(const f32x4 (&acc)[2][2][4][2], const Unit& u, int wr, int wc, int fr, int fq) const {
;     ...
;                     const int row = u.pm * BM + ai * HALF + wr * 64 + m * 16 + fr;
;                     const int t = row & (SEQ - 1);
;                     const bf16_t* gp = G + (size_t)row * DFF + col;
;                     const bool hasm = t > 0, hasn = t < SEQ - 1;
;                     u32x4 gm = *(const u32x4*)(gp - (hasm ? DFF : 0));
;                     const u32x4 g0 = *(const u32x4*)gp;
;                     u32x4 gn = *(const u32x4*)(gp + (hasn ? DFF : 0));
;                     const unsigned mm = hasm ? 0xffffffffu : 0u, mn = hasn ? 0xffffffffu : 0u;
;                     gm.x &= mm; gm.y &= mm; gm.z &= mm; gm.w &= mm; gn.x &= mn; gn.y &= mn; gn.z &= mn; gn.w &= mn;
;                     unsigned ow[4];
; #pragma unroll
;                     for (int n = 0; n < 2; ++n) {
;                         const unsigned m0 = n ? gm.z : gm.x, m1 = n ? gm.w : gm.y, c0 = n ? g0.z : g0.x, c1 = n ? g0.w : g0.y, n0 = n ? gn.z : gn.x, n1 = n ? gn.w : gn.y;
;                         const f32x4 fm = {bflo(m0), bfhi(m0), bflo(m1), bfhi(m1)}, f0 = {bflo(c0), bfhi(c0), bflo(c1), bfhi(c1)}, fn = {bflo(n0), bfhi(n0), bflo(n1), bfhi(n1)};
;                         const f32x4 gc = bb[n] + fm * w0[n] + f0 * w1[n] + fn * w2[n];
;                         const f32x4 a = acc[ai][bj][m][n];
;                         constexpr float C1 = -2.0f * LOG2E * 0.7978845608028654f, C2 = C1 * 0.044715f;
;                         const f32x4 arg = gc * ((gc * gc) * C2 + C1);
;                         const f32x4 den = (f32x4){__builtin_amdgcn_exp2f(arg[0]), __builtin_amdgcn_exp2f(arg[1]), __builtin_amdgcn_exp2f(arg[2]), __builtin_amdgcn_exp2f(arg[3])} + 1.0f;
;                         const f32x4 rc = {__builtin_amdgcn_rcpf(den[0]), __builtin_amdgcn_rcpf(den[1]), __builtin_amdgcn_rcpf(den[2]), __builtin_amdgcn_rcpf(den[3])};
;                         const f32x4 o = (gc * a) * rc;
;                         ow[2 * n] = pk2(o[0], o[1]); ow[2 * n + 1] = pk2(o[2], o[3]);
;                     }
;                     *(u32x4*)(H + (size_t)row * DFF + col) = (u32x4){ow[0], ow[1], ow[2], ow[3]};
	s_mov_b32 s100, 88320
	s_mov_b32 s101, 0
	v_lshl_add_u64 v[250:251], v[246:247], 0, s[100:101]
	s_mov_b32 s100, 94464
	v_lshl_add_u64 v[248:249], v[246:247], 0, s[100:101]
	global_load_dwordx4 v[226:229], v[250:251], off offset:-3584
	global_load_dwordx4 v[230:233], v[250:251], off offset:2048
	global_load_dwordx4 v[248:251], v[248:249], off offset:1536
	v_lshlrev_b32_e32 v132, 16, v126
	v_and_b32_e32 v133, 0xffff0000, v126
	v_lshlrev_b32_e32 v126, 16, v127
	v_and_b32_e32 v127, 0xffff0000, v127
	v_pk_fma_f32 v[100:101], v[64:65], v[122:123], v[100:101]
	v_pk_fma_f32 v[98:99], v[62:63], v[130:131], v[98:99]
	v_pk_fma_f32 v[100:101], v[60:61], v[126:127], v[100:101]
	v_pk_fma_f32 v[98:99], v[58:59], v[132:133], v[98:99]
	v_pk_mul_f32 v[122:123], v[100:101], v[100:101]
	v_pk_mul_f32 v[126:127], v[98:99], v[98:99]
	v_pk_fma_f32 v[122:123], v[122:123], s[86:87], v[162:163] op_sel_hi:[1,0,0] neg_lo:[1,0,0] neg_hi:[1,0,0]
	v_pk_fma_f32 v[126:127], v[126:127], s[86:87], v[162:163] op_sel_hi:[1,0,0] neg_lo:[1,0,0] neg_hi:[1,0,0]
	v_pk_mul_f32 v[122:123], v[100:101], v[122:123]
	v_pk_mul_f32 v[126:127], v[98:99], v[126:127]
	v_exp_f32_e32 v122, v122
	v_exp_f32_e32 v126, v126
	v_exp_f32_e32 v127, v127
	v_exp_f32_e32 v123, v123
	v_pk_mul_f32 v[94:95], v[94:95], v[98:99]
	v_pk_mul_f32 v[96:97], v[96:97], v[100:101]
	v_pk_add_f32 v[126:127], v[126:127], 1.0 op_sel_hi:[1,0]
	v_pk_add_f32 v[122:123], v[122:123], 1.0 op_sel_hi:[1,0]
	v_rcp_f32_e32 v126, v126
	v_rcp_f32_e32 v127, v127
	v_rcp_f32_e32 v122, v122
	v_rcp_f32_e32 v123, v123
	v_lshlrev_b32_e32 v98, 16, v135
	v_pk_mul_f32 v[94:95], v[94:95], v[126:127]
	v_and_b32_e32 v99, 0xffff0000, v135
	v_pk_mul_f32 v[96:97], v[96:97], v[122:123]
	v_cvt_pk_bf16_f32 v94, v94, v95
	v_cvt_pk_bf16_f32 v95, v96, v97
	v_lshlrev_b32_e32 v96, 16, v134
	v_and_b32_e32 v97, 0xffff0000, v134
	v_lshlrev_b32_e32 v100, 16, v124
	v_and_b32_e32 v101, 0xffff0000, v124
	v_lshlrev_b32_e32 v122, 16, v125
	v_and_b32_e32 v123, 0xffff0000, v125
	v_pk_fma_f32 v[96:97], v[50:51], v[96:97], v[54:55]
	v_pk_fma_f32 v[98:99], v[52:53], v[98:99], v[56:57]
	v_lshlrev_b32_e32 v124, 16, v128
	v_and_b32_e32 v125, 0xffff0000, v128
	v_lshlrev_b32_e32 v126, 16, v129
	v_and_b32_e32 v127, 0xffff0000, v129
	v_pk_fma_f32 v[98:99], v[48:49], v[122:123], v[98:99]
	v_pk_fma_f32 v[96:97], v[46:47], v[100:101], v[96:97]
	v_pk_fma_f32 v[98:99], v[44:45], v[126:127], v[98:99]
	v_pk_fma_f32 v[96:97], v[42:43], v[124:125], v[96:97]
	v_pk_mul_f32 v[100:101], v[98:99], v[98:99]
	v_pk_mul_f32 v[122:123], v[96:97], v[96:97]
	v_pk_fma_f32 v[100:101], v[100:101], s[86:87], v[162:163] op_sel_hi:[1,0,0] neg_lo:[1,0,0] neg_hi:[1,0,0]
	v_pk_fma_f32 v[122:123], v[122:123], s[86:87], v[162:163] op_sel_hi:[1,0,0] neg_lo:[1,0,0] neg_hi:[1,0,0]
	v_pk_mul_f32 v[100:101], v[98:99], v[100:101]
	v_pk_mul_f32 v[122:123], v[96:97], v[122:123]
	v_exp_f32_e32 v100, v100
	v_exp_f32_e32 v122, v122
	v_exp_f32_e32 v123, v123
	v_exp_f32_e32 v101, v101
	v_pk_mul_f32 v[90:91], v[90:91], v[96:97]
	v_pk_mul_f32 v[92:93], v[92:93], v[98:99]
	v_pk_add_f32 v[122:123], v[122:123], 1.0 op_sel_hi:[1,0]
	v_pk_add_f32 v[100:101], v[100:101], 1.0 op_sel_hi:[1,0]
	v_rcp_f32_e32 v122, v122
	v_rcp_f32_e32 v123, v123
	v_rcp_f32_e32 v100, v100
	v_rcp_f32_e32 v101, v101
	v_pk_mul_f32 v[90:91], v[90:91], v[122:123]
	s_nop 0
	v_cvt_pk_bf16_f32 v96, v90, v91
	v_pk_mul_f32 v[92:93], v[92:93], v[100:101]
	s_nop 0
	v_cvt_pk_bf16_f32 v97, v92, v93
	global_store_dwordx4 v[220:221], v[94:97], off offset:256
	s_nop 0
	s_waitcnt vmcnt(3)
	v_lshlrev_b32_e32 v122, 16, v226
	v_and_b32_e32 v123, 0xffff0000, v226
	v_lshlrev_b32_e32 v90, 16, v227
	v_and_b32_e32 v91, 0xffff0000, v227
	s_waitcnt vmcnt(2)
	v_lshlrev_b32_e32 v124, 16, v230
	v_and_b32_e32 v125, 0xffff0000, v230
	v_lshlrev_b32_e32 v94, 16, v231
	v_and_b32_e32 v95, 0xffff0000, v231
	v_pk_fma_f32 v[122:123], v[66:67], v[122:123], v[70:71]
	v_pk_fma_f32 v[90:91], v[68:69], v[90:91], v[72:73]
	s_waitcnt vmcnt(1)
	s_mov_b32 s100, 178432
	s_mov_b32 s101, 0
	v_lshl_add_u64 v[222:223], v[246:247], 0, s[100:101]
	s_mov_b32 s100, 184576
	v_lshl_add_u64 v[220:221], v[246:247], 0, s[100:101]
	global_load_dwordx4 v[212:215], v[222:223], off offset:-3584
	global_load_dwordx4 v[216:219], v[222:223], off offset:2048
	global_load_dwordx4 v[220:223], v[220:221], off offset:1536
	v_lshlrev_b32_e32 v126, 16, v248
	v_and_b32_e32 v127, 0xffff0000, v248
	v_lshlrev_b32_e32 v98, 16, v249
	v_and_b32_e32 v99, 0xffff0000, v249
	v_pk_fma_f32 v[90:91], v[64:65], v[94:95], v[90:91]
	v_pk_fma_f32 v[94:95], v[62:63], v[124:125], v[122:123]
	v_pk_fma_f32 v[90:91], v[60:61], v[98:99], v[90:91]
	v_pk_fma_f32 v[94:95], v[58:59], v[126:127], v[94:95]
	v_pk_mul_f32 v[98:99], v[90:91], v[90:91]
	v_pk_mul_f32 v[122:123], v[94:95], v[94:95]
	v_pk_fma_f32 v[98:99], v[98:99], s[86:87], v[162:163] op_sel_hi:[1,0,0] neg_lo:[1,0,0] neg_hi:[1,0,0]
	v_pk_fma_f32 v[122:123], v[122:123], s[86:87], v[162:163] op_sel_hi:[1,0,0] neg_lo:[1,0,0] neg_hi:[1,0,0]
	v_pk_mul_f32 v[98:99], v[90:91], v[98:99]
	v_pk_mul_f32 v[122:123], v[94:95], v[122:123]
	v_exp_f32_e32 v98, v98
	v_exp_f32_e32 v122, v122
	v_exp_f32_e32 v123, v123
	v_exp_f32_e32 v99, v99
	v_pk_mul_f32 v[86:87], v[86:87], v[94:95]
	v_pk_mul_f32 v[88:89], v[88:89], v[90:91]
	v_pk_add_f32 v[122:123], v[122:123], 1.0 op_sel_hi:[1,0]
	v_pk_add_f32 v[98:99], v[98:99], 1.0 op_sel_hi:[1,0]
	v_rcp_f32_e32 v122, v122
	v_rcp_f32_e32 v123, v123
	v_rcp_f32_e32 v98, v98
	v_rcp_f32_e32 v99, v99
	v_lshlrev_b32_e32 v90, 16, v229
	v_pk_mul_f32 v[86:87], v[86:87], v[122:123]
	v_and_b32_e32 v91, 0xffff0000, v229
	v_pk_mul_f32 v[88:89], v[88:89], v[98:99]
	v_cvt_pk_bf16_f32 v86, v86, v87
; __device__ __forceinline__ float bflo(unsigned u) { return __uint_as_float(u << 16); }
;     __device__ __forceinline__ void operator()(const f32x4 (&acc)[2][2][4][2], const Unit& u, int wr, int wc, int fr, int fq) const {
;     ...
;                     const int row = u.pm * BM + ai * HALF + wr * 64 + m * 16 + fr;
;                     const int t = row & (SEQ - 1);
;                     const bf16_t* gp = G + (size_t)row * DFF + col;
;                     const bool hasm = t > 0, hasn = t < SEQ - 1;
;                     u32x4 gm = *(const u32x4*)(gp - (hasm ? DFF : 0));
;                     const u32x4 g0 = *(const u32x4*)gp;
;                     u32x4 gn = *(const u32x4*)(gp + (hasn ? DFF : 0));
;                     const unsigned mm = hasm ? 0xffffffffu : 0u, mn = hasn ? 0xffffffffu : 0u;
;                     gm.x &= mm; gm.y &= mm; gm.z &= mm; gm.w &= mm; gn.x &= mn; gn.y &= mn; gn.z &= mn; gn.w &= mn;
;                     unsigned ow[4];
; #pragma unroll
;                     for (int n = 0; n < 2; ++n) {
;                         const unsigned m0 = n ? gm.z : gm.x, m1 = n ? gm.w : gm.y, c0 = n ? g0.z : g0.x, c1 = n ? g0.w : g0.y, n0 = n ? gn.z : gn.x, n1 = n ? gn.w : gn.y;
;                         const f32x4 fm = {bflo(m0), bfhi(m0), bflo(m1), bfhi(m1)}, f0 = {bflo(c0), bfhi(c0), bflo(c1), bfhi(c1)}, fn = {bflo(n0), bfhi(n0), bflo(n1), bfhi(n1)};
;                         const f32x4 gc = bb[n] + fm * w0[n] + f0 * w1[n] + fn * w2[n];
;                         const f32x4 a = acc[ai][bj][m][n];
;                         constexpr float C1 = -2.0f * LOG2E * 0.7978845608028654f, C2 = C1 * 0.044715f;
;                         const f32x4 arg = gc * ((gc * gc) * C2 + C1);
;                         const f32x4 den = (f32x4){__builtin_amdgcn_exp2f(arg[0]), __builtin_amdgcn_exp2f(arg[1]), __builtin_amdgcn_exp2f(arg[2]), __builtin_amdgcn_exp2f(arg[3])} + 1.0f;
;                         const f32x4 rc = {__builtin_amdgcn_rcpf(den[0]), __builtin_amdgcn_rcpf(den[1]), __builtin_amdgcn_rcpf(den[2]), __builtin_amdgcn_rcpf(den[3])};
;                         const f32x4 o = (gc * a) * rc;
;                         ow[2 * n] = pk2(o[0], o[1]); ow[2 * n + 1] = pk2(o[2], o[3]);
;                     }
;                     *(u32x4*)(H + (size_t)row * DFF + col) = (u32x4){ow[0], ow[1], ow[2], ow[3]};
	v_cvt_pk_bf16_f32 v87, v88, v89
	v_lshlrev_b32_e32 v88, 16, v228
	v_and_b32_e32 v89, 0xffff0000, v228
	v_lshlrev_b32_e32 v92, 16, v232
	v_and_b32_e32 v93, 0xffff0000, v232
	v_lshlrev_b32_e32 v94, 16, v233
	v_and_b32_e32 v95, 0xffff0000, v233
	v_pk_fma_f32 v[88:89], v[50:51], v[88:89], v[54:55]
	v_pk_fma_f32 v[90:91], v[52:53], v[90:91], v[56:57]
	v_lshlrev_b32_e32 v96, 16, v250
	v_and_b32_e32 v97, 0xffff0000, v250
	v_lshlrev_b32_e32 v98, 16, v251
	v_and_b32_e32 v99, 0xffff0000, v251
	v_pk_fma_f32 v[90:91], v[48:49], v[94:95], v[90:91]
	v_pk_fma_f32 v[88:89], v[46:47], v[92:93], v[88:89]
	v_pk_fma_f32 v[90:91], v[44:45], v[98:99], v[90:91]
	v_pk_fma_f32 v[88:89], v[42:43], v[96:97], v[88:89]
	v_pk_mul_f32 v[92:93], v[90:91], v[90:91]
	v_pk_mul_f32 v[94:95], v[88:89], v[88:89]
	v_pk_fma_f32 v[92:93], v[92:93], s[86:87], v[162:163] op_sel_hi:[1,0,0] neg_lo:[1,0,0] neg_hi:[1,0,0]
	v_pk_fma_f32 v[94:95], v[94:95], s[86:87], v[162:163] op_sel_hi:[1,0,0] neg_lo:[1,0,0] neg_hi:[1,0,0]
	v_pk_mul_f32 v[92:93], v[90:91], v[92:93]
	v_pk_mul_f32 v[94:95], v[88:89], v[94:95]
	v_exp_f32_e32 v92, v92
	v_exp_f32_e32 v94, v94
	v_exp_f32_e32 v95, v95
	v_exp_f32_e32 v93, v93
	v_pk_mul_f32 v[82:83], v[82:83], v[88:89]
	v_pk_mul_f32 v[84:85], v[84:85], v[90:91]
	v_pk_add_f32 v[94:95], v[94:95], 1.0 op_sel_hi:[1,0]
	v_pk_add_f32 v[92:93], v[92:93], 1.0 op_sel_hi:[1,0]
	v_rcp_f32_e32 v94, v94
	v_rcp_f32_e32 v95, v95
	v_rcp_f32_e32 v92, v92
	v_rcp_f32_e32 v93, v93
	v_pk_mul_f32 v[82:83], v[82:83], v[94:95]
	s_nop 0
	v_cvt_pk_bf16_f32 v88, v82, v83
	v_pk_mul_f32 v[84:85], v[84:85], v[92:93]
	s_nop 0
	v_cvt_pk_bf16_f32 v89, v84, v85
	global_store_dwordx4 v[210:211], v[86:89], off offset:256
	s_nop 0
	s_waitcnt vmcnt(3)
	v_lshlrev_b32_e32 v94, 16, v212
	v_and_b32_e32 v95, 0xffff0000, v212
	v_lshlrev_b32_e32 v82, 16, v213
	v_and_b32_e32 v83, 0xffff0000, v213
	s_waitcnt vmcnt(2)
	v_lshlrev_b32_e32 v96, 16, v216
	v_and_b32_e32 v97, 0xffff0000, v216
	v_lshlrev_b32_e32 v86, 16, v217
	v_and_b32_e32 v87, 0xffff0000, v217
	v_pk_fma_f32 v[94:95], v[66:67], v[94:95], v[70:71]
	v_pk_fma_f32 v[82:83], v[68:69], v[82:83], v[72:73]
	s_waitcnt vmcnt(1)
	s_mov_b32 s100, 268544
	s_mov_b32 s101, 0
	v_lshl_add_u64 v[250:251], v[246:247], 0, s[100:101]
	s_mov_b32 s100, 274688
	v_lshl_add_u64 v[248:249], v[246:247], 0, s[100:101]
	global_load_dwordx4 v[228:231], v[250:251], off offset:-3584
	global_load_dwordx4 v[232:235], v[250:251], off offset:2048
	global_load_dwordx4 v[248:251], v[248:249], off offset:1536
	v_lshlrev_b32_e32 v98, 16, v220
	v_and_b32_e32 v99, 0xffff0000, v220
	v_lshlrev_b32_e32 v90, 16, v221
	v_and_b32_e32 v91, 0xffff0000, v221
	v_pk_fma_f32 v[82:83], v[64:65], v[86:87], v[82:83]
	v_pk_fma_f32 v[86:87], v[62:63], v[96:97], v[94:95]
	v_pk_fma_f32 v[82:83], v[60:61], v[90:91], v[82:83]
	v_pk_fma_f32 v[86:87], v[58:59], v[98:99], v[86:87]
	v_pk_mul_f32 v[90:91], v[82:83], v[82:83]
	v_pk_mul_f32 v[94:95], v[86:87], v[86:87]
	v_pk_fma_f32 v[90:91], v[90:91], s[86:87], v[162:163] op_sel_hi:[1,0,0] neg_lo:[1,0,0] neg_hi:[1,0,0]
	v_pk_fma_f32 v[94:95], v[94:95], s[86:87], v[162:163] op_sel_hi:[1,0,0] neg_lo:[1,0,0] neg_hi:[1,0,0]
	v_pk_mul_f32 v[90:91], v[82:83], v[90:91]
	v_pk_mul_f32 v[94:95], v[86:87], v[94:95]
	v_exp_f32_e32 v90, v90
	v_exp_f32_e32 v94, v94
	v_exp_f32_e32 v95, v95
	v_exp_f32_e32 v91, v91
	v_pk_mul_f32 v[78:79], v[78:79], v[86:87]
	v_pk_mul_f32 v[80:81], v[80:81], v[82:83]
	v_pk_add_f32 v[94:95], v[94:95], 1.0 op_sel_hi:[1,0]
	v_pk_add_f32 v[90:91], v[90:91], 1.0 op_sel_hi:[1,0]
	v_rcp_f32_e32 v94, v94
	v_rcp_f32_e32 v95, v95
	v_rcp_f32_e32 v90, v90
	v_rcp_f32_e32 v91, v91
	v_lshlrev_b32_e32 v82, 16, v215
	v_pk_mul_f32 v[78:79], v[78:79], v[94:95]
	v_and_b32_e32 v83, 0xffff0000, v215
	v_pk_mul_f32 v[80:81], v[80:81], v[90:91]
	v_cvt_pk_bf16_f32 v78, v78, v79
	v_cvt_pk_bf16_f32 v79, v80, v81
	v_lshlrev_b32_e32 v80, 16, v214
	v_and_b32_e32 v81, 0xffff0000, v214
	v_lshlrev_b32_e32 v84, 16, v218
	v_and_b32_e32 v85, 0xffff0000, v218
	v_lshlrev_b32_e32 v86, 16, v219
	v_and_b32_e32 v87, 0xffff0000, v219
	v_pk_fma_f32 v[80:81], v[50:51], v[80:81], v[54:55]
	v_pk_fma_f32 v[82:83], v[52:53], v[82:83], v[56:57]
	v_lshlrev_b32_e32 v88, 16, v222
	v_and_b32_e32 v89, 0xffff0000, v222
	v_lshlrev_b32_e32 v90, 16, v223
	v_and_b32_e32 v91, 0xffff0000, v223
	v_pk_fma_f32 v[82:83], v[48:49], v[86:87], v[82:83]
	v_pk_fma_f32 v[80:81], v[46:47], v[84:85], v[80:81]
	v_pk_fma_f32 v[82:83], v[44:45], v[90:91], v[82:83]
	v_pk_fma_f32 v[80:81], v[42:43], v[88:89], v[80:81]
	v_pk_mul_f32 v[84:85], v[82:83], v[82:83]
	v_pk_mul_f32 v[86:87], v[80:81], v[80:81]
	v_pk_fma_f32 v[84:85], v[84:85], s[86:87], v[162:163] op_sel_hi:[1,0,0] neg_lo:[1,0,0] neg_hi:[1,0,0]
	v_pk_fma_f32 v[86:87], v[86:87], s[86:87], v[162:163] op_sel_hi:[1,0,0] neg_lo:[1,0,0] neg_hi:[1,0,0]
	v_pk_mul_f32 v[84:85], v[82:83], v[84:85]
	v_pk_mul_f32 v[86:87], v[80:81], v[86:87]
	v_exp_f32_e32 v84, v84
	v_exp_f32_e32 v86, v86
	v_exp_f32_e32 v87, v87
	v_exp_f32_e32 v85, v85
	v_pk_mul_f32 v[74:75], v[74:75], v[80:81]
	v_pk_mul_f32 v[76:77], v[76:77], v[82:83]
	v_pk_add_f32 v[86:87], v[86:87], 1.0 op_sel_hi:[1,0]
	v_pk_add_f32 v[84:85], v[84:85], 1.0 op_sel_hi:[1,0]
	v_rcp_f32_e32 v86, v86
	v_rcp_f32_e32 v87, v87
	v_rcp_f32_e32 v84, v84
	v_rcp_f32_e32 v85, v85
	v_pk_mul_f32 v[74:75], v[74:75], v[86:87]
	s_nop 0
	v_cvt_pk_bf16_f32 v80, v74, v75
	v_pk_mul_f32 v[76:77], v[76:77], v[84:85]
	s_nop 0
	v_cvt_pk_bf16_f32 v81, v76, v77
	global_store_dwordx4 v[202:203], v[78:81], off offset:256
	s_nop 0
	s_waitcnt vmcnt(1)
; __device__ __forceinline__ float bflo(unsigned u) { return __uint_as_float(u << 16); }
;     __device__ __forceinline__ void operator()(const f32x4 (&acc)[2][2][4][2], const Unit& u, int wr, int wc, int fr, int fq) const {
;     ...
;                     const int row = u.pm * BM + ai * HALF + wr * 64 + m * 16 + fr;
;                     const int t = row & (SEQ - 1);
;                     const bf16_t* gp = G + (size_t)row * DFF + col;
;                     const bool hasm = t > 0, hasn = t < SEQ - 1;
;                     u32x4 gm = *(const u32x4*)(gp - (hasm ? DFF : 0));
;                     const u32x4 g0 = *(const u32x4*)gp;
;                     u32x4 gn = *(const u32x4*)(gp + (hasn ? DFF : 0));
;                     const unsigned mm = hasm ? 0xffffffffu : 0u, mn = hasn ? 0xffffffffu : 0u;
;                     gm.x &= mm; gm.y &= mm; gm.z &= mm; gm.w &= mm; gn.x &= mn; gn.y &= mn; gn.z &= mn; gn.w &= mn;
;                     unsigned ow[4];
; #pragma unroll
;                     for (int n = 0; n < 2; ++n) {
;                         const unsigned m0 = n ? gm.z : gm.x, m1 = n ? gm.w : gm.y, c0 = n ? g0.z : g0.x, c1 = n ? g0.w : g0.y, n0 = n ? gn.z : gn.x, n1 = n ? gn.w : gn.y;
;                         const f32x4 fm = {bflo(m0), bfhi(m0), bflo(m1), bfhi(m1)}, f0 = {bflo(c0), bfhi(c0), bflo(c1), bfhi(c1)}, fn = {bflo(n0), bfhi(n0), bflo(n1), bfhi(n1)};
;                         const f32x4 gc = bb[n] + fm * w0[n] + f0 * w1[n] + fn * w2[n];
;                         const f32x4 a = acc[ai][bj][m][n];
;                         constexpr float C1 = -2.0f * LOG2E * 0.7978845608028654f, C2 = C1 * 0.044715f;
;                         const f32x4 arg = gc * ((gc * gc) * C2 + C1);
;                         const f32x4 den = (f32x4){__builtin_amdgcn_exp2f(arg[0]), __builtin_amdgcn_exp2f(arg[1]), __builtin_amdgcn_exp2f(arg[2]), __builtin_amdgcn_exp2f(arg[3])} + 1.0f;
;                         const f32x4 rc = {__builtin_amdgcn_rcpf(den[0]), __builtin_amdgcn_rcpf(den[1]), __builtin_amdgcn_rcpf(den[2]), __builtin_amdgcn_rcpf(den[3])};
;                         const f32x4 o = (gc * a) * rc;
;                         ow[2 * n] = pk2(o[0], o[1]); ow[2 * n + 1] = pk2(o[2], o[3]);
;                     }
;                     *(u32x4*)(H + (size_t)row * DFF + col) = (u32x4){ow[0], ow[1], ow[2], ow[3]};
	s_mov_b32 s100, 719104
	s_mov_b32 s101, 0
	v_lshl_add_u64 v[224:225], v[246:247], 0, s[100:101]
	s_mov_b32 s100, 725248
	v_lshl_add_u64 v[222:223], v[246:247], 0, s[100:101]
	global_load_dwordx4 v[214:217], v[224:225], off offset:-3584
	global_load_dwordx4 v[218:221], v[224:225], off offset:2048
	global_load_dwordx4 v[222:225], v[222:223], off offset:1536
	v_cndmask_b32_e64 v12, v248, 0, s[6:7]
	v_cndmask_b32_e64 v89, v249, 0, s[6:7]
	v_lshlrev_b32_e32 v82, 16, v228
	v_and_b32_e32 v83, 0xffff0000, v228
	v_lshlrev_b32_e32 v74, 16, v229
	v_and_b32_e32 v75, 0xffff0000, v229
	v_cndmask_b32_e64 v90, v250, 0, s[6:7]
	v_cndmask_b32_e64 v91, v251, 0, s[6:7]
	v_lshlrev_b32_e32 v84, 16, v232
	v_and_b32_e32 v85, 0xffff0000, v232
	v_lshlrev_b32_e32 v78, 16, v233
	v_and_b32_e32 v79, 0xffff0000, v233
	v_pk_fma_f32 v[82:83], v[66:67], v[82:83], v[70:71]
	v_pk_fma_f32 v[74:75], v[68:69], v[74:75], v[72:73]
	v_lshlrev_b32_e32 v86, 16, v12
	v_and_b32_e32 v87, 0xffff0000, v12
	v_lshlrev_b32_e32 v88, 16, v89
	v_and_b32_e32 v89, 0xffff0000, v89
	v_pk_fma_f32 v[74:75], v[64:65], v[78:79], v[74:75]
	v_pk_fma_f32 v[78:79], v[62:63], v[84:85], v[82:83]
	v_pk_fma_f32 v[74:75], v[60:61], v[88:89], v[74:75]
	v_pk_fma_f32 v[78:79], v[58:59], v[86:87], v[78:79]
	v_pk_mul_f32 v[82:83], v[74:75], v[74:75]
	v_pk_mul_f32 v[84:85], v[78:79], v[78:79]
	v_pk_fma_f32 v[82:83], v[82:83], s[86:87], v[162:163] op_sel_hi:[1,0,0] neg_lo:[1,0,0] neg_hi:[1,0,0]
	v_pk_fma_f32 v[84:85], v[84:85], s[86:87], v[162:163] op_sel_hi:[1,0,0] neg_lo:[1,0,0] neg_hi:[1,0,0]
	v_pk_mul_f32 v[82:83], v[74:75], v[82:83]
	v_pk_mul_f32 v[84:85], v[78:79], v[84:85]
	v_exp_f32_e32 v82, v82
	v_exp_f32_e32 v84, v84
	v_exp_f32_e32 v85, v85
	v_exp_f32_e32 v83, v83
	v_pk_mul_f32 v[38:39], v[38:39], v[78:79]
	v_pk_mul_f32 v[40:41], v[40:41], v[74:75]
	v_pk_add_f32 v[84:85], v[84:85], 1.0 op_sel_hi:[1,0]
	v_pk_add_f32 v[82:83], v[82:83], 1.0 op_sel_hi:[1,0]
	v_rcp_f32_e32 v84, v84
	v_rcp_f32_e32 v85, v85
	v_rcp_f32_e32 v82, v82
	v_rcp_f32_e32 v83, v83
	v_lshlrev_b32_e32 v74, 16, v231
	v_pk_mul_f32 v[38:39], v[38:39], v[84:85]
	v_and_b32_e32 v75, 0xffff0000, v231
	v_pk_mul_f32 v[40:41], v[40:41], v[82:83]
	v_cvt_pk_bf16_f32 v38, v38, v39
	v_cvt_pk_bf16_f32 v39, v40, v41
	v_lshlrev_b32_e32 v40, 16, v230
	v_and_b32_e32 v41, 0xffff0000, v230
	v_lshlrev_b32_e32 v76, 16, v234
	v_and_b32_e32 v77, 0xffff0000, v234
	v_lshlrev_b32_e32 v78, 16, v235
	v_and_b32_e32 v79, 0xffff0000, v235
	v_pk_fma_f32 v[40:41], v[50:51], v[40:41], v[54:55]
	v_pk_fma_f32 v[74:75], v[52:53], v[74:75], v[56:57]
	v_lshlrev_b32_e32 v80, 16, v90
	v_and_b32_e32 v81, 0xffff0000, v90
	v_lshlrev_b32_e32 v82, 16, v91
	v_and_b32_e32 v83, 0xffff0000, v91
	v_pk_fma_f32 v[74:75], v[48:49], v[78:79], v[74:75]
	v_pk_fma_f32 v[40:41], v[46:47], v[76:77], v[40:41]
	v_pk_fma_f32 v[74:75], v[44:45], v[82:83], v[74:75]
	v_pk_fma_f32 v[40:41], v[42:43], v[80:81], v[40:41]
	v_pk_mul_f32 v[76:77], v[74:75], v[74:75]
	v_pk_mul_f32 v[78:79], v[40:41], v[40:41]
	v_pk_fma_f32 v[76:77], v[76:77], s[86:87], v[162:163] op_sel_hi:[1,0,0] neg_lo:[1,0,0] neg_hi:[1,0,0]
	v_pk_fma_f32 v[78:79], v[78:79], s[86:87], v[162:163] op_sel_hi:[1,0,0] neg_lo:[1,0,0] neg_hi:[1,0,0]
	v_pk_mul_f32 v[76:77], v[74:75], v[76:77]
	v_pk_mul_f32 v[78:79], v[40:41], v[78:79]
	v_exp_f32_e32 v76, v76
	v_exp_f32_e32 v78, v78
	v_exp_f32_e32 v79, v79
	v_exp_f32_e32 v77, v77
	v_pk_mul_f32 v[34:35], v[34:35], v[40:41]
	v_pk_mul_f32 v[36:37], v[36:37], v[74:75]
	v_pk_add_f32 v[78:79], v[78:79], 1.0 op_sel_hi:[1,0]
	v_pk_add_f32 v[76:77], v[76:77], 1.0 op_sel_hi:[1,0]
	v_rcp_f32_e32 v78, v78
	v_rcp_f32_e32 v79, v79
	v_rcp_f32_e32 v76, v76
	v_rcp_f32_e32 v77, v77
	v_pk_mul_f32 v[34:35], v[34:35], v[78:79]
	s_nop 0
	v_cvt_pk_bf16_f32 v40, v34, v35
	v_pk_mul_f32 v[36:37], v[36:37], v[76:77]
	s_nop 0
	v_cvt_pk_bf16_f32 v41, v36, v37
	global_store_dwordx4 v[160:161], v[38:41], off offset:256
	s_nop 0
	s_waitcnt vmcnt(3)
	v_cndmask_b32_e64 v12, v214, 0, s[4:5]
	v_cndmask_b32_e64 v78, v215, 0, s[4:5]
	v_cndmask_b32_e64 v82, v216, 0, s[4:5]
	v_cndmask_b32_e64 v83, v217, 0, s[4:5]
	v_lshlrev_b32_e32 v34, 16, v12
	v_and_b32_e32 v35, 0xffff0000, v12
	v_lshlrev_b32_e32 v36, 16, v78
	v_and_b32_e32 v37, 0xffff0000, v78
	s_waitcnt vmcnt(2)
	v_lshlrev_b32_e32 v78, 16, v218
	v_and_b32_e32 v79, 0xffff0000, v218
	v_lshlrev_b32_e32 v38, 16, v219
	v_and_b32_e32 v39, 0xffff0000, v219
	v_pk_fma_f32 v[34:35], v[66:67], v[34:35], v[70:71]
	v_pk_fma_f32 v[36:37], v[68:69], v[36:37], v[72:73]
	s_waitcnt vmcnt(1)
; __device__ __forceinline__ float bflo(unsigned u) { return __uint_as_float(u << 16); }
;     __device__ __forceinline__ void operator()(const f32x4 (&acc)[2][2][4][2], const Unit& u, int wr, int wc, int fr, int fq) const {
;     ...
;                     const int row = u.pm * BM + ai * HALF + wr * 64 + m * 16 + fr;
;                     const int t = row & (SEQ - 1);
;                     const bf16_t* gp = G + (size_t)row * DFF + col;
;                     const bool hasm = t > 0, hasn = t < SEQ - 1;
;                     u32x4 gm = *(const u32x4*)(gp - (hasm ? DFF : 0));
;                     const u32x4 g0 = *(const u32x4*)gp;
;                     u32x4 gn = *(const u32x4*)(gp + (hasn ? DFF : 0));
;                     const unsigned mm = hasm ? 0xffffffffu : 0u, mn = hasn ? 0xffffffffu : 0u;
;                     gm.x &= mm; gm.y &= mm; gm.z &= mm; gm.w &= mm; gn.x &= mn; gn.y &= mn; gn.z &= mn; gn.w &= mn;
;                     unsigned ow[4];
; #pragma unroll
;                     for (int n = 0; n < 2; ++n) {
;                         const unsigned m0 = n ? gm.z : gm.x, m1 = n ? gm.w : gm.y, c0 = n ? g0.z : g0.x, c1 = n ? g0.w : g0.y, n0 = n ? gn.z : gn.x, n1 = n ? gn.w : gn.y;
;                         const f32x4 fm = {bflo(m0), bfhi(m0), bflo(m1), bfhi(m1)}, f0 = {bflo(c0), bfhi(c0), bflo(c1), bfhi(c1)}, fn = {bflo(n0), bfhi(n0), bflo(n1), bfhi(n1)};
;                         const f32x4 gc = bb[n] + fm * w0[n] + f0 * w1[n] + fn * w2[n];
;                         const f32x4 a = acc[ai][bj][m][n];
;                         constexpr float C1 = -2.0f * LOG2E * 0.7978845608028654f, C2 = C1 * 0.044715f;
;                         const f32x4 arg = gc * ((gc * gc) * C2 + C1);
;                         const f32x4 den = (f32x4){__builtin_amdgcn_exp2f(arg[0]), __builtin_amdgcn_exp2f(arg[1]), __builtin_amdgcn_exp2f(arg[2]), __builtin_amdgcn_exp2f(arg[3])} + 1.0f;
;                         const f32x4 rc = {__builtin_amdgcn_rcpf(den[0]), __builtin_amdgcn_rcpf(den[1]), __builtin_amdgcn_rcpf(den[2]), __builtin_amdgcn_rcpf(den[3])};
;                         const f32x4 o = (gc * a) * rc;
;                         ow[2 * n] = pk2(o[0], o[1]); ow[2 * n + 1] = pk2(o[2], o[3]);
;                     }
;                     *(u32x4*)(H + (size_t)row * DFF + col) = (u32x4){ow[0], ow[1], ow[2], ow[3]};
	s_mov_b32 s100, 809216
	s_mov_b32 s101, 0
	v_lshl_add_u64 v[250:251], v[246:247], 0, s[100:101]
	s_mov_b32 s100, 815360
	v_lshl_add_u64 v[248:249], v[246:247], 0, s[100:101]
	global_load_dwordx4 v[226:229], v[250:251], off offset:-3584
	global_load_dwordx4 v[230:233], v[250:251], off offset:2048
	global_load_dwordx4 v[248:251], v[248:249], off offset:1536
	v_lshlrev_b32_e32 v80, 16, v222
	v_and_b32_e32 v81, 0xffff0000, v222
	v_lshlrev_b32_e32 v74, 16, v223
	v_and_b32_e32 v75, 0xffff0000, v223
	v_pk_fma_f32 v[36:37], v[64:65], v[38:39], v[36:37]
	v_pk_fma_f32 v[34:35], v[62:63], v[78:79], v[34:35]
	v_pk_fma_f32 v[36:37], v[60:61], v[74:75], v[36:37]
	v_pk_fma_f32 v[34:35], v[58:59], v[80:81], v[34:35]
	v_pk_mul_f32 v[38:39], v[36:37], v[36:37]
	v_pk_mul_f32 v[74:75], v[34:35], v[34:35]
	v_pk_fma_f32 v[38:39], v[38:39], s[86:87], v[162:163] op_sel_hi:[1,0,0] neg_lo:[1,0,0] neg_hi:[1,0,0]
	v_pk_fma_f32 v[74:75], v[74:75], s[86:87], v[162:163] op_sel_hi:[1,0,0] neg_lo:[1,0,0] neg_hi:[1,0,0]
	v_pk_mul_f32 v[38:39], v[36:37], v[38:39]
	v_pk_mul_f32 v[74:75], v[34:35], v[74:75]
	v_exp_f32_e32 v38, v38
	v_exp_f32_e32 v74, v74
	v_exp_f32_e32 v75, v75
	v_exp_f32_e32 v39, v39
	v_pk_mul_f32 v[30:31], v[30:31], v[34:35]
	v_pk_mul_f32 v[32:33], v[32:33], v[36:37]
	v_pk_add_f32 v[74:75], v[74:75], 1.0 op_sel_hi:[1,0]
	v_pk_add_f32 v[38:39], v[38:39], 1.0 op_sel_hi:[1,0]
	v_rcp_f32_e32 v74, v74
	v_rcp_f32_e32 v75, v75
	v_rcp_f32_e32 v38, v38
	v_rcp_f32_e32 v39, v39
	v_lshlrev_b32_e32 v34, 16, v83
	v_pk_mul_f32 v[30:31], v[30:31], v[74:75]
	v_and_b32_e32 v35, 0xffff0000, v83
	v_pk_mul_f32 v[32:33], v[32:33], v[38:39]
	v_cvt_pk_bf16_f32 v30, v30, v31
	v_cvt_pk_bf16_f32 v31, v32, v33
	v_lshlrev_b32_e32 v32, 16, v82
	v_and_b32_e32 v33, 0xffff0000, v82
	v_lshlrev_b32_e32 v36, 16, v220
	v_and_b32_e32 v37, 0xffff0000, v220
	v_lshlrev_b32_e32 v38, 16, v221
	v_and_b32_e32 v39, 0xffff0000, v221
	v_pk_fma_f32 v[32:33], v[50:51], v[32:33], v[54:55]
	v_pk_fma_f32 v[34:35], v[52:53], v[34:35], v[56:57]
	v_lshlrev_b32_e32 v40, 16, v224
	v_and_b32_e32 v41, 0xffff0000, v224
	v_lshlrev_b32_e32 v74, 16, v225
	v_and_b32_e32 v75, 0xffff0000, v225
	v_pk_fma_f32 v[34:35], v[48:49], v[38:39], v[34:35]
	v_pk_fma_f32 v[32:33], v[46:47], v[36:37], v[32:33]
	v_pk_fma_f32 v[34:35], v[44:45], v[74:75], v[34:35]
	v_pk_fma_f32 v[32:33], v[42:43], v[40:41], v[32:33]
	v_pk_mul_f32 v[36:37], v[34:35], v[34:35]
	v_pk_mul_f32 v[38:39], v[32:33], v[32:33]
	v_pk_fma_f32 v[36:37], v[36:37], s[86:87], v[162:163] op_sel_hi:[1,0,0] neg_lo:[1,0,0] neg_hi:[1,0,0]
	v_pk_fma_f32 v[38:39], v[38:39], s[86:87], v[162:163] op_sel_hi:[1,0,0] neg_lo:[1,0,0] neg_hi:[1,0,0]
	v_pk_mul_f32 v[36:37], v[34:35], v[36:37]
	v_pk_mul_f32 v[38:39], v[32:33], v[38:39]
	v_exp_f32_e32 v36, v36
	v_exp_f32_e32 v38, v38
	v_exp_f32_e32 v39, v39
	v_exp_f32_e32 v37, v37
	v_pk_mul_f32 v[26:27], v[26:27], v[32:33]
	v_pk_mul_f32 v[28:29], v[28:29], v[34:35]
	v_pk_add_f32 v[38:39], v[38:39], 1.0 op_sel_hi:[1,0]
	v_pk_add_f32 v[36:37], v[36:37], 1.0 op_sel_hi:[1,0]
	v_rcp_f32_e32 v38, v38
	v_rcp_f32_e32 v39, v39
	v_rcp_f32_e32 v36, v36
	v_rcp_f32_e32 v37, v37
	s_mov_b64 s[4:5], -1
	v_pk_mul_f32 v[26:27], v[26:27], v[38:39]
	v_pk_mul_f32 v[28:29], v[28:29], v[36:37]
	v_cvt_pk_bf16_f32 v32, v26, v27
	v_cvt_pk_bf16_f32 v33, v28, v29
	global_store_dwordx4 v[120:121], v[30:33], off offset:256
	s_nop 0
	s_waitcnt vmcnt(3)
	v_lshlrev_b32_e32 v38, 16, v226
	v_and_b32_e32 v39, 0xffff0000, v226
	v_lshlrev_b32_e32 v26, 16, v227
	v_and_b32_e32 v27, 0xffff0000, v227
	s_waitcnt vmcnt(2)
	v_lshlrev_b32_e32 v40, 16, v230
	v_and_b32_e32 v41, 0xffff0000, v230
	v_lshlrev_b32_e32 v30, 16, v231
	v_and_b32_e32 v31, 0xffff0000, v231
	v_pk_fma_f32 v[38:39], v[66:67], v[38:39], v[70:71]
	v_pk_fma_f32 v[26:27], v[68:69], v[26:27], v[72:73]
	s_waitcnt vmcnt(1)
	s_mov_b32 s100, 899328
	s_mov_b32 s101, 0
	v_lshl_add_u64 v[224:225], v[246:247], 0, s[100:101]
	s_mov_b32 s100, 905472
	v_lshl_add_u64 v[222:223], v[246:247], 0, s[100:101]
	global_load_dwordx4 v[214:217], v[224:225], off offset:-3584
	global_load_dwordx4 v[218:221], v[224:225], off offset:2048
	global_load_dwordx4 v[222:225], v[222:223], off offset:1536
	v_lshlrev_b32_e32 v74, 16, v248
	v_and_b32_e32 v75, 0xffff0000, v248
	v_lshlrev_b32_e32 v34, 16, v249
	v_and_b32_e32 v35, 0xffff0000, v249
	v_pk_fma_f32 v[26:27], v[64:65], v[30:31], v[26:27]
	v_pk_fma_f32 v[30:31], v[62:63], v[40:41], v[38:39]
	v_pk_fma_f32 v[26:27], v[60:61], v[34:35], v[26:27]
	v_pk_fma_f32 v[30:31], v[58:59], v[74:75], v[30:31]
	v_pk_mul_f32 v[34:35], v[26:27], v[26:27]
	v_pk_mul_f32 v[38:39], v[30:31], v[30:31]
	v_pk_fma_f32 v[34:35], v[34:35], s[86:87], v[162:163] op_sel_hi:[1,0,0] neg_lo:[1,0,0] neg_hi:[1,0,0]
	v_pk_fma_f32 v[38:39], v[38:39], s[86:87], v[162:163] op_sel_hi:[1,0,0] neg_lo:[1,0,0] neg_hi:[1,0,0]
	v_pk_mul_f32 v[34:35], v[26:27], v[34:35]
	v_pk_mul_f32 v[38:39], v[30:31], v[38:39]
	v_exp_f32_e32 v34, v34
	v_exp_f32_e32 v38, v38
	v_exp_f32_e32 v39, v39
	v_exp_f32_e32 v35, v35
	v_pk_mul_f32 v[22:23], v[22:23], v[30:31]
	v_pk_mul_f32 v[24:25], v[24:25], v[26:27]
	v_pk_add_f32 v[38:39], v[38:39], 1.0 op_sel_hi:[1,0]
	v_pk_add_f32 v[34:35], v[34:35], 1.0 op_sel_hi:[1,0]
	v_rcp_f32_e32 v38, v38
	v_rcp_f32_e32 v39, v39
	v_rcp_f32_e32 v34, v34
	v_rcp_f32_e32 v35, v35
	v_lshlrev_b32_e32 v26, 16, v229
	v_pk_mul_f32 v[22:23], v[22:23], v[38:39]
	v_and_b32_e32 v27, 0xffff0000, v229
	v_pk_mul_f32 v[24:25], v[24:25], v[34:35]
	v_cvt_pk_bf16_f32 v22, v22, v23
	v_cvt_pk_bf16_f32 v23, v24, v25
	v_lshlrev_b32_e32 v24, 16, v228
	v_and_b32_e32 v25, 0xffff0000, v228
	v_lshlrev_b32_e32 v28, 16, v232
	v_and_b32_e32 v29, 0xffff0000, v232
; __device__ __forceinline__ float bflo(unsigned u) { return __uint_as_float(u << 16); }
;     __device__ __forceinline__ void operator()(const f32x4 (&acc)[2][2][4][2], const Unit& u, int wr, int wc, int fr, int fq) const {
;     ...
;                     const int row = u.pm * BM + ai * HALF + wr * 64 + m * 16 + fr;
;                     const int t = row & (SEQ - 1);
;                     const bf16_t* gp = G + (size_t)row * DFF + col;
;                     const bool hasm = t > 0, hasn = t < SEQ - 1;
;                     u32x4 gm = *(const u32x4*)(gp - (hasm ? DFF : 0));
;                     const u32x4 g0 = *(const u32x4*)gp;
;                     u32x4 gn = *(const u32x4*)(gp + (hasn ? DFF : 0));
;                     const unsigned mm = hasm ? 0xffffffffu : 0u, mn = hasn ? 0xffffffffu : 0u;
;                     gm.x &= mm; gm.y &= mm; gm.z &= mm; gm.w &= mm; gn.x &= mn; gn.y &= mn; gn.z &= mn; gn.w &= mn;
;                     unsigned ow[4];
; #pragma unroll
;                     for (int n = 0; n < 2; ++n) {
;                         const unsigned m0 = n ? gm.z : gm.x, m1 = n ? gm.w : gm.y, c0 = n ? g0.z : g0.x, c1 = n ? g0.w : g0.y, n0 = n ? gn.z : gn.x, n1 = n ? gn.w : gn.y;
;                         const f32x4 fm = {bflo(m0), bfhi(m0), bflo(m1), bfhi(m1)}, f0 = {bflo(c0), bfhi(c0), bflo(c1), bfhi(c1)}, fn = {bflo(n0), bfhi(n0), bflo(n1), bfhi(n1)};
;                         const f32x4 gc = bb[n] + fm * w0[n] + f0 * w1[n] + fn * w2[n];
;                         const f32x4 a = acc[ai][bj][m][n];
;                         constexpr float C1 = -2.0f * LOG2E * 0.7978845608028654f, C2 = C1 * 0.044715f;
;                         const f32x4 arg = gc * ((gc * gc) * C2 + C1);
;                         const f32x4 den = (f32x4){__builtin_amdgcn_exp2f(arg[0]), __builtin_amdgcn_exp2f(arg[1]), __builtin_amdgcn_exp2f(arg[2]), __builtin_amdgcn_exp2f(arg[3])} + 1.0f;
;                         const f32x4 rc = {__builtin_amdgcn_rcpf(den[0]), __builtin_amdgcn_rcpf(den[1]), __builtin_amdgcn_rcpf(den[2]), __builtin_amdgcn_rcpf(den[3])};
;                         const f32x4 o = (gc * a) * rc;
;                         ow[2 * n] = pk2(o[0], o[1]); ow[2 * n + 1] = pk2(o[2], o[3]);
;                     }
;                     *(u32x4*)(H + (size_t)row * DFF + col) = (u32x4){ow[0], ow[1], ow[2], ow[3]};
	v_lshlrev_b32_e32 v30, 16, v233
	v_and_b32_e32 v31, 0xffff0000, v233
	v_pk_fma_f32 v[24:25], v[50:51], v[24:25], v[54:55]
	v_pk_fma_f32 v[26:27], v[52:53], v[26:27], v[56:57]
	v_lshlrev_b32_e32 v32, 16, v250
	v_and_b32_e32 v33, 0xffff0000, v250
	v_lshlrev_b32_e32 v34, 16, v251
	v_and_b32_e32 v35, 0xffff0000, v251
	v_pk_fma_f32 v[26:27], v[48:49], v[30:31], v[26:27]
	v_pk_fma_f32 v[24:25], v[46:47], v[28:29], v[24:25]
	v_pk_fma_f32 v[26:27], v[44:45], v[34:35], v[26:27]
	v_pk_fma_f32 v[24:25], v[42:43], v[32:33], v[24:25]
	v_pk_mul_f32 v[28:29], v[26:27], v[26:27]
	v_pk_mul_f32 v[30:31], v[24:25], v[24:25]
	v_pk_fma_f32 v[28:29], v[28:29], s[86:87], v[162:163] op_sel_hi:[1,0,0] neg_lo:[1,0,0] neg_hi:[1,0,0]
	v_pk_fma_f32 v[30:31], v[30:31], s[86:87], v[162:163] op_sel_hi:[1,0,0] neg_lo:[1,0,0] neg_hi:[1,0,0]
	v_pk_mul_f32 v[28:29], v[26:27], v[28:29]
	v_pk_mul_f32 v[30:31], v[24:25], v[30:31]
	v_exp_f32_e32 v28, v28
	v_exp_f32_e32 v30, v30
	v_exp_f32_e32 v31, v31
	v_exp_f32_e32 v29, v29
	v_pk_mul_f32 v[18:19], v[18:19], v[24:25]
	v_pk_mul_f32 v[20:21], v[20:21], v[26:27]
	v_pk_add_f32 v[30:31], v[30:31], 1.0 op_sel_hi:[1,0]
	v_pk_add_f32 v[28:29], v[28:29], 1.0 op_sel_hi:[1,0]
	v_rcp_f32_e32 v30, v30
	v_rcp_f32_e32 v31, v31
	v_rcp_f32_e32 v28, v28
	v_rcp_f32_e32 v29, v29
	v_pk_mul_f32 v[18:19], v[18:19], v[30:31]
	s_nop 0
	v_cvt_pk_bf16_f32 v24, v18, v19
	v_pk_mul_f32 v[20:21], v[20:21], v[28:29]
	s_nop 0
	v_cvt_pk_bf16_f32 v25, v20, v21
	global_store_dwordx4 v[112:113], v[22:25], off offset:256
	s_nop 0
	s_waitcnt vmcnt(3)
	v_lshlrev_b32_e32 v30, 16, v214
	v_and_b32_e32 v31, 0xffff0000, v214
	v_lshlrev_b32_e32 v18, 16, v215
	v_and_b32_e32 v19, 0xffff0000, v215
	s_waitcnt vmcnt(2)
	v_lshlrev_b32_e32 v32, 16, v218
	v_and_b32_e32 v33, 0xffff0000, v218
	v_lshlrev_b32_e32 v22, 16, v219
	v_and_b32_e32 v23, 0xffff0000, v219
	v_pk_fma_f32 v[30:31], v[66:67], v[30:31], v[70:71]
	v_pk_fma_f32 v[18:19], v[68:69], v[18:19], v[72:73]
	s_waitcnt vmcnt(1)
	s_mov_b32 s100, 989440
	s_mov_b32 s101, 0
	v_lshl_add_u64 v[250:251], v[246:247], 0, s[100:101]
	s_mov_b32 s100, 995584
	v_lshl_add_u64 v[248:249], v[246:247], 0, s[100:101]
	global_load_dwordx4 v[226:229], v[250:251], off offset:-3584
	global_load_dwordx4 v[230:233], v[250:251], off offset:2048
	global_load_dwordx4 v[248:251], v[248:249], off offset:1536
	v_lshlrev_b32_e32 v34, 16, v222
	v_and_b32_e32 v35, 0xffff0000, v222
	v_lshlrev_b32_e32 v26, 16, v223
	v_and_b32_e32 v27, 0xffff0000, v223
	v_pk_fma_f32 v[18:19], v[64:65], v[22:23], v[18:19]
	v_pk_fma_f32 v[22:23], v[62:63], v[32:33], v[30:31]
	v_pk_fma_f32 v[18:19], v[60:61], v[26:27], v[18:19]
	v_pk_fma_f32 v[22:23], v[58:59], v[34:35], v[22:23]
	v_pk_mul_f32 v[26:27], v[18:19], v[18:19]
	v_pk_mul_f32 v[30:31], v[22:23], v[22:23]
	v_pk_fma_f32 v[26:27], v[26:27], s[86:87], v[162:163] op_sel_hi:[1,0,0] neg_lo:[1,0,0] neg_hi:[1,0,0]
	v_pk_fma_f32 v[30:31], v[30:31], s[86:87], v[162:163] op_sel_hi:[1,0,0] neg_lo:[1,0,0] neg_hi:[1,0,0]
	v_pk_mul_f32 v[26:27], v[18:19], v[26:27]
	v_pk_mul_f32 v[30:31], v[22:23], v[30:31]
	v_exp_f32_e32 v26, v26
	v_exp_f32_e32 v30, v30
	v_exp_f32_e32 v31, v31
	v_exp_f32_e32 v27, v27
	v_pk_mul_f32 v[14:15], v[14:15], v[22:23]
	v_pk_mul_f32 v[16:17], v[16:17], v[18:19]
	v_pk_add_f32 v[30:31], v[30:31], 1.0 op_sel_hi:[1,0]
	v_pk_add_f32 v[26:27], v[26:27], 1.0 op_sel_hi:[1,0]
	v_rcp_f32_e32 v30, v30
	v_rcp_f32_e32 v31, v31
	v_rcp_f32_e32 v26, v26
	v_rcp_f32_e32 v27, v27
	v_lshlrev_b32_e32 v18, 16, v217
	v_pk_mul_f32 v[14:15], v[14:15], v[30:31]
	v_and_b32_e32 v19, 0xffff0000, v217
	v_pk_mul_f32 v[16:17], v[16:17], v[26:27]
	v_cvt_pk_bf16_f32 v14, v14, v15
	v_cvt_pk_bf16_f32 v15, v16, v17
	v_lshlrev_b32_e32 v16, 16, v216
	v_and_b32_e32 v17, 0xffff0000, v216
	v_lshlrev_b32_e32 v20, 16, v220
	v_and_b32_e32 v21, 0xffff0000, v220
	v_lshlrev_b32_e32 v22, 16, v221
	v_and_b32_e32 v23, 0xffff0000, v221
	v_pk_fma_f32 v[16:17], v[50:51], v[16:17], v[54:55]
	v_pk_fma_f32 v[18:19], v[52:53], v[18:19], v[56:57]
	v_lshlrev_b32_e32 v24, 16, v224
	v_and_b32_e32 v25, 0xffff0000, v224
	v_lshlrev_b32_e32 v26, 16, v225
	v_and_b32_e32 v27, 0xffff0000, v225
	v_pk_fma_f32 v[18:19], v[48:49], v[22:23], v[18:19]
	v_pk_fma_f32 v[16:17], v[46:47], v[20:21], v[16:17]
	v_pk_fma_f32 v[18:19], v[44:45], v[26:27], v[18:19]
	v_pk_fma_f32 v[16:17], v[42:43], v[24:25], v[16:17]
	v_pk_mul_f32 v[20:21], v[18:19], v[18:19]
	v_pk_mul_f32 v[22:23], v[16:17], v[16:17]
	v_pk_fma_f32 v[20:21], v[20:21], s[86:87], v[162:163] op_sel_hi:[1,0,0] neg_lo:[1,0,0] neg_hi:[1,0,0]
	v_pk_fma_f32 v[22:23], v[22:23], s[86:87], v[162:163] op_sel_hi:[1,0,0] neg_lo:[1,0,0] neg_hi:[1,0,0]
	v_pk_mul_f32 v[20:21], v[18:19], v[20:21]
	v_pk_mul_f32 v[22:23], v[16:17], v[22:23]
	v_exp_f32_e32 v20, v20
	v_exp_f32_e32 v22, v22
	v_exp_f32_e32 v23, v23
	v_exp_f32_e32 v21, v21
	v_pk_mul_f32 v[8:9], v[8:9], v[16:17]
	v_pk_mul_f32 v[10:11], v[10:11], v[18:19]
	v_pk_add_f32 v[22:23], v[22:23], 1.0 op_sel_hi:[1,0]
	v_pk_add_f32 v[20:21], v[20:21], 1.0 op_sel_hi:[1,0]
	v_rcp_f32_e32 v22, v22
	v_rcp_f32_e32 v23, v23
	v_rcp_f32_e32 v20, v20
	v_rcp_f32_e32 v21, v21
	v_pk_mul_f32 v[8:9], v[8:9], v[22:23]
	s_nop 0
	v_cvt_pk_bf16_f32 v16, v8, v9
	v_pk_mul_f32 v[10:11], v[10:11], v[20:21]
	s_nop 0
	v_cvt_pk_bf16_f32 v17, v10, v11
	global_store_dwordx4 v[104:105], v[14:17], off offset:256
	s_nop 0
	s_waitcnt vmcnt(1)
; __device__ __forceinline__ float bflo(unsigned u) { return __uint_as_float(u << 16); }
;     __device__ __forceinline__ void operator()(const f32x4 (&acc)[2][2][4][2], const Unit& u, int wr, int wc, int fr, int fq) const {
;     ...
;                     const int row = u.pm * BM + ai * HALF + wr * 64 + m * 16 + fr;
;                     const int t = row & (SEQ - 1);
;                     const bf16_t* gp = G + (size_t)row * DFF + col;
;                     const bool hasm = t > 0, hasn = t < SEQ - 1;
;                     u32x4 gm = *(const u32x4*)(gp - (hasm ? DFF : 0));
;                     const u32x4 g0 = *(const u32x4*)gp;
;                     u32x4 gn = *(const u32x4*)(gp + (hasn ? DFF : 0));
;                     const unsigned mm = hasm ? 0xffffffffu : 0u, mn = hasn ? 0xffffffffu : 0u;
;                     gm.x &= mm; gm.y &= mm; gm.z &= mm; gm.w &= mm; gn.x &= mn; gn.y &= mn; gn.z &= mn; gn.w &= mn;
;                     unsigned ow[4];
; #pragma unroll
;                     for (int n = 0; n < 2; ++n) {
;                         const unsigned m0 = n ? gm.z : gm.x, m1 = n ? gm.w : gm.y, c0 = n ? g0.z : g0.x, c1 = n ? g0.w : g0.y, n0 = n ? gn.z : gn.x, n1 = n ? gn.w : gn.y;
;                         const f32x4 fm = {bflo(m0), bfhi(m0), bflo(m1), bfhi(m1)}, f0 = {bflo(c0), bfhi(c0), bflo(c1), bfhi(c1)}, fn = {bflo(n0), bfhi(n0), bflo(n1), bfhi(n1)};
;                         const f32x4 gc = bb[n] + fm * w0[n] + f0 * w1[n] + fn * w2[n];
;                         const f32x4 a = acc[ai][bj][m][n];
;                         constexpr float C1 = -2.0f * LOG2E * 0.7978845608028654f, C2 = C1 * 0.044715f;
;                         const f32x4 arg = gc * ((gc * gc) * C2 + C1);
;                         const f32x4 den = (f32x4){__builtin_amdgcn_exp2f(arg[0]), __builtin_amdgcn_exp2f(arg[1]), __builtin_amdgcn_exp2f(arg[2]), __builtin_amdgcn_exp2f(arg[3])} + 1.0f;
;                         const f32x4 rc = {__builtin_amdgcn_rcpf(den[0]), __builtin_amdgcn_rcpf(den[1]), __builtin_amdgcn_rcpf(den[2]), __builtin_amdgcn_rcpf(den[3])};
;                         const f32x4 o = (gc * a) * rc;
;                         ow[2 * n] = pk2(o[0], o[1]); ow[2 * n + 1] = pk2(o[2], o[3]);
;                     }
;                     *(u32x4*)(H + (size_t)row * DFF + col) = (u32x4){ow[0], ow[1], ow[2], ow[3]};
	v_cndmask_b32_e64 v12, v248, 0, vcc
	v_cndmask_b32_e64 v25, v249, 0, vcc
	v_lshlrev_b32_e32 v18, 16, v226
	v_and_b32_e32 v19, 0xffff0000, v226
	v_lshlrev_b32_e32 v8, 16, v227
	v_and_b32_e32 v9, 0xffff0000, v227
	v_cndmask_b32_e64 v26, v250, 0, vcc
	v_cndmask_b32_e64 v27, v251, 0, vcc
	v_lshlrev_b32_e32 v20, 16, v230
	v_and_b32_e32 v21, 0xffff0000, v230
	v_lshlrev_b32_e32 v14, 16, v231
	v_and_b32_e32 v15, 0xffff0000, v231
	v_pk_fma_f32 v[18:19], v[66:67], v[18:19], v[70:71]
	v_pk_fma_f32 v[8:9], v[68:69], v[8:9], v[72:73]
	v_lshlrev_b32_e32 v22, 16, v12
	v_and_b32_e32 v23, 0xffff0000, v12
	v_lshlrev_b32_e32 v24, 16, v25
	v_and_b32_e32 v25, 0xffff0000, v25
	v_pk_fma_f32 v[8:9], v[64:65], v[14:15], v[8:9]
	v_pk_fma_f32 v[14:15], v[62:63], v[20:21], v[18:19]
	v_pk_fma_f32 v[8:9], v[60:61], v[24:25], v[8:9]
	v_pk_fma_f32 v[14:15], v[58:59], v[22:23], v[14:15]
	v_pk_mul_f32 v[18:19], v[8:9], v[8:9]
	v_pk_mul_f32 v[20:21], v[14:15], v[14:15]
	v_pk_fma_f32 v[18:19], v[18:19], s[86:87], v[162:163] op_sel_hi:[1,0,0] neg_lo:[1,0,0] neg_hi:[1,0,0]
	v_pk_fma_f32 v[20:21], v[20:21], s[86:87], v[162:163] op_sel_hi:[1,0,0] neg_lo:[1,0,0] neg_hi:[1,0,0]
	v_pk_mul_f32 v[18:19], v[8:9], v[18:19]
	v_pk_mul_f32 v[20:21], v[14:15], v[20:21]
	v_exp_f32_e32 v18, v18
	v_exp_f32_e32 v20, v20
	v_exp_f32_e32 v21, v21
	v_exp_f32_e32 v19, v19
	v_pk_mul_f32 v[4:5], v[4:5], v[14:15]
	v_pk_mul_f32 v[6:7], v[6:7], v[8:9]
	v_pk_add_f32 v[20:21], v[20:21], 1.0 op_sel_hi:[1,0]
	v_pk_add_f32 v[18:19], v[18:19], 1.0 op_sel_hi:[1,0]
	v_rcp_f32_e32 v20, v20
	v_rcp_f32_e32 v21, v21
	v_rcp_f32_e32 v18, v18
	v_rcp_f32_e32 v19, v19
	v_lshlrev_b32_e32 v8, 16, v229
	v_pk_mul_f32 v[4:5], v[4:5], v[20:21]
	v_and_b32_e32 v9, 0xffff0000, v229
	v_pk_mul_f32 v[6:7], v[6:7], v[18:19]
	v_cvt_pk_bf16_f32 v4, v4, v5
	v_cvt_pk_bf16_f32 v5, v6, v7
	v_lshlrev_b32_e32 v6, 16, v228
	v_and_b32_e32 v7, 0xffff0000, v228
	v_lshlrev_b32_e32 v10, 16, v232
	v_and_b32_e32 v11, 0xffff0000, v232
	v_lshlrev_b32_e32 v14, 16, v233
	v_and_b32_e32 v15, 0xffff0000, v233
	v_pk_fma_f32 v[6:7], v[50:51], v[6:7], v[54:55]
	v_pk_fma_f32 v[8:9], v[52:53], v[8:9], v[56:57]
	v_lshlrev_b32_e32 v16, 16, v26
	v_and_b32_e32 v17, 0xffff0000, v26
	v_lshlrev_b32_e32 v18, 16, v27
	v_and_b32_e32 v19, 0xffff0000, v27
	v_pk_fma_f32 v[8:9], v[48:49], v[14:15], v[8:9]
	v_pk_fma_f32 v[6:7], v[46:47], v[10:11], v[6:7]
	v_pk_fma_f32 v[8:9], v[44:45], v[18:19], v[8:9]
	v_pk_fma_f32 v[6:7], v[42:43], v[16:17], v[6:7]
	v_pk_mul_f32 v[10:11], v[8:9], v[8:9]
	v_pk_mul_f32 v[14:15], v[6:7], v[6:7]
	v_pk_fma_f32 v[10:11], v[10:11], s[86:87], v[162:163] op_sel_hi:[1,0,0] neg_lo:[1,0,0] neg_hi:[1,0,0]
	v_pk_fma_f32 v[14:15], v[14:15], s[86:87], v[162:163] op_sel_hi:[1,0,0] neg_lo:[1,0,0] neg_hi:[1,0,0]
	v_pk_mul_f32 v[10:11], v[8:9], v[10:11]
	v_pk_mul_f32 v[14:15], v[6:7], v[14:15]
	v_exp_f32_e32 v10, v10
	v_exp_f32_e32 v14, v14
	v_exp_f32_e32 v15, v15
	v_exp_f32_e32 v11, v11
	v_pk_mul_f32 v[0:1], v[0:1], v[6:7]
	v_pk_mul_f32 v[2:3], v[2:3], v[8:9]
	v_pk_add_f32 v[14:15], v[14:15], 1.0 op_sel_hi:[1,0]
	v_pk_add_f32 v[10:11], v[10:11], 1.0 op_sel_hi:[1,0]
	v_rcp_f32_e32 v14, v14
	v_rcp_f32_e32 v15, v15
	v_rcp_f32_e32 v10, v10
	v_rcp_f32_e32 v11, v11
	s_andn2_b64 vcc, exec, s[2:3]
	v_pk_mul_f32 v[0:1], v[0:1], v[14:15]
	v_pk_mul_f32 v[2:3], v[2:3], v[10:11]
	v_cvt_pk_bf16_f32 v6, v0, v1
	v_cvt_pk_bf16_f32 v7, v2, v3
	global_store_dwordx4 v[102:103], v[4:7], off offset:256
	s_cbranch_vccnz .LBB0_1108
	s_andn2_b64 vcc, exec, s[22:23]
	s_cbranch_vccnz .LBB0_1107
	s_barrier
	s_branch .LBB0_1107

;     __device__ __forceinline__ void rowstat(const f32x4 (&v)[2][2][4][2], const Unit& u, int wr, int wc, int fr, int fq, float* slot, unsigned* cnt) const {
;     ...
;         for (int ai = 0; ai < 2; ++ai)
; #pragma unroll
;             for (int m = 0; m < 4; ++m) {
;                 float ss = 0.f;
; #pragma unroll
;                 for (int bj = 0; bj < 2; ++bj)
; #pragma unroll
;                     for (int n = 0; n < 2; ++n) { const f32x4 x = v[ai][bj][m][n]; ss += (x[0] * x[0] + x[1] * x[1]) + (x[2] * x[2] + x[3] * x[3]); }
;                 ss += __shfl_xor(ss, 16); ss += __shfl_xor(ss, 32);
;                 if (fq == 0) Pp[(ai * HALF + wr * 64 + m * 16 + fr) * 4 + wc] = ss;
.LBB0_1191:
	v_and_b32_e32 v131, 64, v238
	v_xor_b32_e32 v130, 16, v238
	v_add_u32_e32 v131, 64, v131
	v_cmp_lt_i32_e32 vcc, v130, v131
	s_nop 1
	v_mul_f32_e32 v132, v81, v81
	v_fmac_f32_e32 v132, v80, v80
	v_cndmask_b32_e32 v130, v238, v130, vcc
	v_lshlrev_b32_e32 v169, 2, v130
	v_mul_f32_e32 v130, v79, v79
	v_fmac_f32_e32 v130, v78, v78
	v_add_f32_e32 v130, v130, v132
	v_mul_f32_e32 v132, v107, v107
	v_mul_f32_e32 v133, v109, v109
	v_fmac_f32_e32 v132, v106, v106
	v_fmac_f32_e32 v133, v108, v108
	v_add_f32_e32 v132, v132, v133
	v_add_f32_e32 v130, v130, v132
	v_mul_f32_e32 v132, v103, v103
	v_mul_f32_e32 v133, v105, v105
	v_fmac_f32_e32 v132, v102, v102
	v_fmac_f32_e32 v133, v104, v104
	v_add_f32_e32 v132, v132, v133
	v_add_f32_e32 v130, v130, v132
	v_mul_f32_e32 v132, v35, v35
	v_mul_f32_e32 v133, v37, v37
	v_fmac_f32_e32 v132, v34, v34
	v_fmac_f32_e32 v133, v36, v36
	v_add_f32_e32 v132, v132, v133
	v_add_f32_e32 v130, v130, v132
	v_xor_b32_e32 v133, 32, v238
	v_cmp_lt_i32_e32 vcc, v133, v131
	s_nop 1
	v_cndmask_b32_e32 v131, v238, v133, vcc
	v_lshlrev_b32_e32 v170, 2, v131
	v_mov_b32_e32 v134, v130
	v_mul_f32_e32 v130, v75, v75
	v_mul_f32_e32 v131, v77, v77
	v_fmac_f32_e32 v130, v74, v74
	v_fmac_f32_e32 v131, v76, v76
	v_add_f32_e32 v130, v130, v131
	v_mul_f32_e32 v131, v99, v99
	v_mul_f32_e32 v132, v101, v101
	v_fmac_f32_e32 v131, v98, v98
	v_fmac_f32_e32 v132, v100, v100
	v_add_f32_e32 v131, v131, v132
	v_add_f32_e32 v130, v130, v131
	v_mul_f32_e32 v131, v95, v95
	v_mul_f32_e32 v132, v97, v97
	v_fmac_f32_e32 v131, v94, v94
	v_fmac_f32_e32 v132, v96, v96
	v_add_f32_e32 v131, v131, v132
	v_add_f32_e32 v130, v130, v131
	v_mul_f32_e32 v131, v31, v31
	v_mul_f32_e32 v132, v33, v33
	v_fmac_f32_e32 v131, v30, v30
	v_fmac_f32_e32 v132, v32, v32
	v_add_f32_e32 v131, v131, v132
	v_add_f32_e32 v130, v130, v131
	v_mov_b32_e32 v135, v130
	v_mul_f32_e32 v130, v71, v71
	v_mul_f32_e32 v131, v73, v73
	v_fmac_f32_e32 v130, v70, v70
	v_fmac_f32_e32 v131, v72, v72
	v_add_f32_e32 v130, v130, v131
	v_mul_f32_e32 v131, v87, v87
	v_mul_f32_e32 v132, v89, v89
	v_fmac_f32_e32 v131, v86, v86
	v_fmac_f32_e32 v132, v88, v88
	v_add_f32_e32 v131, v131, v132
	v_add_f32_e32 v130, v130, v131
	v_mul_f32_e32 v131, v91, v91
	v_mul_f32_e32 v132, v93, v93
	v_fmac_f32_e32 v131, v90, v90
	v_fmac_f32_e32 v132, v92, v92
	v_add_f32_e32 v131, v131, v132
	v_add_f32_e32 v130, v130, v131
	v_mul_f32_e32 v131, v27, v27
	v_mul_f32_e32 v132, v29, v29
	v_fmac_f32_e32 v131, v26, v26
	v_fmac_f32_e32 v132, v28, v28
	v_add_f32_e32 v131, v131, v132
	v_add_f32_e32 v130, v130, v131
	v_mov_b32_e32 v136, v130
	v_mul_f32_e32 v130, v63, v63
	v_mul_f32_e32 v131, v65, v65
	v_fmac_f32_e32 v130, v62, v62
	v_fmac_f32_e32 v131, v64, v64
	v_add_f32_e32 v130, v130, v131
	v_mul_f32_e32 v131, v123, v123
	v_mul_f32_e32 v132, v125, v125
	v_fmac_f32_e32 v131, v122, v122
	v_fmac_f32_e32 v132, v124, v124
	v_add_f32_e32 v131, v131, v132
	v_add_f32_e32 v130, v130, v131
	v_mul_f32_e32 v131, v83, v83
	v_mul_f32_e32 v132, v85, v85
	v_fmac_f32_e32 v131, v82, v82
	v_fmac_f32_e32 v132, v84, v84
	v_add_f32_e32 v131, v131, v132
	v_add_f32_e32 v130, v130, v131
	v_mul_f32_e32 v131, v23, v23
	v_mul_f32_e32 v132, v25, v25
	v_fmac_f32_e32 v131, v22, v22
	v_fmac_f32_e32 v132, v24, v24
	v_add_f32_e32 v131, v131, v132
	v_add_f32_e32 v130, v130, v131
	v_mov_b32_e32 v137, v130
	v_mul_f32_e32 v130, v59, v59
	v_mul_f32_e32 v131, v61, v61
	v_fmac_f32_e32 v130, v58, v58
	v_fmac_f32_e32 v131, v60, v60
	v_add_f32_e32 v130, v130, v131
	v_mul_f32_e32 v131, v119, v119
	v_mul_f32_e32 v132, v121, v121
	v_fmac_f32_e32 v131, v118, v118
	v_fmac_f32_e32 v132, v120, v120
	v_add_f32_e32 v131, v131, v132
	v_add_f32_e32 v130, v130, v131
	v_mul_f32_e32 v131, v67, v67
	v_mul_f32_e32 v132, v69, v69
	v_fmac_f32_e32 v131, v66, v66
	v_fmac_f32_e32 v132, v68, v68
	v_add_f32_e32 v131, v131, v132
	v_add_f32_e32 v130, v130, v131
	v_mul_f32_e32 v131, v15, v15
	v_mul_f32_e32 v132, v17, v17
	v_fmac_f32_e32 v131, v14, v14
	v_fmac_f32_e32 v132, v16, v16
	v_add_f32_e32 v131, v131, v132
	v_add_f32_e32 v130, v130, v131
	v_mov_b32_e32 v138, v130
	v_mul_f32_e32 v130, v55, v55
	v_mul_f32_e32 v131, v57, v57
	v_fmac_f32_e32 v130, v54, v54
	v_fmac_f32_e32 v131, v56, v56
	v_add_f32_e32 v130, v130, v131
	v_mul_f32_e32 v131, v127, v127
	v_mul_f32_e32 v132, v129, v129
	v_fmac_f32_e32 v131, v126, v126
	v_fmac_f32_e32 v132, v128, v128
	v_add_f32_e32 v131, v131, v132
	v_add_f32_e32 v130, v130, v131
	v_mul_f32_e32 v131, v43, v43
	v_mul_f32_e32 v132, v45, v45
	v_fmac_f32_e32 v131, v42, v42
	v_fmac_f32_e32 v132, v44, v44
	v_add_f32_e32 v131, v131, v132
	v_add_f32_e32 v130, v130, v131
	v_mul_f32_e32 v131, v9, v9
	v_mul_f32_e32 v132, v11, v11
	v_fmac_f32_e32 v131, v8, v8
	v_fmac_f32_e32 v132, v10, v10
	v_add_f32_e32 v131, v131, v132
	v_add_f32_e32 v130, v130, v131
	v_mov_b32_e32 v139, v130
	v_mul_f32_e32 v130, v51, v51
	v_mul_f32_e32 v131, v53, v53
	v_fmac_f32_e32 v130, v50, v50
	v_fmac_f32_e32 v131, v52, v52
	v_add_f32_e32 v130, v130, v131
	v_mul_f32_e32 v131, v115, v115
	v_mul_f32_e32 v132, v117, v117
	v_fmac_f32_e32 v131, v114, v114
	v_fmac_f32_e32 v132, v116, v116
	v_add_f32_e32 v131, v131, v132
	v_add_f32_e32 v130, v130, v131
	v_mul_f32_e32 v131, v39, v39
	v_mul_f32_e32 v132, v41, v41
	v_fmac_f32_e32 v131, v38, v38
	v_fmac_f32_e32 v132, v40, v40
	v_add_f32_e32 v131, v131, v132
	v_add_f32_e32 v130, v130, v131
	v_mul_f32_e32 v131, v5, v5
	v_mul_f32_e32 v132, v7, v7
	v_fmac_f32_e32 v131, v4, v4
	v_fmac_f32_e32 v132, v6, v6
	v_add_f32_e32 v131, v131, v132
	v_add_f32_e32 v130, v130, v131
	v_mov_b32_e32 v140, v130
	v_mul_f32_e32 v130, v47, v47
	v_mul_f32_e32 v131, v49, v49
	v_fmac_f32_e32 v130, v46, v46
	v_fmac_f32_e32 v131, v48, v48
	v_add_f32_e32 v130, v130, v131
	v_mul_f32_e32 v131, v111, v111
	v_mul_f32_e32 v132, v113, v113
	v_fmac_f32_e32 v131, v110, v110
	v_fmac_f32_e32 v132, v112, v112
	v_add_f32_e32 v131, v131, v132
	v_add_f32_e32 v130, v130, v131
	v_mul_f32_e32 v131, v19, v19
	v_mul_f32_e32 v132, v21, v21
	v_fmac_f32_e32 v131, v18, v18
	v_fmac_f32_e32 v132, v20, v20
	v_add_f32_e32 v131, v131, v132
	v_add_f32_e32 v130, v130, v131
	v_mul_f32_e32 v131, v1, v1
	v_mul_f32_e32 v132, v3, v3
	v_fmac_f32_e32 v131, v0, v0
	v_fmac_f32_e32 v132, v2, v2
	v_add_f32_e32 v131, v131, v132
	v_add_f32_e32 v130, v130, v131
	v_mov_b32_e32 v141, v130
	ds_bpermute_b32 v142, v169, v134
	ds_bpermute_b32 v143, v169, v135
	ds_bpermute_b32 v144, v169, v136
	ds_bpermute_b32 v145, v169, v137
	ds_bpermute_b32 v146, v169, v138
	ds_bpermute_b32 v147, v169, v139
	ds_bpermute_b32 v148, v169, v140
	ds_bpermute_b32 v149, v169, v141
	s_waitcnt lgkmcnt(0)
;     __device__ __forceinline__ void rowstat(const f32x4 (&v)[2][2][4][2], const Unit& u, int wr, int wc, int fr, int fq, float* slot, unsigned* cnt) const {
;     ...
;                 ss += __shfl_xor(ss, 16); ss += __shfl_xor(ss, 32);
;                 if (fq == 0) Pp[(ai * HALF + wr * 64 + m * 16 + fr) * 4 + wc] = ss;
	v_add_f32_e32 v134, v134, v142
	v_add_f32_e32 v135, v135, v143
	v_add_f32_e32 v136, v136, v144
	v_add_f32_e32 v137, v137, v145
	v_add_f32_e32 v138, v138, v146
	v_add_f32_e32 v139, v139, v147
	v_add_f32_e32 v140, v140, v148
	v_add_f32_e32 v141, v141, v149
	ds_bpermute_b32 v142, v170, v134
	ds_bpermute_b32 v143, v170, v135
	ds_bpermute_b32 v144, v170, v136
	ds_bpermute_b32 v145, v170, v137
	ds_bpermute_b32 v146, v170, v138
	ds_bpermute_b32 v147, v170, v139
	ds_bpermute_b32 v148, v170, v140
	ds_bpermute_b32 v149, v170, v141
	s_and_saveexec_b64 s[6:7], s[0:1]
	s_cbranch_execz .Lrs_skip_2
	s_waitcnt lgkmcnt(0)
	v_add_f32_e32 v134, v134, v142
	v_add_f32_e32 v135, v135, v143
	v_add_f32_e32 v136, v136, v144
	v_add_f32_e32 v137, v137, v145
	v_add_f32_e32 v138, v138, v146
	v_add_f32_e32 v139, v139, v147
	v_add_f32_e32 v140, v140, v148
	v_add_f32_e32 v141, v141, v149
	ds_write_b32 v168, v134
	ds_write_b32 v168, v135 offset:256
	ds_write_b32 v168, v136 offset:512
	ds_write_b32 v168, v137 offset:768
	ds_write_b32 v168, v138 offset:2048
	ds_write_b32 v168, v139 offset:2304
	ds_write_b32 v168, v140 offset:2560
	ds_write_b32 v168, v141 offset:2816

; #define LAS __attribute__((address_space(3)))
;     __device__ __forceinline__ void operator()(f32x4 (&acc)[2][2][4][2], const Unit& u, int wr, int wc, int fr, int fq) const {
;         const LAS float* S = (const LAS float*)(xl + 4096);
;         const float* md = modb + (size_t)(u.pm >> 4) * 6144;
;         rowstat(acc, u, wr, wc, fr, fq, slot1, cnt1);
; #pragma unroll
;         for (int bj = 0; bj < 2; ++bj)
; #pragma unroll
;             for (int n = 0; n < 2; ++n) {
;                 const int col = u.pn * BM + bj * HALF + wc * 32 + 8 * fq + 4 * n;
;                 const f32x4 gg = *(const f32x4*)(md + gate_off + col) * *(const f32x4*)(gpost + col);
; #pragma unroll
;                 for (int ai = 0; ai < 2; ++ai)
; #pragma unroll
;                     for (int m = 0; m < 4; ++m) {
;                         const int rl = ai * HALF + wr * 64 + m * 16 + fr; const size_t off = (size_t)(u.pm * BM + rl) * DM + col;
;                         const f32x4 xv = *(const f32x4*)(xin + off);
;                         const f32x4 xn = xv + gg * (acc[ai][bj][m][n] * S[rl]);
.LBB0_1220:
	s_or_b64 exec, exec, s[8:9]
	s_ashr_i32 s8, s96, 4
	s_mul_hi_i32 s9, s8, 0x6000
	s_mulk_i32 s8, 0x6000
	s_add_u32 s49, s25, s8
	s_addc_u32 s50, s29, s9
	v_lshl_or_b32 v184, s82, 8, v221
	s_lshl_b32 s8, s96, 8
	s_add_u32 vcc_lo, s49, 0x5000
	v_ashrrev_i32_e32 v185, 31, v184
	s_addc_u32 vcc_hi, s50, 0
	v_lshlrev_b64 v[194:195], 2, v[184:185]
	s_waitcnt vmcnt(0) lgkmcnt(0)
	s_barrier
	s_waitcnt lgkmcnt(0)
	v_lshl_add_u64 v[196:197], vcc, 0, v[194:195]
	v_lshl_add_u64 v[198:199], s[16:17], 0, v[194:195]
	global_load_dwordx4 v[130:133], v[196:197], off
	global_load_dwordx4 v[134:137], v[198:199], off
	v_add_u32_e32 v204, s8, v205
	v_add_u32_e32 v208, s8, v241
	v_add_u32_e32 v220, s8, v229
	v_add_u32_e32 v222, s8, v231
	v_add_u32_e32 v228, s8, v240
	v_add_u32_e32 v230, s8, v242
	v_add_u32_e32 v171, s8, v243
	v_add_u32_e32 v176, s8, v244
	v_lshl_add_u32 v204, v204, 10, v184
	v_lshl_add_u32 v208, v208, 10, v184
	v_lshl_add_u32 v220, v220, 10, v184
	v_lshl_add_u32 v222, v222, 10, v184
	v_lshl_add_u32 v228, v228, 10, v184
	v_lshl_add_u32 v230, v230, 10, v184
	v_lshl_add_u32 v171, v171, 10, v184
	v_lshl_add_u32 v176, v176, 10, v184
	v_lshlrev_b32_e32 v204, 2, v204
	v_lshlrev_b32_e32 v208, 2, v208
	v_lshlrev_b32_e32 v220, 2, v220
	v_lshlrev_b32_e32 v222, 2, v222
	v_lshlrev_b32_e32 v228, 2, v228
	v_lshlrev_b32_e32 v230, 2, v230
	v_lshlrev_b32_e32 v171, 2, v171
	v_lshlrev_b32_e32 v176, 2, v176
	global_load_dwordx4 v[138:141], v204, s[60:61]
	global_load_dwordx4 v[142:145], v208, s[60:61]
	global_load_dwordx4 v[146:149], v220, s[60:61]
	global_load_dwordx4 v[172:175], v222, s[60:61]
	global_load_dwordx4 v[200:203], v228, s[60:61]
	global_load_dwordx4 v[210:213], v230, s[60:61]
	global_load_dwordx4 v[214:217], v171, s[60:61]
	global_load_dwordx4 v[224:227], v176, s[60:61]
	ds_read_b32 v164, v246
	ds_read_b32 v178, v247
	ds_read_b32 v180, v248
	ds_read_b32 v182, v249
	ds_read_b32 v190, v250
	ds_read_b32 v192, v251
	ds_read_b32 v206, v236
	ds_read_b32 v218, v166
	s_waitcnt lgkmcnt(7)
	v_pk_mul_f32 v[78:79], v[78:79], v[164:165] op_sel_hi:[1,0]
	v_pk_mul_f32 v[80:81], v[80:81], v[164:165] op_sel_hi:[1,0]
	v_pk_mul_f32 v[106:107], v[106:107], v[164:165] op_sel_hi:[1,0]
	v_pk_mul_f32 v[108:109], v[108:109], v[164:165] op_sel_hi:[1,0]
	v_pk_mul_f32 v[102:103], v[102:103], v[164:165] op_sel_hi:[1,0]
	v_pk_mul_f32 v[104:105], v[104:105], v[164:165] op_sel_hi:[1,0]
	v_pk_mul_f32 v[34:35], v[34:35], v[164:165] op_sel_hi:[1,0]
	v_pk_mul_f32 v[36:37], v[36:37], v[164:165] op_sel_hi:[1,0]
	s_waitcnt lgkmcnt(6)
	v_pk_mul_f32 v[74:75], v[74:75], v[178:179] op_sel_hi:[1,0]
	v_pk_mul_f32 v[76:77], v[76:77], v[178:179] op_sel_hi:[1,0]
	v_pk_mul_f32 v[98:99], v[98:99], v[178:179] op_sel_hi:[1,0]
	v_pk_mul_f32 v[100:101], v[100:101], v[178:179] op_sel_hi:[1,0]
	v_pk_mul_f32 v[94:95], v[94:95], v[178:179] op_sel_hi:[1,0]
	v_pk_mul_f32 v[96:97], v[96:97], v[178:179] op_sel_hi:[1,0]
	v_pk_mul_f32 v[30:31], v[30:31], v[178:179] op_sel_hi:[1,0]
	v_pk_mul_f32 v[32:33], v[32:33], v[178:179] op_sel_hi:[1,0]
	s_waitcnt lgkmcnt(5)
	v_pk_mul_f32 v[70:71], v[70:71], v[180:181] op_sel_hi:[1,0]
	v_pk_mul_f32 v[72:73], v[72:73], v[180:181] op_sel_hi:[1,0]
	v_pk_mul_f32 v[86:87], v[86:87], v[180:181] op_sel_hi:[1,0]
	v_pk_mul_f32 v[88:89], v[88:89], v[180:181] op_sel_hi:[1,0]
	v_pk_mul_f32 v[90:91], v[90:91], v[180:181] op_sel_hi:[1,0]
	v_pk_mul_f32 v[92:93], v[92:93], v[180:181] op_sel_hi:[1,0]
	v_pk_mul_f32 v[26:27], v[26:27], v[180:181] op_sel_hi:[1,0]
	v_pk_mul_f32 v[28:29], v[28:29], v[180:181] op_sel_hi:[1,0]
	s_waitcnt lgkmcnt(4)
	v_pk_mul_f32 v[62:63], v[62:63], v[182:183] op_sel_hi:[1,0]
	v_pk_mul_f32 v[64:65], v[64:65], v[182:183] op_sel_hi:[1,0]
	v_pk_mul_f32 v[122:123], v[122:123], v[182:183] op_sel_hi:[1,0]
	v_pk_mul_f32 v[124:125], v[124:125], v[182:183] op_sel_hi:[1,0]
	v_pk_mul_f32 v[82:83], v[82:83], v[182:183] op_sel_hi:[1,0]
	v_pk_mul_f32 v[84:85], v[84:85], v[182:183] op_sel_hi:[1,0]
	v_pk_mul_f32 v[22:23], v[22:23], v[182:183] op_sel_hi:[1,0]
	v_pk_mul_f32 v[24:25], v[24:25], v[182:183] op_sel_hi:[1,0]
	s_waitcnt lgkmcnt(3)
	v_pk_mul_f32 v[58:59], v[58:59], v[190:191] op_sel_hi:[1,0]
	v_pk_mul_f32 v[60:61], v[60:61], v[190:191] op_sel_hi:[1,0]
	v_pk_mul_f32 v[118:119], v[118:119], v[190:191] op_sel_hi:[1,0]
	v_pk_mul_f32 v[120:121], v[120:121], v[190:191] op_sel_hi:[1,0]
	v_pk_mul_f32 v[66:67], v[66:67], v[190:191] op_sel_hi:[1,0]
	v_pk_mul_f32 v[68:69], v[68:69], v[190:191] op_sel_hi:[1,0]
	v_pk_mul_f32 v[14:15], v[14:15], v[190:191] op_sel_hi:[1,0]
	v_pk_mul_f32 v[16:17], v[16:17], v[190:191] op_sel_hi:[1,0]
	s_waitcnt lgkmcnt(2)
	v_pk_mul_f32 v[54:55], v[54:55], v[192:193] op_sel_hi:[1,0]
	v_pk_mul_f32 v[56:57], v[56:57], v[192:193] op_sel_hi:[1,0]
	v_pk_mul_f32 v[126:127], v[126:127], v[192:193] op_sel_hi:[1,0]
	v_pk_mul_f32 v[128:129], v[128:129], v[192:193] op_sel_hi:[1,0]
	v_pk_mul_f32 v[42:43], v[42:43], v[192:193] op_sel_hi:[1,0]
	v_pk_mul_f32 v[44:45], v[44:45], v[192:193] op_sel_hi:[1,0]
	v_pk_mul_f32 v[8:9], v[8:9], v[192:193] op_sel_hi:[1,0]
	v_pk_mul_f32 v[10:11], v[10:11], v[192:193] op_sel_hi:[1,0]
	s_waitcnt lgkmcnt(1)
	v_pk_mul_f32 v[50:51], v[50:51], v[206:207] op_sel_hi:[1,0]
	v_pk_mul_f32 v[52:53], v[52:53], v[206:207] op_sel_hi:[1,0]
	v_pk_mul_f32 v[114:115], v[114:115], v[206:207] op_sel_hi:[1,0]
	v_pk_mul_f32 v[116:117], v[116:117], v[206:207] op_sel_hi:[1,0]
	v_pk_mul_f32 v[38:39], v[38:39], v[206:207] op_sel_hi:[1,0]
	v_pk_mul_f32 v[40:41], v[40:41], v[206:207] op_sel_hi:[1,0]
	v_pk_mul_f32 v[4:5], v[4:5], v[206:207] op_sel_hi:[1,0]
	v_pk_mul_f32 v[6:7], v[6:7], v[206:207] op_sel_hi:[1,0]
	s_waitcnt lgkmcnt(0)
;     __device__ __forceinline__ void operator()(f32x4 (&acc)[2][2][4][2], const Unit& u, int wr, int wc, int fr, int fq) const {
;     ...
;             for (int n = 0; n < 2; ++n) {
;                 const int col = u.pn * BM + bj * HALF + wc * 32 + 8 * fq + 4 * n;
;                 const f32x4 gg = *(const f32x4*)(md + gate_off + col) * *(const f32x4*)(gpost + col);
; #pragma unroll
;                 for (int ai = 0; ai < 2; ++ai)
; #pragma unroll
;                     for (int m = 0; m < 4; ++m) {
;                         const int rl = ai * HALF + wr * 64 + m * 16 + fr; const size_t off = (size_t)(u.pm * BM + rl) * DM + col;
;                         const f32x4 xv = *(const f32x4*)(xin + off);
;                         const f32x4 xn = xv + gg * (acc[ai][bj][m][n] * S[rl]);
;                         acc[ai][bj][m][n] = xn; *(f32x4*)(xout + off) = xn;
;                     }
	v_pk_mul_f32 v[46:47], v[46:47], v[218:219] op_sel_hi:[1,0]
	v_pk_mul_f32 v[48:49], v[48:49], v[218:219] op_sel_hi:[1,0]
	v_pk_mul_f32 v[110:111], v[110:111], v[218:219] op_sel_hi:[1,0]
	v_pk_mul_f32 v[112:113], v[112:113], v[218:219] op_sel_hi:[1,0]
	v_pk_mul_f32 v[18:19], v[18:19], v[218:219] op_sel_hi:[1,0]
	v_pk_mul_f32 v[20:21], v[20:21], v[218:219] op_sel_hi:[1,0]
	v_pk_mul_f32 v[0:1], v[0:1], v[218:219] op_sel_hi:[1,0]
	v_pk_mul_f32 v[2:3], v[2:3], v[218:219] op_sel_hi:[1,0]
	s_waitcnt vmcnt(8)
	v_pk_mul_f32 v[232:233], v[130:131], v[134:135]
	v_pk_mul_f32 v[234:235], v[132:133], v[136:137]
	global_load_dwordx4 v[130:133], v[196:197], off offset:16
	global_load_dwordx4 v[134:137], v[198:199], off offset:16
	s_waitcnt vmcnt(9)
	v_pk_fma_f32 v[80:81], v[234:235], v[80:81], v[140:141]
	v_pk_fma_f32 v[78:79], v[232:233], v[78:79], v[138:139]
	global_store_dwordx4 v204, v[78:81], s[60:61]
	global_load_dwordx4 v[138:141], v204, s[60:61] offset:16
	s_waitcnt vmcnt(10)
	v_pk_fma_f32 v[76:77], v[234:235], v[76:77], v[144:145]
	v_pk_fma_f32 v[74:75], v[232:233], v[74:75], v[142:143]
	global_store_dwordx4 v208, v[74:77], s[60:61]
	global_load_dwordx4 v[142:145], v208, s[60:61] offset:16
	s_waitcnt vmcnt(11)
	v_pk_fma_f32 v[72:73], v[234:235], v[72:73], v[148:149]
	v_pk_fma_f32 v[70:71], v[232:233], v[70:71], v[146:147]
	global_store_dwordx4 v220, v[70:73], s[60:61]
	global_load_dwordx4 v[146:149], v220, s[60:61] offset:16
	s_waitcnt vmcnt(12)
	v_pk_fma_f32 v[64:65], v[234:235], v[64:65], v[174:175]
	v_pk_fma_f32 v[62:63], v[232:233], v[62:63], v[172:173]
	global_store_dwordx4 v222, v[62:65], s[60:61]
	global_load_dwordx4 v[172:175], v222, s[60:61] offset:16
	s_waitcnt vmcnt(13)
	v_pk_fma_f32 v[60:61], v[234:235], v[60:61], v[202:203]
	v_pk_fma_f32 v[58:59], v[232:233], v[58:59], v[200:201]
	global_store_dwordx4 v228, v[58:61], s[60:61]
	global_load_dwordx4 v[200:203], v228, s[60:61] offset:16
	s_waitcnt vmcnt(14)
	v_pk_fma_f32 v[56:57], v[234:235], v[56:57], v[212:213]
	v_pk_fma_f32 v[54:55], v[232:233], v[54:55], v[210:211]
	global_store_dwordx4 v230, v[54:57], s[60:61]
	global_load_dwordx4 v[210:213], v230, s[60:61] offset:16
	s_waitcnt vmcnt(15)
	v_pk_fma_f32 v[52:53], v[234:235], v[52:53], v[216:217]
	v_pk_fma_f32 v[50:51], v[232:233], v[50:51], v[214:215]
	global_store_dwordx4 v171, v[50:53], s[60:61]
	global_load_dwordx4 v[214:217], v171, s[60:61] offset:16
	s_waitcnt vmcnt(16)
	v_pk_fma_f32 v[48:49], v[234:235], v[48:49], v[226:227]
	v_pk_fma_f32 v[46:47], v[232:233], v[46:47], v[224:225]
	global_store_dwordx4 v176, v[46:49], s[60:61]
	global_load_dwordx4 v[224:227], v176, s[60:61] offset:16
	s_waitcnt vmcnt(16)
	v_pk_mul_f32 v[186:187], v[130:131], v[134:135]
	v_pk_mul_f32 v[188:189], v[132:133], v[136:137]
	global_load_dwordx4 v[130:133], v[196:197], off offset:512
	global_load_dwordx4 v[134:137], v[198:199], off offset:512
	s_waitcnt vmcnt(16)
	v_pk_fma_f32 v[108:109], v[188:189], v[108:109], v[140:141]
	v_pk_fma_f32 v[106:107], v[186:187], v[106:107], v[138:139]
	global_store_dwordx4 v204, v[106:109], s[60:61] offset:16
	global_load_dwordx4 v[138:141], v204, s[60:61] offset:512
	s_waitcnt vmcnt(16)
	v_pk_fma_f32 v[100:101], v[188:189], v[100:101], v[144:145]
	v_pk_fma_f32 v[98:99], v[186:187], v[98:99], v[142:143]
	global_store_dwordx4 v208, v[98:101], s[60:61] offset:16
	global_load_dwordx4 v[142:145], v208, s[60:61] offset:512
	s_waitcnt vmcnt(16)
	v_pk_fma_f32 v[88:89], v[188:189], v[88:89], v[148:149]
	v_pk_fma_f32 v[86:87], v[186:187], v[86:87], v[146:147]
	global_store_dwordx4 v220, v[86:89], s[60:61] offset:16
	global_load_dwordx4 v[146:149], v220, s[60:61] offset:512
	s_waitcnt vmcnt(16)
	v_pk_fma_f32 v[124:125], v[188:189], v[124:125], v[174:175]
	v_pk_fma_f32 v[122:123], v[186:187], v[122:123], v[172:173]
	global_store_dwordx4 v222, v[122:125], s[60:61] offset:16
	global_load_dwordx4 v[172:175], v222, s[60:61] offset:512
	s_waitcnt vmcnt(16)
	v_pk_fma_f32 v[120:121], v[188:189], v[120:121], v[202:203]
	v_pk_fma_f32 v[118:119], v[186:187], v[118:119], v[200:201]
	global_store_dwordx4 v228, v[118:121], s[60:61] offset:16
	global_load_dwordx4 v[200:203], v228, s[60:61] offset:512
	s_waitcnt vmcnt(16)
	v_pk_fma_f32 v[128:129], v[188:189], v[128:129], v[212:213]
	v_pk_fma_f32 v[126:127], v[186:187], v[126:127], v[210:211]
	global_store_dwordx4 v230, v[126:129], s[60:61] offset:16
	global_load_dwordx4 v[210:213], v230, s[60:61] offset:512
	s_waitcnt vmcnt(16)
	v_pk_fma_f32 v[116:117], v[188:189], v[116:117], v[216:217]
	v_pk_fma_f32 v[114:115], v[186:187], v[114:115], v[214:215]
	global_store_dwordx4 v171, v[114:117], s[60:61] offset:16
	global_load_dwordx4 v[214:217], v171, s[60:61] offset:512
	s_waitcnt vmcnt(16)
	v_pk_fma_f32 v[112:113], v[188:189], v[112:113], v[226:227]
	v_pk_fma_f32 v[110:111], v[186:187], v[110:111], v[224:225]
	global_store_dwordx4 v176, v[110:113], s[60:61] offset:16
	global_load_dwordx4 v[224:227], v176, s[60:61] offset:512
	s_waitcnt vmcnt(16)
	v_pk_mul_f32 v[232:233], v[130:131], v[134:135]
	v_pk_mul_f32 v[234:235], v[132:133], v[136:137]
	global_load_dwordx4 v[130:133], v[196:197], off offset:528
	global_load_dwordx4 v[134:137], v[198:199], off offset:528
	s_waitcnt vmcnt(16)
	v_pk_fma_f32 v[104:105], v[234:235], v[104:105], v[140:141]
	v_pk_fma_f32 v[102:103], v[232:233], v[102:103], v[138:139]
	global_store_dwordx4 v204, v[102:105], s[60:61] offset:512
	global_load_dwordx4 v[138:141], v204, s[60:61] offset:528
	s_waitcnt vmcnt(16)
	v_pk_fma_f32 v[96:97], v[234:235], v[96:97], v[144:145]
	v_pk_fma_f32 v[94:95], v[232:233], v[94:95], v[142:143]
	global_store_dwordx4 v208, v[94:97], s[60:61] offset:512
	global_load_dwordx4 v[142:145], v208, s[60:61] offset:528
	s_waitcnt vmcnt(16)
;     __device__ __forceinline__ void rowstat(const f32x4 (&v)[2][2][4][2], const Unit& u, int wr, int wc, int fr, int fq, float* slot, unsigned* cnt) const {
;     ...
;                 float ss = 0.f;
; #pragma unroll
;                 for (int bj = 0; bj < 2; ++bj)
; #pragma unroll
;                     for (int n = 0; n < 2; ++n) { const f32x4 x = v[ai][bj][m][n]; ss += (x[0] * x[0] + x[1] * x[1]) + (x[2] * x[2] + x[3] * x[3]); }
;                 ss += __shfl_xor(ss, 16); ss += __shfl_xor(ss, 32);
;     __device__ __forceinline__ void operator()(f32x4 (&acc)[2][2][4][2], const Unit& u, int wr, int wc, int fr, int fq) const {
;     ...
;             for (int n = 0; n < 2; ++n) {
;                 const int col = u.pn * BM + bj * HALF + wc * 32 + 8 * fq + 4 * n;
;                 const f32x4 gg = *(const f32x4*)(md + gate_off + col) * *(const f32x4*)(gpost + col);
; #pragma unroll
;                 for (int ai = 0; ai < 2; ++ai)
; #pragma unroll
;                     for (int m = 0; m < 4; ++m) {
;                         const int rl = ai * HALF + wr * 64 + m * 16 + fr; const size_t off = (size_t)(u.pm * BM + rl) * DM + col;
;                         const f32x4 xv = *(const f32x4*)(xin + off);
;                         const f32x4 xn = xv + gg * (acc[ai][bj][m][n] * S[rl]);
;                         acc[ai][bj][m][n] = xn; *(f32x4*)(xout + off) = xn;
;                     }
;             }
;         if (XN == nullptr) return;
;         asm volatile("s_waitcnt lgkmcnt(0)" ::: "memory"); __builtin_amdgcn_s_barrier(); asm volatile("" ::: "memory");
;         rowstat(acc, u, wr, wc, fr, fq, slot2, cnt2);
	v_pk_fma_f32 v[92:93], v[234:235], v[92:93], v[148:149]
	v_pk_fma_f32 v[90:91], v[232:233], v[90:91], v[146:147]
	global_store_dwordx4 v220, v[90:93], s[60:61] offset:512
	global_load_dwordx4 v[146:149], v220, s[60:61] offset:528
	s_waitcnt vmcnt(16)
	v_pk_fma_f32 v[84:85], v[234:235], v[84:85], v[174:175]
	v_pk_fma_f32 v[82:83], v[232:233], v[82:83], v[172:173]
	global_store_dwordx4 v222, v[82:85], s[60:61] offset:512
	global_load_dwordx4 v[172:175], v222, s[60:61] offset:528
	s_waitcnt vmcnt(16)
	v_pk_fma_f32 v[68:69], v[234:235], v[68:69], v[202:203]
	v_pk_fma_f32 v[66:67], v[232:233], v[66:67], v[200:201]
	global_store_dwordx4 v228, v[66:69], s[60:61] offset:512
	global_load_dwordx4 v[200:203], v228, s[60:61] offset:528
	s_waitcnt vmcnt(16)
	v_pk_fma_f32 v[44:45], v[234:235], v[44:45], v[212:213]
	v_pk_fma_f32 v[42:43], v[232:233], v[42:43], v[210:211]
	global_store_dwordx4 v230, v[42:45], s[60:61] offset:512
	global_load_dwordx4 v[210:213], v230, s[60:61] offset:528
	s_waitcnt vmcnt(16)
	v_pk_fma_f32 v[40:41], v[234:235], v[40:41], v[216:217]
	v_pk_fma_f32 v[38:39], v[232:233], v[38:39], v[214:215]
	global_store_dwordx4 v171, v[38:41], s[60:61] offset:512
	global_load_dwordx4 v[214:217], v171, s[60:61] offset:528
	s_waitcnt vmcnt(16)
	v_pk_fma_f32 v[20:21], v[234:235], v[20:21], v[226:227]
	v_pk_fma_f32 v[18:19], v[232:233], v[18:19], v[224:225]
	global_store_dwordx4 v176, v[18:21], s[60:61] offset:512
	global_load_dwordx4 v[224:227], v176, s[60:61] offset:528
	s_waitcnt vmcnt(16)
	v_pk_mul_f32 v[186:187], v[130:131], v[134:135]
	v_pk_mul_f32 v[188:189], v[132:133], v[136:137]
	s_waitcnt vmcnt(14)
	v_pk_fma_f32 v[36:37], v[188:189], v[36:37], v[140:141]
	v_pk_fma_f32 v[34:35], v[186:187], v[34:35], v[138:139]
	global_store_dwordx4 v204, v[34:37], s[60:61] offset:528
	s_waitcnt vmcnt(13)
	v_pk_fma_f32 v[132:133], v[188:189], v[32:33], v[144:145]
	v_pk_fma_f32 v[130:131], v[186:187], v[30:31], v[142:143]
	global_store_dwordx4 v208, v[130:133], s[60:61] offset:528
	s_waitcnt vmcnt(12)
	v_pk_fma_f32 v[136:137], v[188:189], v[28:29], v[148:149]
	v_pk_fma_f32 v[134:135], v[186:187], v[26:27], v[146:147]
	global_store_dwordx4 v220, v[134:137], s[60:61] offset:528
	s_waitcnt vmcnt(11)
	v_pk_fma_f32 v[24:25], v[188:189], v[24:25], v[174:175]
	v_pk_fma_f32 v[22:23], v[186:187], v[22:23], v[172:173]
	global_store_dwordx4 v222, v[22:25], s[60:61] offset:528
	s_waitcnt vmcnt(10)
	v_pk_fma_f32 v[16:17], v[188:189], v[16:17], v[202:203]
	v_pk_fma_f32 v[14:15], v[186:187], v[14:15], v[200:201]
	global_store_dwordx4 v228, v[14:17], s[60:61] offset:528
	s_waitcnt vmcnt(9)
	v_pk_fma_f32 v[10:11], v[188:189], v[10:11], v[212:213]
	v_pk_fma_f32 v[8:9], v[186:187], v[8:9], v[210:211]
	global_store_dwordx4 v230, v[8:11], s[60:61] offset:528
	s_waitcnt vmcnt(8)
	v_pk_fma_f32 v[6:7], v[188:189], v[6:7], v[216:217]
	v_pk_fma_f32 v[4:5], v[186:187], v[4:5], v[214:215]
	global_store_dwordx4 v171, v[4:7], s[60:61] offset:528
	s_waitcnt vmcnt(7)
	v_pk_fma_f32 v[2:3], v[188:189], v[2:3], v[226:227]
	v_pk_fma_f32 v[0:1], v[186:187], v[0:1], v[224:225]
	global_store_dwordx4 v176, v[0:3], s[60:61] offset:528
	v_add_u32_e32 v192, s8, v205
	v_ashrrev_i32_e32 v193, 31, v192
	v_add_u32_e32 v190, s8, v241
	v_ashrrev_i32_e32 v191, 31, v190
	v_add_u32_e32 v178, s8, v229
	v_ashrrev_i32_e32 v179, 31, v178
	v_add_u32_e32 v186, s8, v231
	v_ashrrev_i32_e32 v187, 31, v186
	v_add_u32_e32 v164, s8, v240
	v_ashrrev_i32_e32 v165, 31, v164
	v_add_u32_e32 v188, s8, v242
	v_ashrrev_i32_e32 v189, 31, v188
	v_add_u32_e32 v182, s8, v243
	v_ashrrev_i32_e32 v183, 31, v182
	v_add_u32_e32 v180, s8, v244
	v_ashrrev_i32_e32 v181, 31, v180
	s_andn2_b64 vcc, exec, s[90:91]
	v_or_b32_e32 v196, 0x80, v184
	v_ashrrev_i32_e32 v197, 31, v196
	s_cbranch_vccnz .LBB0_1251
	v_mul_f32_e32 v26, v79, v79
	v_mul_f32_e32 v27, v81, v81
	v_fmac_f32_e32 v26, v78, v78
	v_fmac_f32_e32 v27, v80, v80
	v_add_f32_e32 v26, v26, v27
	v_mul_f32_e32 v27, v107, v107
	v_mul_f32_e32 v28, v109, v109
	v_fmac_f32_e32 v27, v106, v106
	v_fmac_f32_e32 v28, v108, v108
	v_add_f32_e32 v27, v27, v28
	v_add_f32_e32 v26, v26, v27
	v_mul_f32_e32 v27, v103, v103
	v_mul_f32_e32 v28, v105, v105
	v_fmac_f32_e32 v27, v102, v102
	v_fmac_f32_e32 v28, v104, v104
	v_add_f32_e32 v27, v27, v28
	v_add_f32_e32 v26, v26, v27
	v_mul_f32_e32 v27, v35, v35
	v_mul_f32_e32 v28, v37, v37
	v_fmac_f32_e32 v27, v34, v34
	v_fmac_f32_e32 v28, v36, v36
	v_add_f32_e32 v27, v27, v28
	v_add_f32_e32 v26, v26, v27
	s_waitcnt lgkmcnt(0)
	s_barrier
;     __device__ __forceinline__ void rowstat(const f32x4 (&v)[2][2][4][2], const Unit& u, int wr, int wc, int fr, int fq, float* slot, unsigned* cnt) const {
;     ...
; #pragma unroll
;         for (int ai = 0; ai < 2; ++ai)
; #pragma unroll
;             for (int m = 0; m < 4; ++m) {
;                 float ss = 0.f;
; #pragma unroll
;                 for (int bj = 0; bj < 2; ++bj)
; #pragma unroll
;                     for (int n = 0; n < 2; ++n) { const f32x4 x = v[ai][bj][m][n]; ss += (x[0] * x[0] + x[1] * x[1]) + (x[2] * x[2] + x[3] * x[3]); }
;                 ss += __shfl_xor(ss, 16); ss += __shfl_xor(ss, 32);
;                 if (fq == 0) Pp[(ai * HALF + wr * 64 + m * 16 + fr) * 4 + wc] = ss;
	v_mov_b32_e32 v29, v26
	v_mul_f32_e32 v26, v75, v75
	v_mul_f32_e32 v27, v77, v77
	v_fmac_f32_e32 v26, v74, v74
	v_fmac_f32_e32 v27, v76, v76
	v_add_f32_e32 v26, v26, v27
	v_mul_f32_e32 v27, v99, v99
	v_mul_f32_e32 v28, v101, v101
	v_fmac_f32_e32 v27, v98, v98
	v_fmac_f32_e32 v28, v100, v100
	v_add_f32_e32 v27, v27, v28
	v_add_f32_e32 v26, v26, v27
	v_mul_f32_e32 v27, v95, v95
	v_mul_f32_e32 v28, v97, v97
	v_fmac_f32_e32 v27, v94, v94
	v_fmac_f32_e32 v28, v96, v96
	v_add_f32_e32 v27, v27, v28
	v_add_f32_e32 v26, v26, v27
	v_mul_f32_e32 v27, v131, v131
	v_mul_f32_e32 v28, v133, v133
	v_fmac_f32_e32 v27, v130, v130
	v_fmac_f32_e32 v28, v132, v132
	v_add_f32_e32 v27, v27, v28
	v_add_f32_e32 v26, v26, v27
	v_mov_b32_e32 v30, v26
	v_mul_f32_e32 v26, v71, v71
	v_mul_f32_e32 v27, v73, v73
	v_fmac_f32_e32 v26, v70, v70
	v_fmac_f32_e32 v27, v72, v72
	v_add_f32_e32 v26, v26, v27
	v_mul_f32_e32 v27, v87, v87
	v_mul_f32_e32 v28, v89, v89
	v_fmac_f32_e32 v27, v86, v86
	v_fmac_f32_e32 v28, v88, v88
	v_add_f32_e32 v27, v27, v28
	v_add_f32_e32 v26, v26, v27
	v_mul_f32_e32 v27, v91, v91
	v_mul_f32_e32 v28, v93, v93
	v_fmac_f32_e32 v27, v90, v90
	v_fmac_f32_e32 v28, v92, v92
	v_add_f32_e32 v27, v27, v28
	v_add_f32_e32 v26, v26, v27
	v_mul_f32_e32 v27, v135, v135
	v_mul_f32_e32 v28, v137, v137
	v_fmac_f32_e32 v27, v134, v134
	v_fmac_f32_e32 v28, v136, v136
	v_add_f32_e32 v27, v27, v28
	v_add_f32_e32 v26, v26, v27
	v_mov_b32_e32 v31, v26
	v_mul_f32_e32 v26, v63, v63
	v_mul_f32_e32 v27, v65, v65
	v_fmac_f32_e32 v26, v62, v62
	v_fmac_f32_e32 v27, v64, v64
	v_add_f32_e32 v26, v26, v27
	v_mul_f32_e32 v27, v123, v123
	v_mul_f32_e32 v28, v125, v125
	v_fmac_f32_e32 v27, v122, v122
	v_fmac_f32_e32 v28, v124, v124
	v_add_f32_e32 v27, v27, v28
	v_add_f32_e32 v26, v26, v27
	v_mul_f32_e32 v27, v83, v83
	v_mul_f32_e32 v28, v85, v85
	v_fmac_f32_e32 v27, v82, v82
	v_fmac_f32_e32 v28, v84, v84
	v_add_f32_e32 v27, v27, v28
	v_add_f32_e32 v26, v26, v27
	v_mul_f32_e32 v27, v23, v23
	v_mul_f32_e32 v28, v25, v25
	v_fmac_f32_e32 v27, v22, v22
	v_fmac_f32_e32 v28, v24, v24
	v_add_f32_e32 v27, v27, v28
	v_add_f32_e32 v26, v26, v27
	v_mov_b32_e32 v32, v26
	v_mul_f32_e32 v26, v59, v59
	v_mul_f32_e32 v27, v61, v61
	v_fmac_f32_e32 v26, v58, v58
	v_fmac_f32_e32 v27, v60, v60
	v_add_f32_e32 v26, v26, v27
	v_mul_f32_e32 v27, v119, v119
	v_mul_f32_e32 v28, v121, v121
	v_fmac_f32_e32 v27, v118, v118
	v_fmac_f32_e32 v28, v120, v120
	v_add_f32_e32 v27, v27, v28
	v_add_f32_e32 v26, v26, v27
	v_mul_f32_e32 v27, v67, v67
	v_mul_f32_e32 v28, v69, v69
	v_fmac_f32_e32 v27, v66, v66
	v_fmac_f32_e32 v28, v68, v68
	v_add_f32_e32 v27, v27, v28
	v_add_f32_e32 v26, v26, v27
	v_mul_f32_e32 v27, v15, v15
	v_mul_f32_e32 v28, v17, v17
	v_fmac_f32_e32 v27, v14, v14
	v_fmac_f32_e32 v28, v16, v16
	v_add_f32_e32 v27, v27, v28
	v_add_f32_e32 v26, v26, v27
	v_mov_b32_e32 v33, v26
	v_mul_f32_e32 v26, v55, v55
	v_mul_f32_e32 v27, v57, v57
	v_fmac_f32_e32 v26, v54, v54
	v_fmac_f32_e32 v27, v56, v56
	v_add_f32_e32 v26, v26, v27
	v_mul_f32_e32 v27, v127, v127
	v_mul_f32_e32 v28, v129, v129
	v_fmac_f32_e32 v27, v126, v126
	v_fmac_f32_e32 v28, v128, v128
	v_add_f32_e32 v27, v27, v28
	v_add_f32_e32 v26, v26, v27
	v_mul_f32_e32 v27, v43, v43
	v_mul_f32_e32 v28, v45, v45
	v_fmac_f32_e32 v27, v42, v42
	v_fmac_f32_e32 v28, v44, v44
	v_add_f32_e32 v27, v27, v28
	v_add_f32_e32 v26, v26, v27
	v_mul_f32_e32 v27, v9, v9
	v_mul_f32_e32 v28, v11, v11
	v_fmac_f32_e32 v27, v8, v8
	v_fmac_f32_e32 v28, v10, v10
	v_add_f32_e32 v27, v27, v28
	v_add_f32_e32 v26, v26, v27
	v_mov_b32_e32 v138, v26
	v_mul_f32_e32 v26, v51, v51
	v_mul_f32_e32 v27, v53, v53
	v_fmac_f32_e32 v26, v50, v50
	v_fmac_f32_e32 v27, v52, v52
	v_add_f32_e32 v26, v26, v27
	v_mul_f32_e32 v27, v115, v115
	v_mul_f32_e32 v28, v117, v117
	v_fmac_f32_e32 v27, v114, v114
	v_fmac_f32_e32 v28, v116, v116
	v_add_f32_e32 v27, v27, v28
	v_add_f32_e32 v26, v26, v27
	v_mul_f32_e32 v27, v39, v39
	v_mul_f32_e32 v28, v41, v41
	v_fmac_f32_e32 v27, v38, v38
	v_fmac_f32_e32 v28, v40, v40
	v_add_f32_e32 v27, v27, v28
	v_add_f32_e32 v26, v26, v27
	v_mul_f32_e32 v27, v5, v5
	v_mul_f32_e32 v28, v7, v7
	v_fmac_f32_e32 v27, v4, v4
	v_fmac_f32_e32 v28, v6, v6
	v_add_f32_e32 v27, v27, v28
	v_add_f32_e32 v26, v26, v27
	v_mov_b32_e32 v139, v26
	v_mul_f32_e32 v26, v47, v47
	v_mul_f32_e32 v27, v49, v49
	v_fmac_f32_e32 v26, v46, v46
	v_fmac_f32_e32 v27, v48, v48
	v_add_f32_e32 v26, v26, v27
	v_mul_f32_e32 v27, v111, v111
	v_mul_f32_e32 v28, v113, v113
	v_fmac_f32_e32 v27, v110, v110
	v_fmac_f32_e32 v28, v112, v112
	v_add_f32_e32 v27, v27, v28
	v_add_f32_e32 v26, v26, v27
	v_mul_f32_e32 v27, v19, v19
	v_mul_f32_e32 v28, v21, v21
	v_fmac_f32_e32 v27, v18, v18
	v_fmac_f32_e32 v28, v20, v20
	v_add_f32_e32 v27, v27, v28
	v_add_f32_e32 v26, v26, v27
	v_mul_f32_e32 v27, v1, v1
	v_mul_f32_e32 v28, v3, v3
	v_fmac_f32_e32 v27, v0, v0
	v_fmac_f32_e32 v28, v2, v2
	v_add_f32_e32 v27, v27, v28
	v_add_f32_e32 v26, v26, v27
	v_mov_b32_e32 v140, v26
	ds_bpermute_b32 v141, v169, v29
	ds_bpermute_b32 v142, v169, v30
	ds_bpermute_b32 v143, v169, v31
	ds_bpermute_b32 v144, v169, v32
	ds_bpermute_b32 v145, v169, v33
	ds_bpermute_b32 v146, v169, v138
	ds_bpermute_b32 v147, v169, v139
	ds_bpermute_b32 v148, v169, v140
	s_waitcnt lgkmcnt(0)
	v_add_f32_e32 v29, v29, v141
	v_add_f32_e32 v30, v30, v142
	v_add_f32_e32 v31, v31, v143
	v_add_f32_e32 v32, v32, v144
	v_add_f32_e32 v33, v33, v145
	v_add_f32_e32 v138, v138, v146
	v_add_f32_e32 v139, v139, v147
	v_add_f32_e32 v140, v140, v148
	ds_bpermute_b32 v141, v170, v29
	ds_bpermute_b32 v142, v170, v30
	ds_bpermute_b32 v143, v170, v31
	ds_bpermute_b32 v144, v170, v32
	ds_bpermute_b32 v145, v170, v33
	ds_bpermute_b32 v146, v170, v138
	ds_bpermute_b32 v147, v170, v139
	ds_bpermute_b32 v148, v170, v140
	s_and_saveexec_b64 s[8:9], s[0:1]
	s_cbranch_execz .Lrs_skip_3
	s_waitcnt lgkmcnt(0)
	v_add_f32_e32 v29, v29, v141
	v_add_f32_e32 v30, v30, v142
	v_add_f32_e32 v31, v31, v143
	v_add_f32_e32 v32, v32, v144
	v_add_f32_e32 v33, v33, v145
	v_add_f32_e32 v138, v138, v146
	v_add_f32_e32 v139, v139, v147
	v_add_f32_e32 v140, v140, v148
	ds_write_b32 v168, v29
	ds_write_b32 v168, v30 offset:256
	ds_write_b32 v168, v31 offset:512
	ds_write_b32 v168, v32 offset:768
	ds_write_b32 v168, v33 offset:2048
	ds_write_b32 v168, v138 offset:2304
	ds_write_b32 v168, v139 offset:2560
	ds_write_b32 v168, v140 offset:2816

; __global__ void __launch_bounds__(NTHR, 2) fwd_megakernel(Params P) {
	.amdhsa_kernel _Z14fwd_megakernel6Params
		.amdhsa_group_segment_fixed_size 0
		.amdhsa_private_segment_fixed_size 0
		.amdhsa_kernarg_size 432
		.amdhsa_user_sgpr_count 2
		.amdhsa_user_sgpr_dispatch_ptr 0
		.amdhsa_user_sgpr_queue_ptr 0
		.amdhsa_user_sgpr_kernarg_segment_ptr 1
		.amdhsa_user_sgpr_dispatch_id 0
		.amdhsa_user_sgpr_kernarg_preload_length 0
		.amdhsa_user_sgpr_kernarg_preload_offset 0
		.amdhsa_user_sgpr_private_segment_size 0
		.amdhsa_uses_dynamic_stack 0
		.amdhsa_enable_private_segment 0
		.amdhsa_system_sgpr_workgroup_id_x 1
		.amdhsa_system_sgpr_workgroup_id_y 0
		.amdhsa_system_sgpr_workgroup_id_z 0
		.amdhsa_system_sgpr_workgroup_info 0
		.amdhsa_system_vgpr_workitem_id 2
		.amdhsa_next_free_vgpr 256
		.amdhsa_next_free_sgpr 102
		.amdhsa_accum_offset 256
		.amdhsa_reserve_vcc 1
		.amdhsa_float_round_mode_32 0
		.amdhsa_float_round_mode_16_64 0
		.amdhsa_float_denorm_mode_32 3
		.amdhsa_float_denorm_mode_16_64 3
		.amdhsa_dx10_clamp 1
		.amdhsa_ieee_mode 1
		.amdhsa_fp16_overflow 0
		.amdhsa_tg_split 0
		.amdhsa_exception_fp_ieee_invalid_op 0
		.amdhsa_exception_fp_denorm_src 0
		.amdhsa_exception_fp_ieee_div_zero 0
		.amdhsa_exception_fp_ieee_overflow 0
		.amdhsa_exception_fp_ieee_underflow 0
		.amdhsa_exception_fp_ieee_inexact 0
		.amdhsa_exception_int_div_zero 0
	.end_amdhsa_kernel

; __global__ void __launch_bounds__(NTHR, 2) fwd_megakernel(Params P) {
amdhsa.kernels:
  - .agpr_count:     0
    .args:
      - .offset:         0
        .size:           176
        .value_kind:     by_value
      - .offset:         176
        .size:           4
        .value_kind:     hidden_block_count_x
      - .offset:         180
        .size:           4
        .value_kind:     hidden_block_count_y
      - .offset:         184
        .size:           4
        .value_kind:     hidden_block_count_z
      - .offset:         188
        .size:           2
        .value_kind:     hidden_group_size_x
      - .offset:         190
        .size:           2
        .value_kind:     hidden_group_size_y
      - .offset:         192
        .size:           2
        .value_kind:     hidden_group_size_z
      - .offset:         194
        .size:           2
        .value_kind:     hidden_remainder_x
      - .offset:         196
        .size:           2
        .value_kind:     hidden_remainder_y
      - .offset:         198
        .size:           2
        .value_kind:     hidden_remainder_z
      - .offset:         216
        .size:           8
        .value_kind:     hidden_global_offset_x
      - .offset:         224
        .size:           8
        .value_kind:     hidden_global_offset_y
      - .offset:         232
        .size:           8
        .value_kind:     hidden_global_offset_z
      - .offset:         240
        .size:           2
        .value_kind:     hidden_grid_dims
      - .offset:         264
        .size:           8
        .value_kind:     hidden_multigrid_sync_arg
      - .offset:         296
        .size:           4
        .value_kind:     hidden_dynamic_lds_size
    .group_segment_fixed_size: 0
    .kernarg_segment_align: 8
    .kernarg_segment_size: 432
    .language:       OpenCL C
    .language_version:
      - 2
      - 0
    .max_flat_workgroup_size: 512
    .name:           _Z14fwd_megakernel6Params
    .private_segment_fixed_size: 0
    .sgpr_count:     108
    .sgpr_spill_count: 223
    .symbol:         _Z14fwd_megakernel6Params.kd
    .uniform_work_group_size: 1
    .uses_dynamic_stack: false
    .vgpr_count:     256
    .vgpr_spill_count: 0
    .wavefront_size: 64
